# GEMM counted waits coarsened to three per MFMA block (before MFMA 1, 3, 7)
# speedup vs baseline: 1.0033x; 1.0033x over previous
.LBB0_304:
	s_add_u32 s2, s68, 0xfff80080
	s_addc_u32 s17, s69, -1
	s_add_i32 s26, 0, 0x10000
	v_add_u32_e32 v156, s26, v141
	ds_read_b128 v[144:147], v156
	ds_read_b128 v[148:151], v156 offset:1024
	ds_read_b128 v[152:155], v156 offset:2048
	ds_read_b128 v[156:159], v156 offset:3072
	s_cmp_eq_u32 s44, 28
	s_cselect_b32 s73, s55, s17
	s_cselect_b32 s72, s83, s2
	s_cselect_b32 s71, s24, s92
	s_cselect_b32 s70, s25, s43
	v_lshl_add_u64 v[164:165], s[68:69], 0, v[136:137]
	s_add_i32 m0, s58, 0xc000
	ds_read_b128 v[160:163], v143
	ds_read_b128 v[188:191], v143 offset:1024
	ds_read_b128 v[192:195], v143 offset:2048
	ds_read_b128 v[196:199], v143 offset:3072
	ds_read_b128 v[200:203], v143 offset:4096
	ds_read_b128 v[216:219], v143 offset:5120
	ds_read_b128 v[220:223], v143 offset:6144
	ds_read_b128 v[224:227], v143 offset:7168
	global_load_lds_dwordx4 v[164:165], off
	v_lshl_add_u64 v[164:165], s[68:69], 0, v[138:139]
	s_add_i32 m0, s58, 0xe000
	s_nop 0
	global_load_lds_dwordx4 v[164:165], off
	s_waitcnt lgkmcnt(8)
	s_barrier
	s_waitcnt lgkmcnt(7)
	v_mfma_f32_16x16x32_bf16 v[126:129], v[144:147], v[160:163], v[126:129]
	v_mfma_f32_16x16x32_bf16 v[122:125], v[152:155], v[160:163], v[122:125]
	s_waitcnt lgkmcnt(3)
	v_mfma_f32_16x16x32_bf16 v[118:121], v[144:147], v[192:195], v[118:121]
	v_mfma_f32_16x16x32_bf16 v[114:117], v[152:155], v[192:195], v[114:117]
	v_mfma_f32_16x16x32_bf16 v[102:105], v[144:147], v[200:203], v[102:105]
	v_mfma_f32_16x16x32_bf16 v[98:101], v[152:155], v[200:203], v[98:101]
	s_waitcnt lgkmcnt(0)
	v_mfma_f32_16x16x32_bf16 v[86:89], v[144:147], v[220:223], v[86:89]
	v_mfma_f32_16x16x32_bf16 v[82:85], v[152:155], v[220:223], v[82:85]
	v_mfma_f32_16x16x32_bf16 v[126:129], v[148:151], v[188:191], v[126:129]
	v_mfma_f32_16x16x32_bf16 v[122:125], v[156:159], v[188:191], v[122:125]
	v_mfma_f32_16x16x32_bf16 v[118:121], v[148:151], v[196:199], v[118:121]
	v_mfma_f32_16x16x32_bf16 v[114:117], v[156:159], v[196:199], v[114:117]
	v_mfma_f32_16x16x32_bf16 v[102:105], v[148:151], v[216:219], v[102:105]
	v_mfma_f32_16x16x32_bf16 v[98:101], v[156:159], v[216:219], v[98:101]
	v_mfma_f32_16x16x32_bf16 v[86:89], v[148:151], v[224:227], v[86:89]
	v_mfma_f32_16x16x32_bf16 v[82:85], v[156:159], v[224:227], v[82:85]
	s_barrier
	s_add_i32 s2, 0, 0x14000
	v_add_u32_e32 v164, s2, v141
	s_add_i32 s17, s26, s3
	ds_read_b128 v[228:231], v164
	ds_read_b128 v[232:235], v164 offset:1024
	ds_read_b128 v[236:239], v164 offset:2048
	ds_read_b128 v[240:243], v164 offset:3072
	v_lshl_add_u64 v[164:165], s[70:71], 0, v[0:1]
	s_mov_b32 m0, s17
	v_lshl_add_u64 v[204:205], s[70:71], 0, v[130:131]
	global_load_lds_dwordx4 v[164:165], off
	s_add_i32 m0, s17, 0x2000
	s_nop 0
	global_load_lds_dwordx4 v[204:205], off
	s_barrier
	s_waitcnt lgkmcnt(1)
	v_mfma_f32_16x16x32_bf16 v[110:113], v[228:231], v[160:163], v[110:113]
	v_mfma_f32_16x16x32_bf16 v[106:109], v[236:239], v[160:163], v[106:109]
	v_mfma_f32_16x16x32_bf16 v[94:97], v[228:231], v[192:195], v[94:97]
	v_mfma_f32_16x16x32_bf16 v[90:93], v[236:239], v[192:195], v[90:93]
	v_mfma_f32_16x16x32_bf16 v[78:81], v[228:231], v[200:203], v[78:81]
	v_mfma_f32_16x16x32_bf16 v[74:77], v[236:239], v[200:203], v[74:77]
	s_waitcnt lgkmcnt(0)
	v_mfma_f32_16x16x32_bf16 v[70:73], v[228:231], v[220:223], v[70:73]
	v_mfma_f32_16x16x32_bf16 v[66:69], v[236:239], v[220:223], v[66:69]
	v_mfma_f32_16x16x32_bf16 v[110:113], v[232:235], v[188:191], v[110:113]
	v_mfma_f32_16x16x32_bf16 v[106:109], v[240:243], v[188:191], v[106:109]
	v_mfma_f32_16x16x32_bf16 v[94:97], v[232:235], v[196:199], v[94:97]
	v_mfma_f32_16x16x32_bf16 v[90:93], v[240:243], v[196:199], v[90:93]
	v_mfma_f32_16x16x32_bf16 v[78:81], v[232:235], v[216:219], v[78:81]
	v_mfma_f32_16x16x32_bf16 v[74:77], v[240:243], v[216:219], v[74:77]
	v_mfma_f32_16x16x32_bf16 v[70:73], v[232:235], v[224:227], v[70:73]
	v_mfma_f32_16x16x32_bf16 v[66:69], v[240:243], v[224:227], v[66:69]
	s_mov_b32 m0, s58
	v_lshl_add_u64 v[244:245], s[72:73], 0, v[134:135]
	s_barrier
	ds_read_b128 v[160:163], v143 offset:16384
	ds_read_b128 v[188:191], v143 offset:17408
	ds_read_b128 v[192:195], v143 offset:18432
	ds_read_b128 v[196:199], v143 offset:19456
	ds_read_b128 v[200:203], v143 offset:20480
	ds_read_b128 v[216:219], v143 offset:21504
	ds_read_b128 v[220:223], v143 offset:22528
	ds_read_b128 v[224:227], v143 offset:23552
	global_load_lds_dwordx4 v[244:245], off
	v_lshl_add_u64 v[246:247], s[72:73], 0, v[132:133]
	s_mov_b32 m0, s74
	s_nop 0
	global_load_lds_dwordx4 v[246:247], off
	s_barrier
	s_waitcnt lgkmcnt(7)
	v_mfma_f32_16x16x32_bf16 v[62:65], v[144:147], v[160:163], v[62:65]
	v_mfma_f32_16x16x32_bf16 v[58:61], v[152:155], v[160:163], v[58:61]
	s_waitcnt lgkmcnt(3)
	v_mfma_f32_16x16x32_bf16 v[54:57], v[144:147], v[192:195], v[54:57]
	v_mfma_f32_16x16x32_bf16 v[50:53], v[152:155], v[192:195], v[50:53]
	v_mfma_f32_16x16x32_bf16 v[38:41], v[144:147], v[200:203], v[38:41]
	v_mfma_f32_16x16x32_bf16 v[34:37], v[152:155], v[200:203], v[34:37]
	s_waitcnt lgkmcnt(0)
	v_mfma_f32_16x16x32_bf16 v[22:25], v[144:147], v[220:223], v[22:25]
	v_mfma_f32_16x16x32_bf16 v[18:21], v[152:155], v[220:223], v[18:21]
	v_mfma_f32_16x16x32_bf16 v[62:65], v[148:151], v[188:191], v[62:65]
	v_mfma_f32_16x16x32_bf16 v[58:61], v[156:159], v[188:191], v[58:61]
	v_mfma_f32_16x16x32_bf16 v[54:57], v[148:151], v[196:199], v[54:57]
	v_mfma_f32_16x16x32_bf16 v[50:53], v[156:159], v[196:199], v[50:53]
	v_mfma_f32_16x16x32_bf16 v[38:41], v[148:151], v[216:219], v[38:41]
	v_mfma_f32_16x16x32_bf16 v[34:37], v[156:159], v[216:219], v[34:37]
	v_mfma_f32_16x16x32_bf16 v[22:25], v[148:151], v[224:227], v[22:25]
	v_mfma_f32_16x16x32_bf16 v[18:21], v[156:159], v[224:227], v[18:21]
	s_barrier
	s_add_u32 s26, s70, 0x80000
	s_addc_u32 s27, s71, 0
	s_add_i32 s2, s2, s3
	v_lshl_add_u64 v[144:145], s[26:27], 0, v[0:1]
	s_mov_b32 m0, s2
	s_nop 0
	global_load_lds_dwordx4 v[144:145], off
	v_lshl_add_u64 v[144:145], s[26:27], 0, v[130:131]
	s_add_i32 m0, s2, 0x2000
	s_nop 0
	global_load_lds_dwordx4 v[144:145], off
	s_waitcnt vmcnt(6)
	s_barrier
	v_mfma_f32_16x16x32_bf16 v[46:49], v[228:231], v[160:163], v[46:49]
	v_mfma_f32_16x16x32_bf16 v[42:45], v[236:239], v[160:163], v[42:45]
	v_mfma_f32_16x16x32_bf16 v[30:33], v[228:231], v[192:195], v[30:33]
	v_mfma_f32_16x16x32_bf16 v[26:29], v[236:239], v[192:195], v[26:29]
	v_mfma_f32_16x16x32_bf16 v[14:17], v[228:231], v[200:203], v[14:17]
	v_mfma_f32_16x16x32_bf16 v[10:13], v[236:239], v[200:203], v[10:13]
	v_mfma_f32_16x16x32_bf16 v[6:9], v[228:231], v[220:223], v[6:9]
	v_mfma_f32_16x16x32_bf16 v[2:5], v[236:239], v[220:223], v[2:5]
	v_mfma_f32_16x16x32_bf16 v[46:49], v[232:235], v[188:191], v[46:49]
	v_mfma_f32_16x16x32_bf16 v[42:45], v[240:243], v[188:191], v[42:45]
	v_mfma_f32_16x16x32_bf16 v[30:33], v[232:235], v[196:199], v[30:33]
	v_mfma_f32_16x16x32_bf16 v[26:29], v[240:243], v[196:199], v[26:29]
	v_mfma_f32_16x16x32_bf16 v[14:17], v[232:235], v[216:219], v[14:17]
	v_mfma_f32_16x16x32_bf16 v[10:13], v[240:243], v[216:219], v[10:13]
	v_mfma_f32_16x16x32_bf16 v[6:9], v[232:235], v[224:227], v[6:9]
	v_mfma_f32_16x16x32_bf16 v[2:5], v[240:243], v[224:227], v[2:5]
	s_add_i32 s2, 0, 0x18000
	v_add_u32_e32 v156, s2, v141
	s_barrier
	ds_read_b128 v[144:147], v156
	ds_read_b128 v[148:151], v156 offset:1024
	ds_read_b128 v[152:155], v156 offset:2048
	ds_read_b128 v[156:159], v156 offset:3072
	s_add_u32 s26, s72, 0x80000
	s_addc_u32 s27, s73, 0
	s_mov_b32 m0, s75
	v_lshl_add_u64 v[228:229], s[26:27], 0, v[134:135]
	ds_read_b128 v[160:163], v143 offset:32768
	ds_read_b128 v[188:191], v143 offset:33792
	ds_read_b128 v[192:195], v143 offset:34816
	ds_read_b128 v[196:199], v143 offset:35840
	ds_read_b128 v[200:203], v143 offset:36864
	ds_read_b128 v[216:219], v143 offset:37888
	ds_read_b128 v[220:223], v143 offset:38912
	ds_read_b128 v[224:227], v143 offset:39936
	global_load_lds_dwordx4 v[228:229], off
	v_lshl_add_u64 v[228:229], s[26:27], 0, v[132:133]
	s_mov_b32 m0, s79
	s_nop 0
	global_load_lds_dwordx4 v[228:229], off
	s_waitcnt lgkmcnt(8)
	s_barrier
	s_waitcnt lgkmcnt(7)
	v_mfma_f32_16x16x32_bf16 v[126:129], v[144:147], v[160:163], v[126:129]
	v_mfma_f32_16x16x32_bf16 v[122:125], v[152:155], v[160:163], v[122:125]
	s_waitcnt lgkmcnt(3)
	v_mfma_f32_16x16x32_bf16 v[118:121], v[144:147], v[192:195], v[118:121]
	v_mfma_f32_16x16x32_bf16 v[114:117], v[152:155], v[192:195], v[114:117]
	v_mfma_f32_16x16x32_bf16 v[102:105], v[144:147], v[200:203], v[102:105]
	v_mfma_f32_16x16x32_bf16 v[98:101], v[152:155], v[200:203], v[98:101]
	s_waitcnt lgkmcnt(0)
	v_mfma_f32_16x16x32_bf16 v[86:89], v[144:147], v[220:223], v[86:89]
	v_mfma_f32_16x16x32_bf16 v[82:85], v[152:155], v[220:223], v[82:85]
	v_mfma_f32_16x16x32_bf16 v[126:129], v[148:151], v[188:191], v[126:129]
	v_mfma_f32_16x16x32_bf16 v[122:125], v[156:159], v[188:191], v[122:125]
	v_mfma_f32_16x16x32_bf16 v[118:121], v[148:151], v[196:199], v[118:121]
	v_mfma_f32_16x16x32_bf16 v[114:117], v[156:159], v[196:199], v[114:117]
	v_mfma_f32_16x16x32_bf16 v[102:105], v[148:151], v[216:219], v[102:105]
	v_mfma_f32_16x16x32_bf16 v[98:101], v[156:159], v[216:219], v[98:101]
	v_mfma_f32_16x16x32_bf16 v[86:89], v[148:151], v[224:227], v[86:89]
	v_mfma_f32_16x16x32_bf16 v[82:85], v[156:159], v[224:227], v[82:85]
	s_barrier
	s_add_i32 s17, 0, 0x1c000
	s_add_i32 s2, s2, s3
	v_add_u32_e32 v206, s17, v141
	v_lshl_add_u64 v[164:165], v[164:165], 0, s[28:29]
	s_mov_b32 m0, s2
	ds_read_b128 v[228:231], v206
	ds_read_b128 v[232:235], v206 offset:1024
	ds_read_b128 v[236:239], v206 offset:2048
	ds_read_b128 v[240:243], v206 offset:3072
	global_load_lds_dwordx4 v[164:165], off
	v_lshl_add_u64 v[164:165], v[204:205], 0, s[28:29]
	s_add_i32 m0, s2, 0x2000
	s_nop 0
	global_load_lds_dwordx4 v[164:165], off
	s_barrier
	s_waitcnt lgkmcnt(1)
	v_mfma_f32_16x16x32_bf16 v[110:113], v[228:231], v[160:163], v[110:113]
	v_mfma_f32_16x16x32_bf16 v[106:109], v[236:239], v[160:163], v[106:109]
	v_mfma_f32_16x16x32_bf16 v[94:97], v[228:231], v[192:195], v[94:97]
	v_mfma_f32_16x16x32_bf16 v[90:93], v[236:239], v[192:195], v[90:93]
	v_mfma_f32_16x16x32_bf16 v[78:81], v[228:231], v[200:203], v[78:81]
	v_mfma_f32_16x16x32_bf16 v[74:77], v[236:239], v[200:203], v[74:77]
	s_waitcnt lgkmcnt(0)
	v_mfma_f32_16x16x32_bf16 v[70:73], v[228:231], v[220:223], v[70:73]
	v_mfma_f32_16x16x32_bf16 v[66:69], v[236:239], v[220:223], v[66:69]
	v_mfma_f32_16x16x32_bf16 v[110:113], v[232:235], v[188:191], v[110:113]
	v_mfma_f32_16x16x32_bf16 v[106:109], v[240:243], v[188:191], v[106:109]
	v_mfma_f32_16x16x32_bf16 v[94:97], v[232:235], v[196:199], v[94:97]
	v_mfma_f32_16x16x32_bf16 v[90:93], v[240:243], v[196:199], v[90:93]
	v_mfma_f32_16x16x32_bf16 v[78:81], v[232:235], v[216:219], v[78:81]
	v_mfma_f32_16x16x32_bf16 v[74:77], v[240:243], v[216:219], v[74:77]
	v_mfma_f32_16x16x32_bf16 v[70:73], v[232:235], v[224:227], v[70:73]
	v_mfma_f32_16x16x32_bf16 v[66:69], v[240:243], v[224:227], v[66:69]
	s_mov_b32 m0, s80
	v_lshl_add_u64 v[164:165], v[244:245], 0, s[28:29]
	s_barrier
	ds_read_b128 v[160:163], v143 offset:49152
	ds_read_b128 v[188:191], v143 offset:50176
	ds_read_b128 v[192:195], v143 offset:51200
	ds_read_b128 v[196:199], v143 offset:52224
	ds_read_b128 v[200:203], v143 offset:53248
	ds_read_b128 v[216:219], v143 offset:54272
	ds_read_b128 v[220:223], v143 offset:55296
	ds_read_b128 v[224:227], v143 offset:56320
	global_load_lds_dwordx4 v[164:165], off
	v_lshl_add_u64 v[164:165], v[246:247], 0, s[28:29]
	s_mov_b32 m0, s81
	s_nop 0
	global_load_lds_dwordx4 v[164:165], off
	s_barrier
	s_waitcnt lgkmcnt(7)
	v_mfma_f32_16x16x32_bf16 v[62:65], v[144:147], v[160:163], v[62:65]
	v_mfma_f32_16x16x32_bf16 v[58:61], v[152:155], v[160:163], v[58:61]
	s_waitcnt lgkmcnt(3)
	v_mfma_f32_16x16x32_bf16 v[54:57], v[144:147], v[192:195], v[54:57]
	v_mfma_f32_16x16x32_bf16 v[50:53], v[152:155], v[192:195], v[50:53]
	v_mfma_f32_16x16x32_bf16 v[38:41], v[144:147], v[200:203], v[38:41]
	v_mfma_f32_16x16x32_bf16 v[34:37], v[152:155], v[200:203], v[34:37]
	s_waitcnt lgkmcnt(0)
	v_mfma_f32_16x16x32_bf16 v[22:25], v[144:147], v[220:223], v[22:25]
	v_mfma_f32_16x16x32_bf16 v[18:21], v[152:155], v[220:223], v[18:21]
	v_mfma_f32_16x16x32_bf16 v[62:65], v[148:151], v[188:191], v[62:65]
	v_mfma_f32_16x16x32_bf16 v[58:61], v[156:159], v[188:191], v[58:61]
	v_mfma_f32_16x16x32_bf16 v[54:57], v[148:151], v[196:199], v[54:57]
	v_mfma_f32_16x16x32_bf16 v[50:53], v[156:159], v[196:199], v[50:53]
	v_mfma_f32_16x16x32_bf16 v[38:41], v[148:151], v[216:219], v[38:41]
	v_mfma_f32_16x16x32_bf16 v[34:37], v[156:159], v[216:219], v[34:37]
	v_mfma_f32_16x16x32_bf16 v[22:25], v[148:151], v[224:227], v[22:25]
	v_mfma_f32_16x16x32_bf16 v[18:21], v[156:159], v[224:227], v[18:21]
	s_barrier
	s_add_u32 s26, s70, 0x80080
	s_addc_u32 s27, s71, 0
	s_add_i32 s2, s17, s3
	v_lshl_add_u64 v[144:145], s[26:27], 0, v[0:1]
	s_mov_b32 m0, s2
	s_nop 0
	global_load_lds_dwordx4 v[144:145], off
	v_lshl_add_u64 v[144:145], s[26:27], 0, v[130:131]
	s_add_i32 m0, s2, 0x2000
	s_nop 0
	global_load_lds_dwordx4 v[144:145], off
	s_waitcnt vmcnt(6)
	s_barrier
	v_mfma_f32_16x16x32_bf16 v[46:49], v[228:231], v[160:163], v[46:49]
	v_mfma_f32_16x16x32_bf16 v[42:45], v[236:239], v[160:163], v[42:45]
	v_mfma_f32_16x16x32_bf16 v[30:33], v[228:231], v[192:195], v[30:33]
	v_mfma_f32_16x16x32_bf16 v[26:29], v[236:239], v[192:195], v[26:29]
	v_mfma_f32_16x16x32_bf16 v[14:17], v[228:231], v[200:203], v[14:17]
	v_mfma_f32_16x16x32_bf16 v[10:13], v[236:239], v[200:203], v[10:13]
	v_mfma_f32_16x16x32_bf16 v[6:9], v[228:231], v[220:223], v[6:9]
	v_mfma_f32_16x16x32_bf16 v[2:5], v[236:239], v[220:223], v[2:5]
	v_mfma_f32_16x16x32_bf16 v[46:49], v[232:235], v[188:191], v[46:49]
	v_mfma_f32_16x16x32_bf16 v[42:45], v[240:243], v[188:191], v[42:45]
	v_mfma_f32_16x16x32_bf16 v[30:33], v[232:235], v[196:199], v[30:33]
	v_mfma_f32_16x16x32_bf16 v[26:29], v[240:243], v[196:199], v[26:29]
	v_mfma_f32_16x16x32_bf16 v[14:17], v[232:235], v[216:219], v[14:17]
	v_mfma_f32_16x16x32_bf16 v[10:13], v[240:243], v[216:219], v[10:13]
	v_mfma_f32_16x16x32_bf16 v[6:9], v[232:235], v[224:227], v[6:9]
	v_mfma_f32_16x16x32_bf16 v[2:5], v[240:243], v[224:227], v[2:5]
	s_add_i32 s44, s44, 2
	s_add_u32 s68, s68, 0x100
	s_addc_u32 s69, s69, 0
	s_add_u32 s43, s43, 0x100
	s_addc_u32 s92, s92, 0
	s_cmp_gt_u32 s44, 29
	s_barrier
	s_cbranch_scc0 .LBB0_304
	v_lshl_add_u32 v146, s47, 8, v140
	v_lshl_or_b32 v144, s46, 8, v142
	v_cvt_pk_bf16_f32 v126, v126, v127
	v_cvt_pk_bf16_f32 v127, v128, v129
	v_cvt_pk_bf16_f32 v128, v122, v123
	v_mov_b64_e32 v[122:123], s[22:23]
	v_ashrrev_i32_e32 v145, 31, v144
	v_cvt_pk_bf16_f32 v70, v70, v71
	v_cvt_pk_bf16_f32 v71, v72, v73
	v_cvt_pk_bf16_f32 v72, v66, v67
	v_add_u32_e32 v66, 0x80, v146
	v_cvt_pk_bf16_f32 v129, v124, v125
	v_mad_i64_i32 v[124:125], s[24:25], v146, s97, v[122:123]
	v_lshlrev_b64 v[144:145], 1, v[144:145]
	v_cvt_pk_bf16_f32 v62, v62, v63
	v_cvt_pk_bf16_f32 v63, v64, v65
	v_cvt_pk_bf16_f32 v64, v58, v59
	v_mad_i64_i32 v[58:59], s[24:25], v66, s97, v[122:123]
	v_lshl_add_u64 v[124:125], v[124:125], 0, v[144:145]
	v_cvt_pk_bf16_f32 v110, v110, v111
	v_cvt_pk_bf16_f32 v111, v112, v113
	v_cvt_pk_bf16_f32 v112, v106, v107
	v_cvt_pk_bf16_f32 v113, v108, v109
	v_lshl_add_u64 v[58:59], v[58:59], 0, v[144:145]
	v_cvt_pk_bf16_f32 v46, v46, v47
	v_cvt_pk_bf16_f32 v47, v48, v49
	v_cvt_pk_bf16_f32 v48, v42, v43
	v_cvt_pk_bf16_f32 v49, v44, v45
	global_store_dwordx4 v[124:125], v[110:113], off offset:256
	global_store_dwordx4 v[58:59], v[46:49], off offset:256
	v_cvt_pk_bf16_f32 v94, v94, v95
	v_or_b32_e32 v110, 16, v146
	v_add_u32_e32 v46, 0x90, v146
	v_mad_i64_i32 v[110:111], s[24:25], v110, s97, v[122:123]
	v_mad_i64_i32 v[46:47], s[24:25], v46, s97, v[122:123]
	v_lshl_add_u64 v[110:111], v[110:111], 0, v[144:145]
	v_cvt_pk_bf16_f32 v95, v96, v97
	v_cvt_pk_bf16_f32 v96, v90, v91
	v_cvt_pk_bf16_f32 v97, v92, v93
	v_lshl_add_u64 v[46:47], v[46:47], 0, v[144:145]
	v_cvt_pk_bf16_f32 v30, v30, v31
	v_cvt_pk_bf16_f32 v31, v32, v33
	v_cvt_pk_bf16_f32 v32, v26, v27
	v_cvt_pk_bf16_f32 v33, v28, v29
	global_store_dwordx4 v[110:111], v[94:97], off offset:256
	global_store_dwordx4 v[46:47], v[30:33], off offset:256
	v_cvt_pk_bf16_f32 v78, v78, v79
	v_or_b32_e32 v94, 32, v146
	v_add_u32_e32 v30, 0xa0, v146
	v_mad_i64_i32 v[94:95], s[24:25], v94, s97, v[122:123]
	v_mad_i64_i32 v[30:31], s[24:25], v30, s97, v[122:123]
	v_lshl_add_u64 v[94:95], v[94:95], 0, v[144:145]
	v_cvt_pk_bf16_f32 v79, v80, v81
	v_cvt_pk_bf16_f32 v80, v74, v75
	v_cvt_pk_bf16_f32 v81, v76, v77
	v_lshl_add_u64 v[30:31], v[30:31], 0, v[144:145]
	v_cvt_pk_bf16_f32 v14, v14, v15
	v_cvt_pk_bf16_f32 v15, v16, v17
	v_cvt_pk_bf16_f32 v16, v10, v11
	v_cvt_pk_bf16_f32 v17, v12, v13
	global_store_dwordx4 v[94:95], v[78:81], off offset:256
	global_store_dwordx4 v[30:31], v[14:17], off offset:256
	v_cvt_pk_bf16_f32 v106, v118, v119
	v_or_b32_e32 v78, 48, v146
	v_add_u32_e32 v14, 0xb0, v146
	v_mad_i64_i32 v[78:79], s[24:25], v78, s97, v[122:123]
	v_mad_i64_i32 v[14:15], s[24:25], v14, s97, v[122:123]
	v_cvt_pk_bf16_f32 v107, v120, v121
	v_cvt_pk_bf16_f32 v108, v114, v115
	v_cvt_pk_bf16_f32 v109, v116, v117
	v_cvt_pk_bf16_f32 v90, v102, v103
	v_cvt_pk_bf16_f32 v91, v104, v105
	v_cvt_pk_bf16_f32 v92, v98, v99
	v_cvt_pk_bf16_f32 v93, v100, v101
	v_cvt_pk_bf16_f32 v74, v86, v87
	v_cvt_pk_bf16_f32 v75, v88, v89
	v_cvt_pk_bf16_f32 v76, v82, v83
	v_cvt_pk_bf16_f32 v77, v84, v85
	v_lshl_add_u64 v[78:79], v[78:79], 0, v[144:145]
	v_cvt_pk_bf16_f32 v73, v68, v69
	v_cvt_pk_bf16_f32 v65, v60, v61
	v_cvt_pk_bf16_f32 v42, v54, v55
	v_cvt_pk_bf16_f32 v43, v56, v57
	v_cvt_pk_bf16_f32 v44, v50, v51
	v_cvt_pk_bf16_f32 v45, v52, v53
	v_cvt_pk_bf16_f32 v26, v38, v39
	v_cvt_pk_bf16_f32 v27, v40, v41
	v_cvt_pk_bf16_f32 v28, v34, v35
	v_cvt_pk_bf16_f32 v29, v36, v37
	v_cvt_pk_bf16_f32 v10, v22, v23
	v_cvt_pk_bf16_f32 v11, v24, v25
	v_cvt_pk_bf16_f32 v12, v18, v19
	v_cvt_pk_bf16_f32 v13, v20, v21
	v_lshl_add_u64 v[14:15], v[14:15], 0, v[144:145]
	v_cvt_pk_bf16_f32 v6, v6, v7
	v_cvt_pk_bf16_f32 v7, v8, v9
	v_cvt_pk_bf16_f32 v8, v2, v3
	v_cvt_pk_bf16_f32 v9, v4, v5
	s_and_b64 vcc, exec, s[0:1]
	s_mov_b32 s46, s42
	s_mov_b32 s47, s54
	s_mov_b64 s[70:71], s[64:65]
	s_mov_b64 s[68:69], s[62:63]
	global_store_dwordx4 v[124:125], v[126:129], off
	global_store_dwordx4 v[110:111], v[106:109], off
	global_store_dwordx4 v[94:95], v[90:93], off
	global_store_dwordx4 v[78:79], v[74:77], off
	global_store_dwordx4 v[78:79], v[70:73], off offset:256
	global_store_dwordx4 v[58:59], v[62:65], off
	global_store_dwordx4 v[46:47], v[42:45], off
	global_store_dwordx4 v[30:31], v[26:29], off
	global_store_dwordx4 v[14:15], v[10:13], off
	global_store_dwordx4 v[14:15], v[6:9], off offset:256
	s_cbranch_vccz .LBB0_301
	v_readlane_b32 s0, v254, 12
	s_waitcnt vmcnt(0)
	v_readlane_b32 s1, v254, 13
	v_readlane_b32 s84, v251, 38
	v_readlane_b32 s18, v253, 0
	s_andn2_b64 vcc, exec, s[0:1]
	v_readlane_b32 s85, v251, 39
	v_readlane_b32 s86, v251, 40
	v_readlane_b32 s87, v251, 41
	v_readlane_b32 s14, v250, 63
	v_readlane_b32 s19, v253, 1
	s_cbranch_vccnz .LBB0_308
	s_barrier

.LBB0_433:
	s_add_u32 s6, s78, 0x100
	s_addc_u32 s7, s79, 0
	s_add_i32 s2, 0, 0x10000
	v_add_u32_e32 v0, s2, v153
	ds_read_b128 v[142:145], v0
	ds_read_b128 v[146:149], v0 offset:1024
	ds_read_b128 v[156:159], v0 offset:2048
	ds_read_b128 v[160:163], v0 offset:3072
	s_cmp_eq_u32 s44, 4
	s_cselect_b32 s83, s75, s7
	s_cselect_b32 s82, s74, s6
	s_cselect_b32 s81, s11, s46
	s_cselect_b32 s80, s24, s25
	v_lshl_add_u64 v[150:151], s[78:79], 0, v[138:139]
	s_add_i32 m0, s58, 0xc000
	ds_read_b128 v[188:191], v155
	ds_read_b128 v[192:195], v155 offset:1024
	ds_read_b128 v[196:199], v155 offset:2048
	ds_read_b128 v[200:203], v155 offset:3072
	ds_read_b128 v[216:219], v155 offset:4096
	ds_read_b128 v[220:223], v155 offset:5120
	ds_read_b128 v[224:227], v155 offset:6144
	ds_read_b128 v[228:231], v155 offset:7168
	global_load_lds_dwordx4 v[150:151], off
	v_lshl_add_u64 v[150:151], s[78:79], 0, v[140:141]
	s_add_i32 m0, s58, 0xe000
	s_nop 0
	global_load_lds_dwordx4 v[150:151], off
	s_waitcnt lgkmcnt(8)
	s_barrier
	s_waitcnt lgkmcnt(7)
	v_mfma_f32_16x16x32_bf16 v[126:129], v[142:145], v[188:191], v[126:129]
	v_mfma_f32_16x16x32_bf16 v[122:125], v[156:159], v[188:191], v[122:125]
	s_waitcnt lgkmcnt(3)
	v_mfma_f32_16x16x32_bf16 v[110:113], v[142:145], v[196:199], v[110:113]
	v_mfma_f32_16x16x32_bf16 v[106:109], v[156:159], v[196:199], v[106:109]
	v_mfma_f32_16x16x32_bf16 v[94:97], v[142:145], v[216:219], v[94:97]
	v_mfma_f32_16x16x32_bf16 v[90:93], v[156:159], v[216:219], v[90:93]
	s_waitcnt lgkmcnt(0)
	v_mfma_f32_16x16x32_bf16 v[78:81], v[142:145], v[224:227], v[78:81]
	v_mfma_f32_16x16x32_bf16 v[74:77], v[156:159], v[224:227], v[74:77]
	v_mfma_f32_16x16x32_bf16 v[126:129], v[146:149], v[192:195], v[126:129]
	v_mfma_f32_16x16x32_bf16 v[122:125], v[160:163], v[192:195], v[122:125]
	v_mfma_f32_16x16x32_bf16 v[110:113], v[146:149], v[200:203], v[110:113]
	v_mfma_f32_16x16x32_bf16 v[106:109], v[160:163], v[200:203], v[106:109]
	v_mfma_f32_16x16x32_bf16 v[94:97], v[146:149], v[220:223], v[94:97]
	v_mfma_f32_16x16x32_bf16 v[90:93], v[160:163], v[220:223], v[90:93]
	v_mfma_f32_16x16x32_bf16 v[78:81], v[146:149], v[228:231], v[78:81]
	v_mfma_f32_16x16x32_bf16 v[74:77], v[160:163], v[228:231], v[74:77]
	s_barrier
	s_add_i32 s17, 0, 0x14000
	s_add_i32 s2, s2, s3
	v_add_u32_e32 v0, s17, v153
	v_lshl_add_u64 v[150:151], s[80:81], 0, v[134:135]
	s_mov_b32 m0, s2
	ds_read_b128 v[232:235], v0
	ds_read_b128 v[236:239], v0 offset:1024
	ds_read_b128 v[240:243], v0 offset:2048
	ds_read_b128 v[244:247], v0 offset:3072
	global_load_lds_dwordx4 v[150:151], off
	v_lshl_add_u64 v[164:165], s[80:81], 0, v[130:131]
	s_add_i32 m0, s2, 0x2000
	s_nop 0
	global_load_lds_dwordx4 v[164:165], off
	s_barrier
	s_waitcnt lgkmcnt(1)
	v_mfma_f32_16x16x32_bf16 v[118:121], v[232:235], v[188:191], v[118:121]
	v_mfma_f32_16x16x32_bf16 v[114:117], v[240:243], v[188:191], v[114:117]
	v_mfma_f32_16x16x32_bf16 v[102:105], v[232:235], v[196:199], v[102:105]
	v_mfma_f32_16x16x32_bf16 v[98:101], v[240:243], v[196:199], v[98:101]
	v_mfma_f32_16x16x32_bf16 v[86:89], v[232:235], v[216:219], v[86:89]
	v_mfma_f32_16x16x32_bf16 v[82:85], v[240:243], v[216:219], v[82:85]
	s_waitcnt lgkmcnt(0)
	v_mfma_f32_16x16x32_bf16 v[70:73], v[232:235], v[224:227], v[70:73]
	v_mfma_f32_16x16x32_bf16 v[66:69], v[240:243], v[224:227], v[66:69]
	v_mfma_f32_16x16x32_bf16 v[118:121], v[236:239], v[192:195], v[118:121]
	v_mfma_f32_16x16x32_bf16 v[114:117], v[244:247], v[192:195], v[114:117]
	v_mfma_f32_16x16x32_bf16 v[102:105], v[236:239], v[200:203], v[102:105]
	v_mfma_f32_16x16x32_bf16 v[98:101], v[244:247], v[200:203], v[98:101]
	v_mfma_f32_16x16x32_bf16 v[86:89], v[236:239], v[220:223], v[86:89]
	v_mfma_f32_16x16x32_bf16 v[82:85], v[244:247], v[220:223], v[82:85]
	v_mfma_f32_16x16x32_bf16 v[70:73], v[236:239], v[228:231], v[70:73]
	v_mfma_f32_16x16x32_bf16 v[66:69], v[244:247], v[228:231], v[66:69]
	s_mov_b32 m0, s58
	v_lshl_add_u64 v[204:205], s[82:83], 0, v[136:137]
	s_barrier
	ds_read_b128 v[188:191], v155 offset:16384
	ds_read_b128 v[192:195], v155 offset:17408
	ds_read_b128 v[196:199], v155 offset:18432
	ds_read_b128 v[200:203], v155 offset:19456
	ds_read_b128 v[216:219], v155 offset:20480
	ds_read_b128 v[220:223], v155 offset:21504
	ds_read_b128 v[224:227], v155 offset:22528
	ds_read_b128 v[228:231], v155 offset:23552
	global_load_lds_dwordx4 v[204:205], off
	v_lshl_add_u64 v[248:249], s[82:83], 0, v[132:133]
	s_mov_b32 m0, s69
	s_nop 0
	global_load_lds_dwordx4 v[248:249], off
	s_barrier
	s_waitcnt lgkmcnt(7)
	v_mfma_f32_16x16x32_bf16 v[62:65], v[142:145], v[188:191], v[62:65]
	v_mfma_f32_16x16x32_bf16 v[58:61], v[156:159], v[188:191], v[58:61]
	s_waitcnt lgkmcnt(3)
	v_mfma_f32_16x16x32_bf16 v[46:49], v[142:145], v[196:199], v[46:49]
	v_mfma_f32_16x16x32_bf16 v[42:45], v[156:159], v[196:199], v[42:45]
	v_mfma_f32_16x16x32_bf16 v[30:33], v[142:145], v[216:219], v[30:33]
	v_mfma_f32_16x16x32_bf16 v[26:29], v[156:159], v[216:219], v[26:29]
	s_waitcnt lgkmcnt(0)
	v_mfma_f32_16x16x32_bf16 v[14:17], v[142:145], v[224:227], v[14:17]
	v_mfma_f32_16x16x32_bf16 v[10:13], v[156:159], v[224:227], v[10:13]
	v_mfma_f32_16x16x32_bf16 v[62:65], v[146:149], v[192:195], v[62:65]
	v_mfma_f32_16x16x32_bf16 v[58:61], v[160:163], v[192:195], v[58:61]
	v_mfma_f32_16x16x32_bf16 v[46:49], v[146:149], v[200:203], v[46:49]
	v_mfma_f32_16x16x32_bf16 v[42:45], v[160:163], v[200:203], v[42:45]
	v_mfma_f32_16x16x32_bf16 v[30:33], v[146:149], v[220:223], v[30:33]
	v_mfma_f32_16x16x32_bf16 v[26:29], v[160:163], v[220:223], v[26:29]
	v_mfma_f32_16x16x32_bf16 v[14:17], v[146:149], v[228:231], v[14:17]
	v_mfma_f32_16x16x32_bf16 v[10:13], v[160:163], v[228:231], v[10:13]
	s_barrier
	s_add_u32 s26, s80, 0x20000
	s_addc_u32 s27, s81, 0
	s_add_i32 s2, s17, s3
	v_lshl_add_u64 v[142:143], s[26:27], 0, v[134:135]
	s_mov_b32 m0, s2
	s_nop 0
	global_load_lds_dwordx4 v[142:143], off
	v_lshl_add_u64 v[142:143], s[26:27], 0, v[130:131]
	s_add_i32 m0, s2, 0x2000
	s_nop 0
	global_load_lds_dwordx4 v[142:143], off
	s_waitcnt vmcnt(6)
	s_barrier
	v_mfma_f32_16x16x32_bf16 v[54:57], v[232:235], v[188:191], v[54:57]
	v_mfma_f32_16x16x32_bf16 v[50:53], v[240:243], v[188:191], v[50:53]
	v_mfma_f32_16x16x32_bf16 v[38:41], v[232:235], v[196:199], v[38:41]
	v_mfma_f32_16x16x32_bf16 v[34:37], v[240:243], v[196:199], v[34:37]
	v_mfma_f32_16x16x32_bf16 v[22:25], v[232:235], v[216:219], v[22:25]
	v_mfma_f32_16x16x32_bf16 v[18:21], v[240:243], v[216:219], v[18:21]
	v_mfma_f32_16x16x32_bf16 v[6:9], v[232:235], v[224:227], v[6:9]
	v_mfma_f32_16x16x32_bf16 v[2:5], v[240:243], v[224:227], v[2:5]
	v_mfma_f32_16x16x32_bf16 v[54:57], v[236:239], v[192:195], v[54:57]
	v_mfma_f32_16x16x32_bf16 v[50:53], v[244:247], v[192:195], v[50:53]
	v_mfma_f32_16x16x32_bf16 v[38:41], v[236:239], v[200:203], v[38:41]
	v_mfma_f32_16x16x32_bf16 v[34:37], v[244:247], v[200:203], v[34:37]
	v_mfma_f32_16x16x32_bf16 v[22:25], v[236:239], v[220:223], v[22:25]
	v_mfma_f32_16x16x32_bf16 v[18:21], v[244:247], v[220:223], v[18:21]
	v_mfma_f32_16x16x32_bf16 v[6:9], v[236:239], v[228:231], v[6:9]
	v_mfma_f32_16x16x32_bf16 v[2:5], v[244:247], v[228:231], v[2:5]
	s_add_i32 s2, 0, 0x18000
	v_add_u32_e32 v0, s2, v153
	s_barrier
	ds_read_b128 v[142:145], v0
	ds_read_b128 v[146:149], v0 offset:1024
	ds_read_b128 v[156:159], v0 offset:2048
	ds_read_b128 v[160:163], v0 offset:3072
	s_add_u32 s26, s82, 0xd0000
	s_addc_u32 s27, s83, 0
	s_mov_b32 m0, s92
	v_lshl_add_u64 v[232:233], s[26:27], 0, v[136:137]
	ds_read_b128 v[188:191], v155 offset:32768
	ds_read_b128 v[192:195], v155 offset:33792
	ds_read_b128 v[196:199], v155 offset:34816
	ds_read_b128 v[200:203], v155 offset:35840
	ds_read_b128 v[216:219], v155 offset:36864
	ds_read_b128 v[220:223], v155 offset:37888
	ds_read_b128 v[224:227], v155 offset:38912
	ds_read_b128 v[228:231], v155 offset:39936
	global_load_lds_dwordx4 v[232:233], off
	v_lshl_add_u64 v[232:233], s[26:27], 0, v[132:133]
	s_mov_b32 m0, s93
	s_nop 0
	global_load_lds_dwordx4 v[232:233], off
	s_waitcnt lgkmcnt(8)
	s_barrier
	s_waitcnt lgkmcnt(7)
	v_mfma_f32_16x16x32_bf16 v[126:129], v[142:145], v[188:191], v[126:129]
	v_mfma_f32_16x16x32_bf16 v[122:125], v[156:159], v[188:191], v[122:125]
	s_waitcnt lgkmcnt(3)
	v_mfma_f32_16x16x32_bf16 v[110:113], v[142:145], v[196:199], v[110:113]
	v_mfma_f32_16x16x32_bf16 v[106:109], v[156:159], v[196:199], v[106:109]
	v_mfma_f32_16x16x32_bf16 v[94:97], v[142:145], v[216:219], v[94:97]
	v_mfma_f32_16x16x32_bf16 v[90:93], v[156:159], v[216:219], v[90:93]
	s_waitcnt lgkmcnt(0)
	v_mfma_f32_16x16x32_bf16 v[78:81], v[142:145], v[224:227], v[78:81]
	v_mfma_f32_16x16x32_bf16 v[74:77], v[156:159], v[224:227], v[74:77]
	v_mfma_f32_16x16x32_bf16 v[126:129], v[146:149], v[192:195], v[126:129]
	v_mfma_f32_16x16x32_bf16 v[122:125], v[160:163], v[192:195], v[122:125]
	v_mfma_f32_16x16x32_bf16 v[110:113], v[146:149], v[200:203], v[110:113]
	v_mfma_f32_16x16x32_bf16 v[106:109], v[160:163], v[200:203], v[106:109]
	v_mfma_f32_16x16x32_bf16 v[94:97], v[146:149], v[220:223], v[94:97]
	v_mfma_f32_16x16x32_bf16 v[90:93], v[160:163], v[220:223], v[90:93]
	v_mfma_f32_16x16x32_bf16 v[78:81], v[146:149], v[228:231], v[78:81]
	v_mfma_f32_16x16x32_bf16 v[74:77], v[160:163], v[228:231], v[74:77]
	s_barrier
	s_add_i32 s17, 0, 0x1c000
	s_add_i32 s2, s2, s3
	v_add_u32_e32 v0, s17, v153
	v_lshl_add_u64 v[150:151], v[150:151], 0, s[28:29]
	s_mov_b32 m0, s2
	ds_read_b128 v[232:235], v0
	ds_read_b128 v[236:239], v0 offset:1024
	ds_read_b128 v[240:243], v0 offset:2048
	ds_read_b128 v[244:247], v0 offset:3072
	global_load_lds_dwordx4 v[150:151], off
	v_lshl_add_u64 v[150:151], v[164:165], 0, s[28:29]
	s_add_i32 m0, s2, 0x2000
	s_nop 0
	global_load_lds_dwordx4 v[150:151], off
	s_barrier
	s_waitcnt lgkmcnt(1)
	v_mfma_f32_16x16x32_bf16 v[118:121], v[232:235], v[188:191], v[118:121]
	v_mfma_f32_16x16x32_bf16 v[114:117], v[240:243], v[188:191], v[114:117]
	v_mfma_f32_16x16x32_bf16 v[102:105], v[232:235], v[196:199], v[102:105]
	v_mfma_f32_16x16x32_bf16 v[98:101], v[240:243], v[196:199], v[98:101]
	v_mfma_f32_16x16x32_bf16 v[86:89], v[232:235], v[216:219], v[86:89]
	v_mfma_f32_16x16x32_bf16 v[82:85], v[240:243], v[216:219], v[82:85]
	s_waitcnt lgkmcnt(0)
	v_mfma_f32_16x16x32_bf16 v[70:73], v[232:235], v[224:227], v[70:73]
	v_mfma_f32_16x16x32_bf16 v[66:69], v[240:243], v[224:227], v[66:69]
	v_mfma_f32_16x16x32_bf16 v[118:121], v[236:239], v[192:195], v[118:121]
	v_mfma_f32_16x16x32_bf16 v[114:117], v[244:247], v[192:195], v[114:117]
	v_mfma_f32_16x16x32_bf16 v[102:105], v[236:239], v[200:203], v[102:105]
	v_mfma_f32_16x16x32_bf16 v[98:101], v[244:247], v[200:203], v[98:101]
	v_mfma_f32_16x16x32_bf16 v[86:89], v[236:239], v[220:223], v[86:89]
	v_mfma_f32_16x16x32_bf16 v[82:85], v[244:247], v[220:223], v[82:85]
	v_mfma_f32_16x16x32_bf16 v[70:73], v[236:239], v[228:231], v[70:73]
	v_mfma_f32_16x16x32_bf16 v[66:69], v[244:247], v[228:231], v[66:69]
	s_mov_b32 m0, s72
	v_lshl_add_u64 v[150:151], v[204:205], 0, s[28:29]
	s_barrier
	ds_read_b128 v[188:191], v155 offset:49152
	ds_read_b128 v[192:195], v155 offset:50176
	ds_read_b128 v[196:199], v155 offset:51200
	ds_read_b128 v[200:203], v155 offset:52224
	ds_read_b128 v[216:219], v155 offset:53248
	ds_read_b128 v[220:223], v155 offset:54272
	ds_read_b128 v[224:227], v155 offset:55296
	ds_read_b128 v[228:231], v155 offset:56320
	global_load_lds_dwordx4 v[150:151], off
	v_lshl_add_u64 v[150:151], v[248:249], 0, s[28:29]
	s_mov_b32 m0, s73
	s_nop 0
	global_load_lds_dwordx4 v[150:151], off
	s_barrier
	s_waitcnt lgkmcnt(7)
	v_mfma_f32_16x16x32_bf16 v[62:65], v[142:145], v[188:191], v[62:65]
	v_mfma_f32_16x16x32_bf16 v[58:61], v[156:159], v[188:191], v[58:61]
	s_waitcnt lgkmcnt(3)
	v_mfma_f32_16x16x32_bf16 v[46:49], v[142:145], v[196:199], v[46:49]
	v_mfma_f32_16x16x32_bf16 v[42:45], v[156:159], v[196:199], v[42:45]
	v_mfma_f32_16x16x32_bf16 v[30:33], v[142:145], v[216:219], v[30:33]
	v_mfma_f32_16x16x32_bf16 v[26:29], v[156:159], v[216:219], v[26:29]
	s_waitcnt lgkmcnt(0)
	v_mfma_f32_16x16x32_bf16 v[14:17], v[142:145], v[224:227], v[14:17]
	v_mfma_f32_16x16x32_bf16 v[10:13], v[156:159], v[224:227], v[10:13]
	v_mfma_f32_16x16x32_bf16 v[62:65], v[146:149], v[192:195], v[62:65]
	v_mfma_f32_16x16x32_bf16 v[58:61], v[160:163], v[192:195], v[58:61]
	v_mfma_f32_16x16x32_bf16 v[46:49], v[146:149], v[200:203], v[46:49]
	v_mfma_f32_16x16x32_bf16 v[42:45], v[160:163], v[200:203], v[42:45]
	v_mfma_f32_16x16x32_bf16 v[30:33], v[146:149], v[220:223], v[30:33]
	v_mfma_f32_16x16x32_bf16 v[26:29], v[160:163], v[220:223], v[26:29]
	v_mfma_f32_16x16x32_bf16 v[14:17], v[146:149], v[228:231], v[14:17]
	v_mfma_f32_16x16x32_bf16 v[10:13], v[160:163], v[228:231], v[10:13]
	s_barrier
	s_add_u32 s26, s80, 0x20080
	s_addc_u32 s27, s81, 0
	s_add_i32 s2, s17, s3
	v_lshl_add_u64 v[142:143], s[26:27], 0, v[134:135]
	s_mov_b32 m0, s2
	s_nop 0
	global_load_lds_dwordx4 v[142:143], off
	v_lshl_add_u64 v[142:143], s[26:27], 0, v[130:131]
	s_add_i32 m0, s2, 0x2000
	s_nop 0
	global_load_lds_dwordx4 v[142:143], off
	s_waitcnt vmcnt(6)
	s_barrier
	v_mfma_f32_16x16x32_bf16 v[54:57], v[232:235], v[188:191], v[54:57]
	v_mfma_f32_16x16x32_bf16 v[50:53], v[240:243], v[188:191], v[50:53]
	v_mfma_f32_16x16x32_bf16 v[38:41], v[232:235], v[196:199], v[38:41]
	v_mfma_f32_16x16x32_bf16 v[34:37], v[240:243], v[196:199], v[34:37]
	v_mfma_f32_16x16x32_bf16 v[22:25], v[232:235], v[216:219], v[22:25]
	v_mfma_f32_16x16x32_bf16 v[18:21], v[240:243], v[216:219], v[18:21]
	v_mfma_f32_16x16x32_bf16 v[6:9], v[232:235], v[224:227], v[6:9]
	v_mfma_f32_16x16x32_bf16 v[2:5], v[240:243], v[224:227], v[2:5]
	v_mfma_f32_16x16x32_bf16 v[54:57], v[236:239], v[192:195], v[54:57]
	v_mfma_f32_16x16x32_bf16 v[50:53], v[244:247], v[192:195], v[50:53]
	v_mfma_f32_16x16x32_bf16 v[38:41], v[236:239], v[200:203], v[38:41]
	v_mfma_f32_16x16x32_bf16 v[34:37], v[244:247], v[200:203], v[34:37]
	v_mfma_f32_16x16x32_bf16 v[22:25], v[236:239], v[220:223], v[22:25]
	v_mfma_f32_16x16x32_bf16 v[18:21], v[244:247], v[220:223], v[18:21]
	v_mfma_f32_16x16x32_bf16 v[6:9], v[236:239], v[228:231], v[6:9]
	v_mfma_f32_16x16x32_bf16 v[2:5], v[244:247], v[228:231], v[2:5]
	s_add_i32 s44, s44, 2
	s_add_u32 s25, s25, 0x100
	s_addc_u32 s46, s46, 0
	s_cmp_gt_u32 s44, 5
	s_mov_b64 s[78:79], s[6:7]
	s_barrier
	s_cbranch_scc0 .LBB0_433
	v_lshl_add_u32 v144, s41, 8, v152
	v_ashrrev_i32_e32 v145, 31, v144
	v_lshl_add_u64 v[146:147], v[144:145], 2, s[50:51]
	global_load_dword v216, v[146:147], off
	global_load_dword v217, v[146:147], off offset:64
	global_load_dword v218, v[146:147], off offset:128
	global_load_dword v219, v[146:147], off offset:192
	global_load_dword v220, v[146:147], off offset:512
	global_load_dword v221, v[146:147], off offset:576
	global_load_dword v222, v[146:147], off offset:640
	global_load_dword v223, v[146:147], off offset:704
	v_lshl_or_b32 v142, s40, 8, v154
	s_mov_b32 s2, 0x2aaaaaab
	v_mul_hi_i32 v143, v142, s2
	v_lshlrev_b64 v[148:149], 8, v[144:145]
	v_lshrrev_b32_e32 v145, 31, v143
	v_lshrrev_b32_e32 v143, 5, v143
	v_add_u32_e32 v143, v143, v145
	s_movk_i32 s2, 0xc0
	v_mul_lo_u32 v143, v143, s2
	v_sub_u32_e32 v143, v142, v143
	s_movk_i32 s2, 0x7f
	v_cmp_lt_i32_e32 vcc, s2, v143
	v_add_u32_e32 v143, 0xffffff80, v143
	v_lshl_add_u64 v[148:149], s[20:21], 0, v[148:149]
	s_waitcnt vmcnt(0)
	v_mov_b32_e32 v0, v216
	v_mul_f32_e32 v150, 0x3dd53b94, v0
	v_pk_mul_f32 v[128:129], v[128:129], v[150:151] op_sel_hi:[1,0]
	v_pk_mul_f32 v[126:127], v[126:127], v[150:151] op_sel_hi:[1,0]
	v_pk_mul_f32 v[124:125], v[124:125], v[150:151] op_sel_hi:[1,0]
	v_pk_mul_f32 v[122:123], v[122:123], v[150:151] op_sel_hi:[1,0]
	v_lshrrev_b32_e32 v0, 1, v143
	s_and_saveexec_b64 s[6:7], vcc
	s_cbranch_execz .LBB0_436
	v_lshl_add_u64 v[160:161], v[0:1], 3, v[148:149]
	global_load_dwordx4 v[156:159], v[160:161], off offset:16
	s_nop 0
	global_load_dwordx4 v[160:163], v[160:161], off
	s_waitcnt vmcnt(0)
	v_pk_mul_f32 v[190:191], v[122:123], v[156:157] op_sel:[1,1] op_sel_hi:[0,1]
	v_pk_mul_f32 v[188:189], v[126:127], v[160:161] op_sel:[1,1] op_sel_hi:[0,1]
	v_pk_mul_f32 v[164:165], v[126:127], v[160:161]
	v_pk_fma_f32 v[126:127], v[126:127], v[160:161], v[188:189] op_sel_hi:[1,0,1]
	s_nop 0
	v_mul_f32_e32 v126, v129, v163
	v_pk_fma_f32 v[160:161], v[128:129], v[162:163], v[126:127] op_sel_hi:[1,1,0] neg_lo:[0,0,1] neg_hi:[0,0,1]
	v_mul_f32_e32 v126, v128, v163
	v_pk_fma_f32 v[162:163], v[128:129], v[162:163], v[126:127] op_sel:[1,0,0] op_sel_hi:[0,1,0]
	v_pk_mul_f32 v[128:129], v[122:123], v[156:157]
	v_pk_fma_f32 v[122:123], v[122:123], v[156:157], v[190:191] op_sel_hi:[1,0,1]
	v_sub_f32_e32 v126, v164, v188
	v_mul_f32_e32 v122, v125, v159
	v_pk_fma_f32 v[156:157], v[124:125], v[158:159], v[122:123] op_sel_hi:[1,1,0] neg_lo:[0,0,1] neg_hi:[0,0,1]
	v_mul_f32_e32 v122, v124, v159
	v_pk_fma_f32 v[158:159], v[124:125], v[158:159], v[122:123] op_sel:[1,0,0] op_sel_hi:[0,1,0]
	v_sub_f32_e32 v122, v128, v190
	v_mov_b32_e32 v128, v160
	v_mov_b32_e32 v129, v162
	v_mov_b32_e32 v124, v156
	v_mov_b32_e32 v125, v158

.LBB0_482:
	s_add_u32 s10, s80, 0x100
	s_addc_u32 s11, s81, 0
	s_add_i32 s2, 0, 0x10000
	v_add_u32_e32 v156, s2, v145
	ds_read_b128 v[140:143], v156
	ds_read_b128 v[148:151], v156 offset:1024
	ds_read_b128 v[152:155], v156 offset:2048
	ds_read_b128 v[156:159], v156 offset:3072
	s_cmp_eq_u32 s44, 4
	s_cselect_b32 s93, s77, s11
	s_cselect_b32 s92, s76, s10
	s_cselect_b32 s83, s24, s47
	s_cselect_b32 s82, s25, s46
	v_lshl_add_u64 v[164:165], s[80:81], 0, v[136:137]
	s_add_i32 m0, s58, 0xc000
	ds_read_b128 v[160:163], v147
	ds_read_b128 v[188:191], v147 offset:1024
	ds_read_b128 v[192:195], v147 offset:2048
	ds_read_b128 v[196:199], v147 offset:3072
	ds_read_b128 v[200:203], v147 offset:4096
	ds_read_b128 v[216:219], v147 offset:5120
	ds_read_b128 v[220:223], v147 offset:6144
	ds_read_b128 v[224:227], v147 offset:7168
	global_load_lds_dwordx4 v[164:165], off
	v_lshl_add_u64 v[164:165], s[80:81], 0, v[138:139]
	s_add_i32 m0, s58, 0xe000
	s_nop 0
	global_load_lds_dwordx4 v[164:165], off
	s_waitcnt lgkmcnt(8)
	s_barrier
	s_waitcnt lgkmcnt(7)
	v_mfma_f32_16x16x32_bf16 v[126:129], v[140:143], v[160:163], v[126:129]
	v_mfma_f32_16x16x32_bf16 v[122:125], v[152:155], v[160:163], v[122:125]
	s_waitcnt lgkmcnt(3)
	v_mfma_f32_16x16x32_bf16 v[110:113], v[140:143], v[192:195], v[110:113]
	v_mfma_f32_16x16x32_bf16 v[106:109], v[152:155], v[192:195], v[106:109]
	v_mfma_f32_16x16x32_bf16 v[94:97], v[140:143], v[200:203], v[94:97]
	v_mfma_f32_16x16x32_bf16 v[90:93], v[152:155], v[200:203], v[90:93]
	s_waitcnt lgkmcnt(0)
	v_mfma_f32_16x16x32_bf16 v[78:81], v[140:143], v[220:223], v[78:81]
	v_mfma_f32_16x16x32_bf16 v[74:77], v[152:155], v[220:223], v[74:77]
	v_mfma_f32_16x16x32_bf16 v[126:129], v[148:151], v[188:191], v[126:129]
	v_mfma_f32_16x16x32_bf16 v[122:125], v[156:159], v[188:191], v[122:125]
	v_mfma_f32_16x16x32_bf16 v[110:113], v[148:151], v[196:199], v[110:113]
	v_mfma_f32_16x16x32_bf16 v[106:109], v[156:159], v[196:199], v[106:109]
	v_mfma_f32_16x16x32_bf16 v[94:97], v[148:151], v[216:219], v[94:97]
	v_mfma_f32_16x16x32_bf16 v[90:93], v[156:159], v[216:219], v[90:93]
	v_mfma_f32_16x16x32_bf16 v[78:81], v[148:151], v[224:227], v[78:81]
	v_mfma_f32_16x16x32_bf16 v[74:77], v[156:159], v[224:227], v[74:77]
	s_barrier
	s_add_i32 s17, 0, 0x14000
	v_add_u32_e32 v164, s17, v145
	s_add_i32 s2, s2, s3
	ds_read_b128 v[228:231], v164
	ds_read_b128 v[232:235], v164 offset:1024
	ds_read_b128 v[236:239], v164 offset:2048
	ds_read_b128 v[240:243], v164 offset:3072
	v_lshl_add_u64 v[164:165], s[82:83], 0, v[0:1]
	s_mov_b32 m0, s2
	v_lshl_add_u64 v[204:205], s[82:83], 0, v[130:131]
	global_load_lds_dwordx4 v[164:165], off
	s_add_i32 m0, s2, 0x2000
	s_nop 0
	global_load_lds_dwordx4 v[204:205], off
	s_barrier
	s_waitcnt lgkmcnt(1)
	v_mfma_f32_16x16x32_bf16 v[118:121], v[228:231], v[160:163], v[118:121]
	v_mfma_f32_16x16x32_bf16 v[114:117], v[236:239], v[160:163], v[114:117]
	v_mfma_f32_16x16x32_bf16 v[102:105], v[228:231], v[192:195], v[102:105]
	v_mfma_f32_16x16x32_bf16 v[98:101], v[236:239], v[192:195], v[98:101]
	v_mfma_f32_16x16x32_bf16 v[86:89], v[228:231], v[200:203], v[86:89]
	v_mfma_f32_16x16x32_bf16 v[82:85], v[236:239], v[200:203], v[82:85]
	s_waitcnt lgkmcnt(0)
	v_mfma_f32_16x16x32_bf16 v[70:73], v[228:231], v[220:223], v[70:73]
	v_mfma_f32_16x16x32_bf16 v[66:69], v[236:239], v[220:223], v[66:69]
	v_mfma_f32_16x16x32_bf16 v[118:121], v[232:235], v[188:191], v[118:121]
	v_mfma_f32_16x16x32_bf16 v[114:117], v[240:243], v[188:191], v[114:117]
	v_mfma_f32_16x16x32_bf16 v[102:105], v[232:235], v[196:199], v[102:105]
	v_mfma_f32_16x16x32_bf16 v[98:101], v[240:243], v[196:199], v[98:101]
	v_mfma_f32_16x16x32_bf16 v[86:89], v[232:235], v[216:219], v[86:89]
	v_mfma_f32_16x16x32_bf16 v[82:85], v[240:243], v[216:219], v[82:85]
	v_mfma_f32_16x16x32_bf16 v[70:73], v[232:235], v[224:227], v[70:73]
	v_mfma_f32_16x16x32_bf16 v[66:69], v[240:243], v[224:227], v[66:69]
	s_mov_b32 m0, s58
	v_lshl_add_u64 v[244:245], s[92:93], 0, v[134:135]
	s_barrier
	ds_read_b128 v[160:163], v147 offset:16384
	ds_read_b128 v[188:191], v147 offset:17408
	ds_read_b128 v[192:195], v147 offset:18432
	ds_read_b128 v[196:199], v147 offset:19456
	ds_read_b128 v[200:203], v147 offset:20480
	ds_read_b128 v[216:219], v147 offset:21504
	ds_read_b128 v[220:223], v147 offset:22528
	ds_read_b128 v[224:227], v147 offset:23552
	global_load_lds_dwordx4 v[244:245], off
	v_lshl_add_u64 v[246:247], s[92:93], 0, v[132:133]
	s_mov_b32 m0, s69
	s_nop 0
	global_load_lds_dwordx4 v[246:247], off
	s_barrier
	s_waitcnt lgkmcnt(7)
	v_mfma_f32_16x16x32_bf16 v[62:65], v[140:143], v[160:163], v[62:65]
	v_mfma_f32_16x16x32_bf16 v[58:61], v[152:155], v[160:163], v[58:61]
	s_waitcnt lgkmcnt(3)
	v_mfma_f32_16x16x32_bf16 v[46:49], v[140:143], v[192:195], v[46:49]
	v_mfma_f32_16x16x32_bf16 v[42:45], v[152:155], v[192:195], v[42:45]
	v_mfma_f32_16x16x32_bf16 v[30:33], v[140:143], v[200:203], v[30:33]
	v_mfma_f32_16x16x32_bf16 v[26:29], v[152:155], v[200:203], v[26:29]
	s_waitcnt lgkmcnt(0)
	v_mfma_f32_16x16x32_bf16 v[14:17], v[140:143], v[220:223], v[14:17]
	v_mfma_f32_16x16x32_bf16 v[10:13], v[152:155], v[220:223], v[10:13]
	v_mfma_f32_16x16x32_bf16 v[62:65], v[148:151], v[188:191], v[62:65]
	v_mfma_f32_16x16x32_bf16 v[58:61], v[156:159], v[188:191], v[58:61]
	v_mfma_f32_16x16x32_bf16 v[46:49], v[148:151], v[196:199], v[46:49]
	v_mfma_f32_16x16x32_bf16 v[42:45], v[156:159], v[196:199], v[42:45]
	v_mfma_f32_16x16x32_bf16 v[30:33], v[148:151], v[216:219], v[30:33]
	v_mfma_f32_16x16x32_bf16 v[26:29], v[156:159], v[216:219], v[26:29]
	v_mfma_f32_16x16x32_bf16 v[14:17], v[148:151], v[224:227], v[14:17]
	v_mfma_f32_16x16x32_bf16 v[10:13], v[156:159], v[224:227], v[10:13]
	s_barrier
	s_add_u32 s26, s82, 0x20000
	s_addc_u32 s27, s83, 0
	s_add_i32 s2, s17, s3
	v_lshl_add_u64 v[140:141], s[26:27], 0, v[0:1]
	s_mov_b32 m0, s2
	s_nop 0
	global_load_lds_dwordx4 v[140:141], off
	v_lshl_add_u64 v[140:141], s[26:27], 0, v[130:131]
	s_add_i32 m0, s2, 0x2000
	s_nop 0
	global_load_lds_dwordx4 v[140:141], off
	s_waitcnt vmcnt(6)
	s_barrier
	v_mfma_f32_16x16x32_bf16 v[54:57], v[228:231], v[160:163], v[54:57]
	v_mfma_f32_16x16x32_bf16 v[50:53], v[236:239], v[160:163], v[50:53]
	v_mfma_f32_16x16x32_bf16 v[38:41], v[228:231], v[192:195], v[38:41]
	v_mfma_f32_16x16x32_bf16 v[34:37], v[236:239], v[192:195], v[34:37]
	v_mfma_f32_16x16x32_bf16 v[22:25], v[228:231], v[200:203], v[22:25]
	v_mfma_f32_16x16x32_bf16 v[18:21], v[236:239], v[200:203], v[18:21]
	v_mfma_f32_16x16x32_bf16 v[6:9], v[228:231], v[220:223], v[6:9]
	v_mfma_f32_16x16x32_bf16 v[2:5], v[236:239], v[220:223], v[2:5]
	v_mfma_f32_16x16x32_bf16 v[54:57], v[232:235], v[188:191], v[54:57]
	v_mfma_f32_16x16x32_bf16 v[50:53], v[240:243], v[188:191], v[50:53]
	v_mfma_f32_16x16x32_bf16 v[38:41], v[232:235], v[196:199], v[38:41]
	v_mfma_f32_16x16x32_bf16 v[34:37], v[240:243], v[196:199], v[34:37]
	v_mfma_f32_16x16x32_bf16 v[22:25], v[232:235], v[216:219], v[22:25]
	v_mfma_f32_16x16x32_bf16 v[18:21], v[240:243], v[216:219], v[18:21]
	v_mfma_f32_16x16x32_bf16 v[6:9], v[232:235], v[224:227], v[6:9]
	v_mfma_f32_16x16x32_bf16 v[2:5], v[240:243], v[224:227], v[2:5]
	s_add_i32 s2, 0, 0x18000
	v_add_u32_e32 v156, s2, v145
	s_barrier
	ds_read_b128 v[140:143], v156
	ds_read_b128 v[148:151], v156 offset:1024
	ds_read_b128 v[152:155], v156 offset:2048
	ds_read_b128 v[156:159], v156 offset:3072
	s_add_u32 s26, s92, 0xd0000
	s_addc_u32 s27, s93, 0
	s_mov_b32 m0, s70
	v_lshl_add_u64 v[228:229], s[26:27], 0, v[134:135]
	ds_read_b128 v[160:163], v147 offset:32768
	ds_read_b128 v[188:191], v147 offset:33792
	ds_read_b128 v[192:195], v147 offset:34816
	ds_read_b128 v[196:199], v147 offset:35840
	ds_read_b128 v[200:203], v147 offset:36864
	ds_read_b128 v[216:219], v147 offset:37888
	ds_read_b128 v[220:223], v147 offset:38912
	ds_read_b128 v[224:227], v147 offset:39936
	global_load_lds_dwordx4 v[228:229], off
	v_lshl_add_u64 v[228:229], s[26:27], 0, v[132:133]
	s_mov_b32 m0, s71
	s_nop 0
	global_load_lds_dwordx4 v[228:229], off
	s_waitcnt lgkmcnt(8)
	s_barrier
	s_waitcnt lgkmcnt(7)
	v_mfma_f32_16x16x32_bf16 v[126:129], v[140:143], v[160:163], v[126:129]
	v_mfma_f32_16x16x32_bf16 v[122:125], v[152:155], v[160:163], v[122:125]
	s_waitcnt lgkmcnt(3)
	v_mfma_f32_16x16x32_bf16 v[110:113], v[140:143], v[192:195], v[110:113]
	v_mfma_f32_16x16x32_bf16 v[106:109], v[152:155], v[192:195], v[106:109]
	v_mfma_f32_16x16x32_bf16 v[94:97], v[140:143], v[200:203], v[94:97]
	v_mfma_f32_16x16x32_bf16 v[90:93], v[152:155], v[200:203], v[90:93]
	s_waitcnt lgkmcnt(0)
	v_mfma_f32_16x16x32_bf16 v[78:81], v[140:143], v[220:223], v[78:81]
	v_mfma_f32_16x16x32_bf16 v[74:77], v[152:155], v[220:223], v[74:77]
	v_mfma_f32_16x16x32_bf16 v[126:129], v[148:151], v[188:191], v[126:129]
	v_mfma_f32_16x16x32_bf16 v[122:125], v[156:159], v[188:191], v[122:125]
	v_mfma_f32_16x16x32_bf16 v[110:113], v[148:151], v[196:199], v[110:113]
	v_mfma_f32_16x16x32_bf16 v[106:109], v[156:159], v[196:199], v[106:109]
	v_mfma_f32_16x16x32_bf16 v[94:97], v[148:151], v[216:219], v[94:97]
	v_mfma_f32_16x16x32_bf16 v[90:93], v[156:159], v[216:219], v[90:93]
	v_mfma_f32_16x16x32_bf16 v[78:81], v[148:151], v[224:227], v[78:81]
	v_mfma_f32_16x16x32_bf16 v[74:77], v[156:159], v[224:227], v[74:77]
	s_barrier
	s_add_i32 s17, 0, 0x1c000
	s_add_i32 s2, s2, s3
	v_add_u32_e32 v206, s17, v145
	v_lshl_add_u64 v[164:165], v[164:165], 0, s[28:29]
	s_mov_b32 m0, s2
	ds_read_b128 v[228:231], v206
	ds_read_b128 v[232:235], v206 offset:1024
	ds_read_b128 v[236:239], v206 offset:2048
	ds_read_b128 v[240:243], v206 offset:3072
	global_load_lds_dwordx4 v[164:165], off
	v_lshl_add_u64 v[164:165], v[204:205], 0, s[28:29]
	s_add_i32 m0, s2, 0x2000
	s_nop 0
	global_load_lds_dwordx4 v[164:165], off
	s_barrier
	s_waitcnt lgkmcnt(1)
	v_mfma_f32_16x16x32_bf16 v[118:121], v[228:231], v[160:163], v[118:121]
	v_mfma_f32_16x16x32_bf16 v[114:117], v[236:239], v[160:163], v[114:117]
	v_mfma_f32_16x16x32_bf16 v[102:105], v[228:231], v[192:195], v[102:105]
	v_mfma_f32_16x16x32_bf16 v[98:101], v[236:239], v[192:195], v[98:101]
	v_mfma_f32_16x16x32_bf16 v[86:89], v[228:231], v[200:203], v[86:89]
	v_mfma_f32_16x16x32_bf16 v[82:85], v[236:239], v[200:203], v[82:85]
	s_waitcnt lgkmcnt(0)
	v_mfma_f32_16x16x32_bf16 v[70:73], v[228:231], v[220:223], v[70:73]
	v_mfma_f32_16x16x32_bf16 v[66:69], v[236:239], v[220:223], v[66:69]
	v_mfma_f32_16x16x32_bf16 v[118:121], v[232:235], v[188:191], v[118:121]
	v_mfma_f32_16x16x32_bf16 v[114:117], v[240:243], v[188:191], v[114:117]
	v_mfma_f32_16x16x32_bf16 v[102:105], v[232:235], v[196:199], v[102:105]
	v_mfma_f32_16x16x32_bf16 v[98:101], v[240:243], v[196:199], v[98:101]
	v_mfma_f32_16x16x32_bf16 v[86:89], v[232:235], v[216:219], v[86:89]
	v_mfma_f32_16x16x32_bf16 v[82:85], v[240:243], v[216:219], v[82:85]
	v_mfma_f32_16x16x32_bf16 v[70:73], v[232:235], v[224:227], v[70:73]
	v_mfma_f32_16x16x32_bf16 v[66:69], v[240:243], v[224:227], v[66:69]
	s_mov_b32 m0, s72
	v_lshl_add_u64 v[164:165], v[244:245], 0, s[28:29]
	s_barrier
	ds_read_b128 v[160:163], v147 offset:49152
	ds_read_b128 v[188:191], v147 offset:50176
	ds_read_b128 v[192:195], v147 offset:51200
	ds_read_b128 v[196:199], v147 offset:52224
	ds_read_b128 v[200:203], v147 offset:53248
	ds_read_b128 v[216:219], v147 offset:54272
	ds_read_b128 v[220:223], v147 offset:55296
	ds_read_b128 v[224:227], v147 offset:56320
	global_load_lds_dwordx4 v[164:165], off
	v_lshl_add_u64 v[164:165], v[246:247], 0, s[28:29]
	s_mov_b32 m0, s73
	s_nop 0
	global_load_lds_dwordx4 v[164:165], off
	s_barrier
	s_waitcnt lgkmcnt(7)
	v_mfma_f32_16x16x32_bf16 v[62:65], v[140:143], v[160:163], v[62:65]
	v_mfma_f32_16x16x32_bf16 v[58:61], v[152:155], v[160:163], v[58:61]
	s_waitcnt lgkmcnt(3)
	v_mfma_f32_16x16x32_bf16 v[46:49], v[140:143], v[192:195], v[46:49]
	v_mfma_f32_16x16x32_bf16 v[42:45], v[152:155], v[192:195], v[42:45]
	v_mfma_f32_16x16x32_bf16 v[30:33], v[140:143], v[200:203], v[30:33]
	v_mfma_f32_16x16x32_bf16 v[26:29], v[152:155], v[200:203], v[26:29]
	s_waitcnt lgkmcnt(0)
	v_mfma_f32_16x16x32_bf16 v[14:17], v[140:143], v[220:223], v[14:17]
	v_mfma_f32_16x16x32_bf16 v[10:13], v[152:155], v[220:223], v[10:13]
	v_mfma_f32_16x16x32_bf16 v[62:65], v[148:151], v[188:191], v[62:65]
	v_mfma_f32_16x16x32_bf16 v[58:61], v[156:159], v[188:191], v[58:61]
	v_mfma_f32_16x16x32_bf16 v[46:49], v[148:151], v[196:199], v[46:49]
	v_mfma_f32_16x16x32_bf16 v[42:45], v[156:159], v[196:199], v[42:45]
	v_mfma_f32_16x16x32_bf16 v[30:33], v[148:151], v[216:219], v[30:33]
	v_mfma_f32_16x16x32_bf16 v[26:29], v[156:159], v[216:219], v[26:29]
	v_mfma_f32_16x16x32_bf16 v[14:17], v[148:151], v[224:227], v[14:17]
	v_mfma_f32_16x16x32_bf16 v[10:13], v[156:159], v[224:227], v[10:13]
	s_barrier
	s_add_u32 s26, s82, 0x20080
	s_addc_u32 s27, s83, 0
	s_add_i32 s2, s17, s3
	v_lshl_add_u64 v[140:141], s[26:27], 0, v[0:1]
	s_mov_b32 m0, s2
	s_nop 0
	global_load_lds_dwordx4 v[140:141], off
	v_lshl_add_u64 v[140:141], s[26:27], 0, v[130:131]
	s_add_i32 m0, s2, 0x2000
	s_nop 0
	global_load_lds_dwordx4 v[140:141], off
	s_waitcnt vmcnt(6)
	s_barrier
	v_mfma_f32_16x16x32_bf16 v[54:57], v[228:231], v[160:163], v[54:57]
	v_mfma_f32_16x16x32_bf16 v[50:53], v[236:239], v[160:163], v[50:53]
	v_mfma_f32_16x16x32_bf16 v[38:41], v[228:231], v[192:195], v[38:41]
	v_mfma_f32_16x16x32_bf16 v[34:37], v[236:239], v[192:195], v[34:37]
	v_mfma_f32_16x16x32_bf16 v[22:25], v[228:231], v[200:203], v[22:25]
	v_mfma_f32_16x16x32_bf16 v[18:21], v[236:239], v[200:203], v[18:21]
	v_mfma_f32_16x16x32_bf16 v[6:9], v[228:231], v[220:223], v[6:9]
	v_mfma_f32_16x16x32_bf16 v[2:5], v[236:239], v[220:223], v[2:5]
	v_mfma_f32_16x16x32_bf16 v[54:57], v[232:235], v[188:191], v[54:57]
	v_mfma_f32_16x16x32_bf16 v[50:53], v[240:243], v[188:191], v[50:53]
	v_mfma_f32_16x16x32_bf16 v[38:41], v[232:235], v[196:199], v[38:41]
	v_mfma_f32_16x16x32_bf16 v[34:37], v[240:243], v[196:199], v[34:37]
	v_mfma_f32_16x16x32_bf16 v[22:25], v[232:235], v[216:219], v[22:25]
	v_mfma_f32_16x16x32_bf16 v[18:21], v[240:243], v[216:219], v[18:21]
	v_mfma_f32_16x16x32_bf16 v[6:9], v[232:235], v[224:227], v[6:9]
	v_mfma_f32_16x16x32_bf16 v[2:5], v[240:243], v[224:227], v[2:5]
	s_add_i32 s44, s44, 2
	s_add_u32 s46, s46, 0x100
	s_addc_u32 s47, s47, 0
	s_cmp_gt_u32 s44, 5
	s_mov_b64 s[80:81], s[10:11]
	s_barrier
	s_cbranch_scc0 .LBB0_482
	v_lshl_add_u32 v142, s63, 8, v144
	v_ashrrev_i32_e32 v143, 31, v142
	v_lshl_add_u64 v[140:141], v[142:143], 2, s[38:39]
	global_load_dword v216, v[140:141], off
	global_load_dword v218, v[140:141], off offset:64
	global_load_dword v220, v[140:141], off offset:128
	global_load_dword v222, v[140:141], off offset:192
	global_load_dword v224, v[140:141], off offset:512
	global_load_dword v226, v[140:141], off offset:576
	global_load_dword v228, v[140:141], off offset:640
	global_load_dword v230, v[140:141], off offset:704
	v_lshl_or_b32 v148, s62, 8, v146
	v_ashrrev_i32_e32 v149, 31, v148
	s_mov_b32 s2, 0x80000
	s_mov_b64 s[4:5], 0x80000
	s_mov_b32 s62, s74
	s_mov_b32 s63, s41
	s_mov_b64 s[82:83], s[78:79]
	s_mov_b64 s[80:81], s[76:77]
	v_readlane_b32 s93, v251, 60
	s_waitcnt vmcnt(7)
	v_mov_b32_e32 v150, v216
	v_pk_mul_f32 v[128:129], v[128:129], v[150:151] op_sel_hi:[1,0]
	v_pk_mul_f32 v[126:127], v[126:127], v[150:151] op_sel_hi:[1,0]
	v_pk_mul_f32 v[122:123], v[122:123], v[150:151] op_sel_hi:[1,0]
	v_pk_mul_f32 v[124:125], v[124:125], v[150:151] op_sel_hi:[1,0]
	v_cvt_pk_bf16_f32 v126, v126, v127
	v_cvt_pk_bf16_f32 v127, v128, v129
	v_cvt_pk_bf16_f32 v128, v122, v123
	v_lshlrev_b64 v[122:123], 12, v[142:143]
	v_cvt_pk_bf16_f32 v129, v124, v125
	v_lshl_add_u64 v[122:123], s[56:57], 0, v[122:123]
	v_lshlrev_b64 v[124:125], 1, v[148:149]
	v_lshl_add_u64 v[122:123], v[122:123], 0, v[124:125]
	global_store_dwordx4 v[122:123], v[126:129], off
	v_pk_mul_f32 v[120:121], v[120:121], v[150:151] op_sel_hi:[1,0]
	v_pk_mul_f32 v[118:119], v[118:119], v[150:151] op_sel_hi:[1,0]
	v_pk_mul_f32 v[126:127], v[116:117], v[150:151] op_sel_hi:[1,0]
	v_pk_mul_f32 v[116:117], v[114:115], v[150:151] op_sel_hi:[1,0]
	v_cvt_pk_bf16_f32 v114, v118, v119
	v_cvt_pk_bf16_f32 v115, v120, v121
	v_cvt_pk_bf16_f32 v116, v116, v117
	v_cvt_pk_bf16_f32 v117, v126, v127
	global_store_dwordx4 v[122:123], v[114:117], off offset:256
	s_nop 1
	v_or_b32_e32 v114, 16, v142
	v_ashrrev_i32_e32 v115, 31, v114
	v_lshl_add_u64 v[116:117], v[114:115], 2, s[38:39]
	s_waitcnt vmcnt(8)
	v_mov_b32_e32 v116, v218
	v_pk_mul_f32 v[110:111], v[110:111], v[116:117] op_sel_hi:[1,0]
	v_pk_mul_f32 v[118:119], v[108:109], v[116:117] op_sel_hi:[1,0]
	v_pk_mul_f32 v[108:109], v[106:107], v[116:117] op_sel_hi:[1,0]
	v_cvt_pk_bf16_f32 v106, v110, v111
	v_lshlrev_b64 v[110:111], 12, v[114:115]
	v_pk_mul_f32 v[112:113], v[112:113], v[116:117] op_sel_hi:[1,0]
	v_lshl_add_u64 v[110:111], s[56:57], 0, v[110:111]
	v_cvt_pk_bf16_f32 v107, v112, v113
	v_cvt_pk_bf16_f32 v108, v108, v109
	v_cvt_pk_bf16_f32 v109, v118, v119
	v_lshl_add_u64 v[110:111], v[110:111], 0, v[124:125]
	global_store_dwordx4 v[110:111], v[106:109], off
	v_pk_mul_f32 v[104:105], v[104:105], v[116:117] op_sel_hi:[1,0]
	v_pk_mul_f32 v[102:103], v[102:103], v[116:117] op_sel_hi:[1,0]
	v_pk_mul_f32 v[106:107], v[100:101], v[116:117] op_sel_hi:[1,0]
	v_pk_mul_f32 v[100:101], v[98:99], v[116:117] op_sel_hi:[1,0]
	v_cvt_pk_bf16_f32 v98, v102, v103
	v_cvt_pk_bf16_f32 v99, v104, v105
	v_cvt_pk_bf16_f32 v100, v100, v101
	v_cvt_pk_bf16_f32 v101, v106, v107
	global_store_dwordx4 v[110:111], v[98:101], off offset:256
	s_nop 1
	v_or_b32_e32 v98, 32, v142
	v_ashrrev_i32_e32 v99, 31, v98
	v_lshl_add_u64 v[100:101], v[98:99], 2, s[38:39]
	s_waitcnt vmcnt(9)
	v_mov_b32_e32 v100, v220
	v_pk_mul_f32 v[94:95], v[94:95], v[100:101] op_sel_hi:[1,0]
	v_pk_mul_f32 v[102:103], v[92:93], v[100:101] op_sel_hi:[1,0]
	v_pk_mul_f32 v[92:93], v[90:91], v[100:101] op_sel_hi:[1,0]
	v_cvt_pk_bf16_f32 v90, v94, v95
	v_lshlrev_b64 v[94:95], 12, v[98:99]
	v_pk_mul_f32 v[96:97], v[96:97], v[100:101] op_sel_hi:[1,0]
	v_lshl_add_u64 v[94:95], s[56:57], 0, v[94:95]
	v_cvt_pk_bf16_f32 v91, v96, v97
	v_cvt_pk_bf16_f32 v92, v92, v93
	v_cvt_pk_bf16_f32 v93, v102, v103
	v_lshl_add_u64 v[94:95], v[94:95], 0, v[124:125]
	global_store_dwordx4 v[94:95], v[90:93], off
	v_pk_mul_f32 v[88:89], v[88:89], v[100:101] op_sel_hi:[1,0]
	v_pk_mul_f32 v[86:87], v[86:87], v[100:101] op_sel_hi:[1,0]
	v_pk_mul_f32 v[90:91], v[84:85], v[100:101] op_sel_hi:[1,0]
	v_pk_mul_f32 v[84:85], v[82:83], v[100:101] op_sel_hi:[1,0]
	v_cvt_pk_bf16_f32 v82, v86, v87
	v_cvt_pk_bf16_f32 v83, v88, v89
	v_cvt_pk_bf16_f32 v84, v84, v85
	v_cvt_pk_bf16_f32 v85, v90, v91
	global_store_dwordx4 v[94:95], v[82:85], off offset:256
	s_nop 1
	v_or_b32_e32 v82, 48, v142
	v_ashrrev_i32_e32 v83, 31, v82
	v_lshl_add_u64 v[84:85], v[82:83], 2, s[38:39]
	s_waitcnt vmcnt(10)
	v_mov_b32_e32 v84, v222
	v_pk_mul_f32 v[78:79], v[78:79], v[84:85] op_sel_hi:[1,0]
	v_pk_mul_f32 v[86:87], v[76:77], v[84:85] op_sel_hi:[1,0]
	v_pk_mul_f32 v[76:77], v[74:75], v[84:85] op_sel_hi:[1,0]
	v_cvt_pk_bf16_f32 v74, v78, v79
	v_lshlrev_b64 v[78:79], 12, v[82:83]
	v_pk_mul_f32 v[80:81], v[80:81], v[84:85] op_sel_hi:[1,0]
	v_lshl_add_u64 v[78:79], s[56:57], 0, v[78:79]
	v_cvt_pk_bf16_f32 v75, v80, v81
	v_cvt_pk_bf16_f32 v76, v76, v77
	v_cvt_pk_bf16_f32 v77, v86, v87
	v_lshl_add_u64 v[78:79], v[78:79], 0, v[124:125]
	global_store_dwordx4 v[78:79], v[74:77], off
	v_pk_mul_f32 v[72:73], v[72:73], v[84:85] op_sel_hi:[1,0]
	v_pk_mul_f32 v[70:71], v[70:71], v[84:85] op_sel_hi:[1,0]
	v_pk_mul_f32 v[74:75], v[68:69], v[84:85] op_sel_hi:[1,0]
	v_pk_mul_f32 v[68:69], v[66:67], v[84:85] op_sel_hi:[1,0]
	v_cvt_pk_bf16_f32 v66, v70, v71
	v_cvt_pk_bf16_f32 v67, v72, v73
	v_cvt_pk_bf16_f32 v68, v68, v69
	v_cvt_pk_bf16_f32 v69, v74, v75
	global_store_dwordx4 v[78:79], v[66:69], off offset:256
	s_waitcnt vmcnt(11)
	v_mov_b32_e32 v66, v224
	v_pk_mul_f32 v[64:65], v[64:65], v[66:67] op_sel_hi:[1,0]
	v_pk_mul_f32 v[62:63], v[62:63], v[66:67] op_sel_hi:[1,0]
	v_pk_mul_f32 v[68:69], v[60:61], v[66:67] op_sel_hi:[1,0]
	v_pk_mul_f32 v[60:61], v[58:59], v[66:67] op_sel_hi:[1,0]
	v_cvt_pk_bf16_f32 v59, v64, v65
	v_add_co_u32_e32 v64, vcc, s2, v122
	v_cvt_pk_bf16_f32 v58, v62, v63
	v_cvt_pk_bf16_f32 v60, v60, v61
	v_cvt_pk_bf16_f32 v61, v68, v69
	v_addc_co_u32_e32 v65, vcc, 0, v123, vcc
	global_store_dwordx4 v[64:65], v[58:61], off
	v_pk_mul_f32 v[56:57], v[56:57], v[66:67] op_sel_hi:[1,0]
	v_pk_mul_f32 v[54:55], v[54:55], v[66:67] op_sel_hi:[1,0]
	v_pk_mul_f32 v[58:59], v[52:53], v[66:67] op_sel_hi:[1,0]
	v_pk_mul_f32 v[52:53], v[50:51], v[66:67] op_sel_hi:[1,0]
	v_lshl_add_u64 v[62:63], v[122:123], 0, s[4:5]
	v_cvt_pk_bf16_f32 v50, v54, v55
	v_cvt_pk_bf16_f32 v51, v56, v57
	v_cvt_pk_bf16_f32 v52, v52, v53
	v_cvt_pk_bf16_f32 v53, v58, v59
	global_store_dwordx4 v[62:63], v[50:53], off offset:256
	s_mov_b32 s2, 0x90000
	s_mov_b64 s[4:5], 0x90000
	s_waitcnt vmcnt(12)
	v_mov_b32_e32 v50, v226
	v_pk_mul_f32 v[48:49], v[48:49], v[50:51] op_sel_hi:[1,0]
	v_pk_mul_f32 v[46:47], v[46:47], v[50:51] op_sel_hi:[1,0]
	v_pk_mul_f32 v[52:53], v[44:45], v[50:51] op_sel_hi:[1,0]
	v_pk_mul_f32 v[44:45], v[42:43], v[50:51] op_sel_hi:[1,0]
	v_cvt_pk_bf16_f32 v43, v48, v49
	v_add_co_u32_e32 v48, vcc, s2, v122
	v_cvt_pk_bf16_f32 v42, v46, v47
	v_cvt_pk_bf16_f32 v44, v44, v45
	v_cvt_pk_bf16_f32 v45, v52, v53
	v_addc_co_u32_e32 v49, vcc, 0, v123, vcc
	global_store_dwordx4 v[48:49], v[42:45], off
	v_pk_mul_f32 v[40:41], v[40:41], v[50:51] op_sel_hi:[1,0]
	v_pk_mul_f32 v[38:39], v[38:39], v[50:51] op_sel_hi:[1,0]
	v_pk_mul_f32 v[42:43], v[36:37], v[50:51] op_sel_hi:[1,0]
	v_pk_mul_f32 v[36:37], v[34:35], v[50:51] op_sel_hi:[1,0]
	v_lshl_add_u64 v[46:47], v[122:123], 0, s[4:5]
	v_cvt_pk_bf16_f32 v34, v38, v39
	v_cvt_pk_bf16_f32 v35, v40, v41
	v_cvt_pk_bf16_f32 v36, v36, v37
	v_cvt_pk_bf16_f32 v37, v42, v43
	global_store_dwordx4 v[46:47], v[34:37], off offset:256
	s_mov_b32 s2, 0xa0000
	s_mov_b64 s[4:5], 0xa0000
	s_waitcnt vmcnt(13)
	v_mov_b32_e32 v34, v228
	v_pk_mul_f32 v[32:33], v[32:33], v[34:35] op_sel_hi:[1,0]
	v_pk_mul_f32 v[30:31], v[30:31], v[34:35] op_sel_hi:[1,0]
	v_pk_mul_f32 v[36:37], v[28:29], v[34:35] op_sel_hi:[1,0]
	v_pk_mul_f32 v[28:29], v[26:27], v[34:35] op_sel_hi:[1,0]
	v_cvt_pk_bf16_f32 v27, v32, v33
	v_add_co_u32_e32 v32, vcc, s2, v122
	v_cvt_pk_bf16_f32 v26, v30, v31
	v_cvt_pk_bf16_f32 v28, v28, v29
	v_cvt_pk_bf16_f32 v29, v36, v37
	v_addc_co_u32_e32 v33, vcc, 0, v123, vcc
	global_store_dwordx4 v[32:33], v[26:29], off
	v_pk_mul_f32 v[24:25], v[24:25], v[34:35] op_sel_hi:[1,0]
	v_pk_mul_f32 v[22:23], v[22:23], v[34:35] op_sel_hi:[1,0]
	v_pk_mul_f32 v[26:27], v[20:21], v[34:35] op_sel_hi:[1,0]
	v_pk_mul_f32 v[20:21], v[18:19], v[34:35] op_sel_hi:[1,0]
	v_lshl_add_u64 v[30:31], v[122:123], 0, s[4:5]
	v_cvt_pk_bf16_f32 v18, v22, v23
	v_cvt_pk_bf16_f32 v19, v24, v25
	v_cvt_pk_bf16_f32 v20, v20, v21
	v_cvt_pk_bf16_f32 v21, v26, v27
	global_store_dwordx4 v[30:31], v[18:21], off offset:256
	s_mov_b32 s2, 0xb0000
	s_mov_b64 s[4:5], 0xb0000
	s_waitcnt vmcnt(14)
	v_mov_b32_e32 v18, v230
	v_pk_mul_f32 v[16:17], v[16:17], v[18:19] op_sel_hi:[1,0]
	v_pk_mul_f32 v[14:15], v[14:15], v[18:19] op_sel_hi:[1,0]
	v_pk_mul_f32 v[20:21], v[12:13], v[18:19] op_sel_hi:[1,0]
	v_pk_mul_f32 v[12:13], v[10:11], v[18:19] op_sel_hi:[1,0]
	v_cvt_pk_bf16_f32 v11, v16, v17
	v_add_co_u32_e32 v16, vcc, s2, v122
	v_cvt_pk_bf16_f32 v10, v14, v15
	v_cvt_pk_bf16_f32 v12, v12, v13
	v_cvt_pk_bf16_f32 v13, v20, v21
	v_addc_co_u32_e32 v17, vcc, 0, v123, vcc
	global_store_dwordx4 v[16:17], v[10:13], off
	v_pk_mul_f32 v[8:9], v[8:9], v[18:19] op_sel_hi:[1,0]
	v_pk_mul_f32 v[6:7], v[6:7], v[18:19] op_sel_hi:[1,0]
	v_pk_mul_f32 v[10:11], v[4:5], v[18:19] op_sel_hi:[1,0]
	v_pk_mul_f32 v[4:5], v[2:3], v[18:19] op_sel_hi:[1,0]
	v_lshl_add_u64 v[14:15], v[122:123], 0, s[4:5]
	v_cvt_pk_bf16_f32 v2, v6, v7
	v_cvt_pk_bf16_f32 v3, v8, v9
	v_cvt_pk_bf16_f32 v4, v4, v5
	v_cvt_pk_bf16_f32 v5, v10, v11
	s_and_b64 vcc, exec, s[6:7]
	global_store_dwordx4 v[14:15], v[2:5], off offset:256
	s_cbranch_vccz .LBB0_473
	v_readlane_b32 s4, v254, 12
	s_waitcnt vmcnt(0)
	v_readlane_b32 s5, v254, 13
	v_readlane_b32 s84, v251, 38
	v_readlane_b32 s18, v253, 0
	s_andn2_b64 vcc, exec, s[4:5]
	v_readlane_b32 s85, v251, 39
	v_readlane_b32 s86, v251, 40
	v_readlane_b32 s87, v251, 41
	v_readlane_b32 s14, v250, 63
	v_readlane_b32 s19, v253, 1
	s_cbranch_vccnz .LBB0_486
	s_barrier

.LBB0_500:
	s_add_u32 s2, s6, 0xfffe0080
	s_addc_u32 s17, s7, -1
	s_add_i32 s26, 0, 0x10000
	v_add_u32_e32 v156, s26, v145
	ds_read_b128 v[140:143], v156
	ds_read_b128 v[148:151], v156 offset:1024
	ds_read_b128 v[152:155], v156 offset:2048
	ds_read_b128 v[156:159], v156 offset:3072
	s_cmp_eq_u32 s44, 4
	s_cselect_b32 s81, s11, s17
	s_cselect_b32 s80, s24, s2
	s_cselect_b32 s79, s75, s46
	s_cselect_b32 s78, s74, s25
	v_lshl_add_u64 v[164:165], s[6:7], 0, v[136:137]
	s_add_i32 m0, s58, 0xc000
	ds_read_b128 v[160:163], v147
	ds_read_b128 v[188:191], v147 offset:1024
	ds_read_b128 v[192:195], v147 offset:2048
	ds_read_b128 v[196:199], v147 offset:3072
	ds_read_b128 v[200:203], v147 offset:4096
	ds_read_b128 v[216:219], v147 offset:5120
	ds_read_b128 v[220:223], v147 offset:6144
	ds_read_b128 v[224:227], v147 offset:7168
	global_load_lds_dwordx4 v[164:165], off
	v_lshl_add_u64 v[164:165], s[6:7], 0, v[138:139]
	s_add_i32 m0, s58, 0xe000
	s_nop 0
	global_load_lds_dwordx4 v[164:165], off
	s_waitcnt lgkmcnt(8)
	s_barrier
	s_waitcnt lgkmcnt(7)
	v_mfma_f32_16x16x32_bf16 v[126:129], v[140:143], v[160:163], v[126:129]
	v_mfma_f32_16x16x32_bf16 v[122:125], v[152:155], v[160:163], v[122:125]
	s_waitcnt lgkmcnt(3)
	v_mfma_f32_16x16x32_bf16 v[110:113], v[140:143], v[192:195], v[110:113]
	v_mfma_f32_16x16x32_bf16 v[106:109], v[152:155], v[192:195], v[106:109]
	v_mfma_f32_16x16x32_bf16 v[94:97], v[140:143], v[200:203], v[94:97]
	v_mfma_f32_16x16x32_bf16 v[90:93], v[152:155], v[200:203], v[90:93]
	s_waitcnt lgkmcnt(0)
	v_mfma_f32_16x16x32_bf16 v[78:81], v[140:143], v[220:223], v[78:81]
	v_mfma_f32_16x16x32_bf16 v[74:77], v[152:155], v[220:223], v[74:77]
	v_mfma_f32_16x16x32_bf16 v[126:129], v[148:151], v[188:191], v[126:129]
	v_mfma_f32_16x16x32_bf16 v[122:125], v[156:159], v[188:191], v[122:125]
	v_mfma_f32_16x16x32_bf16 v[110:113], v[148:151], v[196:199], v[110:113]
	v_mfma_f32_16x16x32_bf16 v[106:109], v[156:159], v[196:199], v[106:109]
	v_mfma_f32_16x16x32_bf16 v[94:97], v[148:151], v[216:219], v[94:97]
	v_mfma_f32_16x16x32_bf16 v[90:93], v[156:159], v[216:219], v[90:93]
	v_mfma_f32_16x16x32_bf16 v[78:81], v[148:151], v[224:227], v[78:81]
	v_mfma_f32_16x16x32_bf16 v[74:77], v[156:159], v[224:227], v[74:77]
	s_barrier
	s_add_i32 s2, 0, 0x14000
	v_add_u32_e32 v164, s2, v145
	s_add_i32 s17, s26, s3
	ds_read_b128 v[228:231], v164
	ds_read_b128 v[232:235], v164 offset:1024
	ds_read_b128 v[236:239], v164 offset:2048
	ds_read_b128 v[240:243], v164 offset:3072
	v_lshl_add_u64 v[164:165], s[78:79], 0, v[0:1]
	s_mov_b32 m0, s17
	v_lshl_add_u64 v[204:205], s[78:79], 0, v[130:131]
	global_load_lds_dwordx4 v[164:165], off
	s_add_i32 m0, s17, 0x2000
	s_nop 0
	global_load_lds_dwordx4 v[204:205], off
	s_barrier
	s_waitcnt lgkmcnt(1)
	v_mfma_f32_16x16x32_bf16 v[118:121], v[228:231], v[160:163], v[118:121]
	v_mfma_f32_16x16x32_bf16 v[114:117], v[236:239], v[160:163], v[114:117]
	v_mfma_f32_16x16x32_bf16 v[102:105], v[228:231], v[192:195], v[102:105]
	v_mfma_f32_16x16x32_bf16 v[98:101], v[236:239], v[192:195], v[98:101]
	v_mfma_f32_16x16x32_bf16 v[86:89], v[228:231], v[200:203], v[86:89]
	v_mfma_f32_16x16x32_bf16 v[82:85], v[236:239], v[200:203], v[82:85]
	s_waitcnt lgkmcnt(0)
	v_mfma_f32_16x16x32_bf16 v[70:73], v[228:231], v[220:223], v[70:73]
	v_mfma_f32_16x16x32_bf16 v[66:69], v[236:239], v[220:223], v[66:69]
	v_mfma_f32_16x16x32_bf16 v[118:121], v[232:235], v[188:191], v[118:121]
	v_mfma_f32_16x16x32_bf16 v[114:117], v[240:243], v[188:191], v[114:117]
	v_mfma_f32_16x16x32_bf16 v[102:105], v[232:235], v[196:199], v[102:105]
	v_mfma_f32_16x16x32_bf16 v[98:101], v[240:243], v[196:199], v[98:101]
	v_mfma_f32_16x16x32_bf16 v[86:89], v[232:235], v[216:219], v[86:89]
	v_mfma_f32_16x16x32_bf16 v[82:85], v[240:243], v[216:219], v[82:85]
	v_mfma_f32_16x16x32_bf16 v[70:73], v[232:235], v[224:227], v[70:73]
	v_mfma_f32_16x16x32_bf16 v[66:69], v[240:243], v[224:227], v[66:69]
	s_mov_b32 m0, s58
	v_lshl_add_u64 v[244:245], s[80:81], 0, v[134:135]
	s_barrier
	ds_read_b128 v[160:163], v147 offset:16384
	ds_read_b128 v[188:191], v147 offset:17408
	ds_read_b128 v[192:195], v147 offset:18432
	ds_read_b128 v[196:199], v147 offset:19456
	ds_read_b128 v[200:203], v147 offset:20480
	ds_read_b128 v[216:219], v147 offset:21504
	ds_read_b128 v[220:223], v147 offset:22528
	ds_read_b128 v[224:227], v147 offset:23552
	global_load_lds_dwordx4 v[244:245], off
	v_lshl_add_u64 v[246:247], s[80:81], 0, v[132:133]
	s_mov_b32 m0, s69
	s_nop 0
	global_load_lds_dwordx4 v[246:247], off
	s_barrier
	s_waitcnt lgkmcnt(7)
	v_mfma_f32_16x16x32_bf16 v[62:65], v[140:143], v[160:163], v[62:65]
	v_mfma_f32_16x16x32_bf16 v[58:61], v[152:155], v[160:163], v[58:61]
	s_waitcnt lgkmcnt(3)
	v_mfma_f32_16x16x32_bf16 v[54:57], v[140:143], v[192:195], v[54:57]
	v_mfma_f32_16x16x32_bf16 v[46:49], v[152:155], v[192:195], v[46:49]
	v_mfma_f32_16x16x32_bf16 v[38:41], v[140:143], v[200:203], v[38:41]
	v_mfma_f32_16x16x32_bf16 v[30:33], v[152:155], v[200:203], v[30:33]
	s_waitcnt lgkmcnt(0)
	v_mfma_f32_16x16x32_bf16 v[22:25], v[140:143], v[220:223], v[22:25]
	v_mfma_f32_16x16x32_bf16 v[14:17], v[152:155], v[220:223], v[14:17]
	v_mfma_f32_16x16x32_bf16 v[62:65], v[148:151], v[188:191], v[62:65]
	v_mfma_f32_16x16x32_bf16 v[58:61], v[156:159], v[188:191], v[58:61]
	v_mfma_f32_16x16x32_bf16 v[54:57], v[148:151], v[196:199], v[54:57]
	v_mfma_f32_16x16x32_bf16 v[46:49], v[156:159], v[196:199], v[46:49]
	v_mfma_f32_16x16x32_bf16 v[38:41], v[148:151], v[216:219], v[38:41]
	v_mfma_f32_16x16x32_bf16 v[30:33], v[156:159], v[216:219], v[30:33]
	v_mfma_f32_16x16x32_bf16 v[22:25], v[148:151], v[224:227], v[22:25]
	v_mfma_f32_16x16x32_bf16 v[14:17], v[156:159], v[224:227], v[14:17]
	s_barrier
	s_add_u32 s26, s78, 0xd0000
	s_addc_u32 s27, s79, 0
	s_add_i32 s2, s2, s3
	v_lshl_add_u64 v[140:141], s[26:27], 0, v[0:1]
	s_mov_b32 m0, s2
	s_nop 0
	global_load_lds_dwordx4 v[140:141], off
	v_lshl_add_u64 v[140:141], s[26:27], 0, v[130:131]
	s_add_i32 m0, s2, 0x2000
	s_nop 0
	global_load_lds_dwordx4 v[140:141], off
	s_waitcnt vmcnt(6)
	s_barrier
	v_mfma_f32_16x16x32_bf16 v[50:53], v[228:231], v[160:163], v[50:53]
	v_mfma_f32_16x16x32_bf16 v[42:45], v[236:239], v[160:163], v[42:45]
	v_mfma_f32_16x16x32_bf16 v[34:37], v[228:231], v[192:195], v[34:37]
	v_mfma_f32_16x16x32_bf16 v[26:29], v[236:239], v[192:195], v[26:29]
	v_mfma_f32_16x16x32_bf16 v[18:21], v[228:231], v[200:203], v[18:21]
	v_mfma_f32_16x16x32_bf16 v[10:13], v[236:239], v[200:203], v[10:13]
	v_mfma_f32_16x16x32_bf16 v[6:9], v[228:231], v[220:223], v[6:9]
	v_mfma_f32_16x16x32_bf16 v[2:5], v[236:239], v[220:223], v[2:5]
	v_mfma_f32_16x16x32_bf16 v[50:53], v[232:235], v[188:191], v[50:53]
	v_mfma_f32_16x16x32_bf16 v[42:45], v[240:243], v[188:191], v[42:45]
	v_mfma_f32_16x16x32_bf16 v[34:37], v[232:235], v[196:199], v[34:37]
	v_mfma_f32_16x16x32_bf16 v[26:29], v[240:243], v[196:199], v[26:29]
	v_mfma_f32_16x16x32_bf16 v[18:21], v[232:235], v[216:219], v[18:21]
	v_mfma_f32_16x16x32_bf16 v[10:13], v[240:243], v[216:219], v[10:13]
	v_mfma_f32_16x16x32_bf16 v[6:9], v[232:235], v[224:227], v[6:9]
	v_mfma_f32_16x16x32_bf16 v[2:5], v[240:243], v[224:227], v[2:5]
	s_add_i32 s2, 0, 0x18000
	v_add_u32_e32 v156, s2, v145
	s_barrier
	ds_read_b128 v[140:143], v156
	ds_read_b128 v[148:151], v156 offset:1024
	ds_read_b128 v[152:155], v156 offset:2048
	ds_read_b128 v[156:159], v156 offset:3072
	s_add_u32 s26, s80, 0x20000
	s_addc_u32 s27, s81, 0
	s_mov_b32 m0, s70
	v_lshl_add_u64 v[228:229], s[26:27], 0, v[134:135]
	ds_read_b128 v[160:163], v147 offset:32768
	ds_read_b128 v[188:191], v147 offset:33792
	ds_read_b128 v[192:195], v147 offset:34816
	ds_read_b128 v[196:199], v147 offset:35840
	ds_read_b128 v[200:203], v147 offset:36864
	ds_read_b128 v[216:219], v147 offset:37888
	ds_read_b128 v[220:223], v147 offset:38912
	ds_read_b128 v[224:227], v147 offset:39936
	global_load_lds_dwordx4 v[228:229], off
	v_lshl_add_u64 v[228:229], s[26:27], 0, v[132:133]
	s_mov_b32 m0, s71
	s_nop 0
	global_load_lds_dwordx4 v[228:229], off
	s_waitcnt lgkmcnt(8)
	s_barrier
	s_waitcnt lgkmcnt(7)
	v_mfma_f32_16x16x32_bf16 v[126:129], v[140:143], v[160:163], v[126:129]
	v_mfma_f32_16x16x32_bf16 v[122:125], v[152:155], v[160:163], v[122:125]
	s_waitcnt lgkmcnt(3)
	v_mfma_f32_16x16x32_bf16 v[110:113], v[140:143], v[192:195], v[110:113]
	v_mfma_f32_16x16x32_bf16 v[106:109], v[152:155], v[192:195], v[106:109]
	v_mfma_f32_16x16x32_bf16 v[94:97], v[140:143], v[200:203], v[94:97]
	v_mfma_f32_16x16x32_bf16 v[90:93], v[152:155], v[200:203], v[90:93]
	s_waitcnt lgkmcnt(0)
	v_mfma_f32_16x16x32_bf16 v[78:81], v[140:143], v[220:223], v[78:81]
	v_mfma_f32_16x16x32_bf16 v[74:77], v[152:155], v[220:223], v[74:77]
	v_mfma_f32_16x16x32_bf16 v[126:129], v[148:151], v[188:191], v[126:129]
	v_mfma_f32_16x16x32_bf16 v[122:125], v[156:159], v[188:191], v[122:125]
	v_mfma_f32_16x16x32_bf16 v[110:113], v[148:151], v[196:199], v[110:113]
	v_mfma_f32_16x16x32_bf16 v[106:109], v[156:159], v[196:199], v[106:109]
	v_mfma_f32_16x16x32_bf16 v[94:97], v[148:151], v[216:219], v[94:97]
	v_mfma_f32_16x16x32_bf16 v[90:93], v[156:159], v[216:219], v[90:93]
	v_mfma_f32_16x16x32_bf16 v[78:81], v[148:151], v[224:227], v[78:81]
	v_mfma_f32_16x16x32_bf16 v[74:77], v[156:159], v[224:227], v[74:77]
	s_barrier
	s_add_i32 s17, 0, 0x1c000
	s_add_i32 s2, s2, s3
	v_add_u32_e32 v206, s17, v145
	v_lshl_add_u64 v[164:165], v[164:165], 0, s[28:29]
	s_mov_b32 m0, s2
	ds_read_b128 v[228:231], v206
	ds_read_b128 v[232:235], v206 offset:1024
	ds_read_b128 v[236:239], v206 offset:2048
	ds_read_b128 v[240:243], v206 offset:3072
	global_load_lds_dwordx4 v[164:165], off
	v_lshl_add_u64 v[164:165], v[204:205], 0, s[28:29]
	s_add_i32 m0, s2, 0x2000
	s_nop 0
	global_load_lds_dwordx4 v[164:165], off
	s_barrier
	s_waitcnt lgkmcnt(1)
	v_mfma_f32_16x16x32_bf16 v[118:121], v[228:231], v[160:163], v[118:121]
	v_mfma_f32_16x16x32_bf16 v[114:117], v[236:239], v[160:163], v[114:117]
	v_mfma_f32_16x16x32_bf16 v[102:105], v[228:231], v[192:195], v[102:105]
	v_mfma_f32_16x16x32_bf16 v[98:101], v[236:239], v[192:195], v[98:101]
	v_mfma_f32_16x16x32_bf16 v[86:89], v[228:231], v[200:203], v[86:89]
	v_mfma_f32_16x16x32_bf16 v[82:85], v[236:239], v[200:203], v[82:85]
	s_waitcnt lgkmcnt(0)
	v_mfma_f32_16x16x32_bf16 v[70:73], v[228:231], v[220:223], v[70:73]
	v_mfma_f32_16x16x32_bf16 v[66:69], v[236:239], v[220:223], v[66:69]
	v_mfma_f32_16x16x32_bf16 v[118:121], v[232:235], v[188:191], v[118:121]
	v_mfma_f32_16x16x32_bf16 v[114:117], v[240:243], v[188:191], v[114:117]
	v_mfma_f32_16x16x32_bf16 v[102:105], v[232:235], v[196:199], v[102:105]
	v_mfma_f32_16x16x32_bf16 v[98:101], v[240:243], v[196:199], v[98:101]
	v_mfma_f32_16x16x32_bf16 v[86:89], v[232:235], v[216:219], v[86:89]
	v_mfma_f32_16x16x32_bf16 v[82:85], v[240:243], v[216:219], v[82:85]
	v_mfma_f32_16x16x32_bf16 v[70:73], v[232:235], v[224:227], v[70:73]
	v_mfma_f32_16x16x32_bf16 v[66:69], v[240:243], v[224:227], v[66:69]
	s_mov_b32 m0, s72
	v_lshl_add_u64 v[164:165], v[244:245], 0, s[28:29]
	s_barrier
	ds_read_b128 v[160:163], v147 offset:49152
	ds_read_b128 v[188:191], v147 offset:50176
	ds_read_b128 v[192:195], v147 offset:51200
	ds_read_b128 v[196:199], v147 offset:52224
	ds_read_b128 v[200:203], v147 offset:53248
	ds_read_b128 v[216:219], v147 offset:54272
	ds_read_b128 v[220:223], v147 offset:55296
	ds_read_b128 v[224:227], v147 offset:56320
	global_load_lds_dwordx4 v[164:165], off
	v_lshl_add_u64 v[164:165], v[246:247], 0, s[28:29]
	s_mov_b32 m0, s73
	s_nop 0
	global_load_lds_dwordx4 v[164:165], off
	s_barrier
	s_waitcnt lgkmcnt(7)
	v_mfma_f32_16x16x32_bf16 v[62:65], v[140:143], v[160:163], v[62:65]
	v_mfma_f32_16x16x32_bf16 v[58:61], v[152:155], v[160:163], v[58:61]
	s_waitcnt lgkmcnt(3)
	v_mfma_f32_16x16x32_bf16 v[54:57], v[140:143], v[192:195], v[54:57]
	v_mfma_f32_16x16x32_bf16 v[46:49], v[152:155], v[192:195], v[46:49]
	v_mfma_f32_16x16x32_bf16 v[38:41], v[140:143], v[200:203], v[38:41]
	v_mfma_f32_16x16x32_bf16 v[30:33], v[152:155], v[200:203], v[30:33]
	s_waitcnt lgkmcnt(0)
	v_mfma_f32_16x16x32_bf16 v[22:25], v[140:143], v[220:223], v[22:25]
	v_mfma_f32_16x16x32_bf16 v[14:17], v[152:155], v[220:223], v[14:17]
	v_mfma_f32_16x16x32_bf16 v[62:65], v[148:151], v[188:191], v[62:65]
	v_mfma_f32_16x16x32_bf16 v[58:61], v[156:159], v[188:191], v[58:61]
	v_mfma_f32_16x16x32_bf16 v[54:57], v[148:151], v[196:199], v[54:57]
	v_mfma_f32_16x16x32_bf16 v[46:49], v[156:159], v[196:199], v[46:49]
	v_mfma_f32_16x16x32_bf16 v[38:41], v[148:151], v[216:219], v[38:41]
	v_mfma_f32_16x16x32_bf16 v[30:33], v[156:159], v[216:219], v[30:33]
	v_mfma_f32_16x16x32_bf16 v[22:25], v[148:151], v[224:227], v[22:25]
	v_mfma_f32_16x16x32_bf16 v[14:17], v[156:159], v[224:227], v[14:17]
	s_barrier
	s_add_u32 s26, s78, 0xd0080
	s_addc_u32 s27, s79, 0
	s_add_i32 s2, s17, s3
	v_lshl_add_u64 v[140:141], s[26:27], 0, v[0:1]
	s_mov_b32 m0, s2
	s_nop 0
	global_load_lds_dwordx4 v[140:141], off
	v_lshl_add_u64 v[140:141], s[26:27], 0, v[130:131]
	s_add_i32 m0, s2, 0x2000
	s_nop 0
	global_load_lds_dwordx4 v[140:141], off
	s_waitcnt vmcnt(6)
	s_barrier
	v_mfma_f32_16x16x32_bf16 v[50:53], v[228:231], v[160:163], v[50:53]
	v_mfma_f32_16x16x32_bf16 v[42:45], v[236:239], v[160:163], v[42:45]
	v_mfma_f32_16x16x32_bf16 v[34:37], v[228:231], v[192:195], v[34:37]
	v_mfma_f32_16x16x32_bf16 v[26:29], v[236:239], v[192:195], v[26:29]
	v_mfma_f32_16x16x32_bf16 v[18:21], v[228:231], v[200:203], v[18:21]
	v_mfma_f32_16x16x32_bf16 v[10:13], v[236:239], v[200:203], v[10:13]
	v_mfma_f32_16x16x32_bf16 v[6:9], v[228:231], v[220:223], v[6:9]
	v_mfma_f32_16x16x32_bf16 v[2:5], v[236:239], v[220:223], v[2:5]
	v_mfma_f32_16x16x32_bf16 v[50:53], v[232:235], v[188:191], v[50:53]
	v_mfma_f32_16x16x32_bf16 v[42:45], v[240:243], v[188:191], v[42:45]
	v_mfma_f32_16x16x32_bf16 v[34:37], v[232:235], v[196:199], v[34:37]
	v_mfma_f32_16x16x32_bf16 v[26:29], v[240:243], v[196:199], v[26:29]
	v_mfma_f32_16x16x32_bf16 v[18:21], v[232:235], v[216:219], v[18:21]
	v_mfma_f32_16x16x32_bf16 v[10:13], v[240:243], v[216:219], v[10:13]
	v_mfma_f32_16x16x32_bf16 v[6:9], v[232:235], v[224:227], v[6:9]
	v_mfma_f32_16x16x32_bf16 v[2:5], v[240:243], v[224:227], v[2:5]
	s_add_i32 s44, s44, 2
	s_add_u32 s6, s6, 0x100
	s_addc_u32 s7, s7, 0
	s_add_u32 s25, s25, 0x100
	s_addc_u32 s46, s46, 0
	s_cmp_gt_u32 s44, 5
	s_barrier
	s_cbranch_scc0 .LBB0_500
	v_lshl_or_b32 v156, s62, 8, v146
	v_ashrrev_i32_e32 v157, 31, v156
	v_lshl_add_u64 v[140:141], v[156:157], 2, s[38:39]
	global_load_dwordx4 v[200:203], v[140:141], off offset:16
	global_load_dwordx4 v[220:223], v[140:141], off
	global_load_dwordx4 v[228:231], v[140:141], off offset:528
	global_load_dwordx4 v[236:239], v[140:141], off offset:512
	v_lshl_add_u32 v142, s63, 8, v144
	v_ashrrev_i32_e32 v143, 31, v142
	s_mov_b32 s2, 0x400000
	s_mov_b64 s[6:7], 0x400000
	s_mov_b32 s62, s41
	s_mov_b32 s63, s10
	s_mov_b64 s[78:79], s[74:75]
	s_mov_b64 s[80:81], s[76:77]
	s_waitcnt vmcnt(0)
	v_mov_b32_e32 v148, v200
	v_mov_b32_e32 v149, v201
	v_mov_b32_e32 v150, v202
	v_mov_b32_e32 v151, v203
	v_mov_b32_e32 v152, v220
	v_mov_b32_e32 v153, v221
	v_mov_b32_e32 v154, v222
	v_mov_b32_e32 v155, v223
	v_pk_mul_f32 v[122:123], v[122:123], v[148:149]
	v_pk_mul_f32 v[126:127], v[126:127], v[152:153]
	v_pk_mul_f32 v[124:125], v[124:125], v[150:151]
	v_cvt_pk_bf16_f32 v150, v122, v123
	v_lshlrev_b64 v[122:123], 15, v[142:143]
	v_pk_mul_f32 v[128:129], v[128:129], v[154:155]
	v_cvt_pk_bf16_f32 v148, v126, v127
	v_cvt_pk_bf16_f32 v151, v124, v125
	v_lshl_add_u64 v[122:123], s[60:61], 0, v[122:123]
	v_lshlrev_b64 v[126:127], 1, v[156:157]
	v_or_b32_e32 v124, 0x80, v156
	v_cvt_pk_bf16_f32 v149, v128, v129
	v_lshl_add_u64 v[122:123], v[122:123], 0, v[126:127]
	v_ashrrev_i32_e32 v125, 31, v124
	global_store_dwordx4 v[122:123], v[148:151], off
	v_lshl_add_u64 v[124:125], v[124:125], 2, s[38:39]
	s_nop 1
	v_mov_b32_e32 v148, v228
	v_mov_b32_e32 v149, v229
	v_mov_b32_e32 v150, v230
	v_mov_b32_e32 v151, v231
	s_nop 1
	v_mov_b32_e32 v152, v236
	v_mov_b32_e32 v153, v237
	v_mov_b32_e32 v154, v238
	v_mov_b32_e32 v155, v239
	s_nop 0
	v_pk_mul_f32 v[128:129], v[116:117], v[150:151]
	v_pk_mul_f32 v[120:121], v[120:121], v[154:155]
	v_pk_mul_f32 v[118:119], v[118:119], v[152:153]
	v_pk_mul_f32 v[116:117], v[114:115], v[148:149]
	v_cvt_pk_bf16_f32 v114, v118, v119
	v_cvt_pk_bf16_f32 v115, v120, v121
	v_cvt_pk_bf16_f32 v116, v116, v117
	v_cvt_pk_bf16_f32 v117, v128, v129
	global_store_dwordx4 v[122:123], v[114:117], off offset:256
	s_nop 1
	v_mov_b32_e32 v114, v200
	v_mov_b32_e32 v115, v201
	v_mov_b32_e32 v116, v202
	v_mov_b32_e32 v117, v203
	s_nop 0
	s_nop 1
	v_mov_b32_e32 v118, v220
	v_mov_b32_e32 v119, v221
	v_mov_b32_e32 v120, v222
	v_mov_b32_e32 v121, v223
	v_or_b32_e32 v128, 16, v142
	v_ashrrev_i32_e32 v129, 31, v128
	s_nop 0
	v_pk_mul_f32 v[116:117], v[108:109], v[116:117]
	v_pk_mul_f32 v[110:111], v[110:111], v[118:119]
	v_pk_mul_f32 v[108:109], v[106:107], v[114:115]
	v_cvt_pk_bf16_f32 v106, v110, v111
	v_lshlrev_b64 v[110:111], 15, v[128:129]
	v_pk_mul_f32 v[112:113], v[112:113], v[120:121]
	v_lshl_add_u64 v[110:111], s[60:61], 0, v[110:111]
	v_cvt_pk_bf16_f32 v107, v112, v113
	v_cvt_pk_bf16_f32 v108, v108, v109
	v_cvt_pk_bf16_f32 v109, v116, v117
	v_lshl_add_u64 v[114:115], v[110:111], 0, v[126:127]
	global_store_dwordx4 v[114:115], v[106:109], off
	s_nop 1
	v_mov_b32_e32 v106, v228
	v_mov_b32_e32 v107, v229
	v_mov_b32_e32 v108, v230
	v_mov_b32_e32 v109, v231
	s_nop 0
	s_nop 1
	v_mov_b32_e32 v110, v236
	v_mov_b32_e32 v111, v237
	v_mov_b32_e32 v112, v238
	v_mov_b32_e32 v113, v239
	s_nop 0
	v_pk_mul_f32 v[108:109], v[100:101], v[108:109]
	v_pk_mul_f32 v[104:105], v[104:105], v[112:113]
	v_pk_mul_f32 v[102:103], v[102:103], v[110:111]
	v_pk_mul_f32 v[100:101], v[98:99], v[106:107]
	v_cvt_pk_bf16_f32 v98, v102, v103
	v_cvt_pk_bf16_f32 v99, v104, v105
	v_cvt_pk_bf16_f32 v100, v100, v101
	v_cvt_pk_bf16_f32 v101, v108, v109
	global_store_dwordx4 v[114:115], v[98:101], off offset:256
	s_nop 1
	v_mov_b32_e32 v98, v200
	v_mov_b32_e32 v99, v201
	v_mov_b32_e32 v100, v202
	v_mov_b32_e32 v101, v203
	s_nop 0
	s_nop 1
	v_mov_b32_e32 v102, v220
	v_mov_b32_e32 v103, v221
	v_mov_b32_e32 v104, v222
	v_mov_b32_e32 v105, v223
	v_or_b32_e32 v106, 32, v142
	v_ashrrev_i32_e32 v107, 31, v106
	s_nop 0
	v_pk_mul_f32 v[100:101], v[92:93], v[100:101]
	v_pk_mul_f32 v[94:95], v[94:95], v[102:103]
	v_pk_mul_f32 v[92:93], v[90:91], v[98:99]
	v_cvt_pk_bf16_f32 v90, v94, v95
	v_lshlrev_b64 v[94:95], 15, v[106:107]
	v_pk_mul_f32 v[96:97], v[96:97], v[104:105]
	v_lshl_add_u64 v[94:95], s[60:61], 0, v[94:95]
	v_cvt_pk_bf16_f32 v91, v96, v97
	v_cvt_pk_bf16_f32 v92, v92, v93
	v_cvt_pk_bf16_f32 v93, v100, v101
	v_lshl_add_u64 v[98:99], v[94:95], 0, v[126:127]
	global_store_dwordx4 v[98:99], v[90:93], off
	s_nop 1
	v_mov_b32_e32 v90, v228
	v_mov_b32_e32 v91, v229
	v_mov_b32_e32 v92, v230
	v_mov_b32_e32 v93, v231
	s_nop 0
	s_nop 1
	v_mov_b32_e32 v94, v236
	v_mov_b32_e32 v95, v237
	v_mov_b32_e32 v96, v238
	v_mov_b32_e32 v97, v239
	s_nop 0
	v_pk_mul_f32 v[92:93], v[84:85], v[92:93]
	v_pk_mul_f32 v[88:89], v[88:89], v[96:97]
	v_pk_mul_f32 v[86:87], v[86:87], v[94:95]
	v_pk_mul_f32 v[84:85], v[82:83], v[90:91]
	v_cvt_pk_bf16_f32 v82, v86, v87
	v_cvt_pk_bf16_f32 v83, v88, v89
	v_cvt_pk_bf16_f32 v84, v84, v85
	v_cvt_pk_bf16_f32 v85, v92, v93
	global_store_dwordx4 v[98:99], v[82:85], off offset:256
	s_nop 1
	v_mov_b32_e32 v82, v200
	v_mov_b32_e32 v83, v201
	v_mov_b32_e32 v84, v202
	v_mov_b32_e32 v85, v203
	s_nop 0
	s_nop 1
	v_mov_b32_e32 v86, v220
	v_mov_b32_e32 v87, v221
	v_mov_b32_e32 v88, v222
	v_mov_b32_e32 v89, v223
	v_or_b32_e32 v90, 48, v142
	v_ashrrev_i32_e32 v91, 31, v90
	s_nop 0
	v_pk_mul_f32 v[84:85], v[76:77], v[84:85]
	v_pk_mul_f32 v[78:79], v[78:79], v[86:87]
	v_pk_mul_f32 v[76:77], v[74:75], v[82:83]
	v_cvt_pk_bf16_f32 v74, v78, v79
	v_lshlrev_b64 v[78:79], 15, v[90:91]
	v_pk_mul_f32 v[80:81], v[80:81], v[88:89]
	v_lshl_add_u64 v[78:79], s[60:61], 0, v[78:79]
	v_cvt_pk_bf16_f32 v75, v80, v81
	v_cvt_pk_bf16_f32 v76, v76, v77
	v_cvt_pk_bf16_f32 v77, v84, v85
	v_lshl_add_u64 v[82:83], v[78:79], 0, v[126:127]
	global_store_dwordx4 v[82:83], v[74:77], off
	s_nop 1
	v_mov_b32_e32 v74, v228
	v_mov_b32_e32 v75, v229
	v_mov_b32_e32 v76, v230
	v_mov_b32_e32 v77, v231
	s_nop 0
	s_nop 1
	v_mov_b32_e32 v78, v236
	v_mov_b32_e32 v79, v237
	v_mov_b32_e32 v80, v238
	v_mov_b32_e32 v81, v239
	s_nop 0
	v_pk_mul_f32 v[76:77], v[68:69], v[76:77]
	v_pk_mul_f32 v[72:73], v[72:73], v[80:81]
	v_pk_mul_f32 v[70:71], v[70:71], v[78:79]
	v_pk_mul_f32 v[68:69], v[66:67], v[74:75]
	v_cvt_pk_bf16_f32 v66, v70, v71
	v_cvt_pk_bf16_f32 v67, v72, v73
	v_cvt_pk_bf16_f32 v68, v68, v69
	v_cvt_pk_bf16_f32 v69, v76, v77
	global_store_dwordx4 v[82:83], v[66:69], off offset:256
	s_nop 1
	v_mov_b32_e32 v66, v200
	v_mov_b32_e32 v67, v201
	v_mov_b32_e32 v68, v202
	v_mov_b32_e32 v69, v203
	s_nop 0
	s_nop 1
	v_mov_b32_e32 v70, v220
	v_mov_b32_e32 v71, v221
	v_mov_b32_e32 v72, v222
	v_mov_b32_e32 v73, v223
	s_nop 0
	v_pk_mul_f32 v[68:69], v[60:61], v[68:69]
	v_pk_mul_f32 v[62:63], v[62:63], v[70:71]
	v_pk_mul_f32 v[64:65], v[64:65], v[72:73]
	v_pk_mul_f32 v[60:61], v[58:59], v[66:67]
	v_cvt_pk_bf16_f32 v58, v62, v63
	v_add_co_u32_e32 v62, vcc, s2, v122
	v_cvt_pk_bf16_f32 v59, v64, v65
	v_cvt_pk_bf16_f32 v60, v60, v61
	v_cvt_pk_bf16_f32 v61, v68, v69
	v_addc_co_u32_e32 v63, vcc, 0, v123, vcc
	global_store_dwordx4 v[62:63], v[58:61], off
	s_nop 1
	v_mov_b32_e32 v58, v228
	v_mov_b32_e32 v59, v229
	v_mov_b32_e32 v60, v230
	v_mov_b32_e32 v61, v231
	s_nop 0
	s_nop 1
	v_mov_b32_e32 v62, v236
	v_mov_b32_e32 v63, v237
	v_mov_b32_e32 v64, v238
	v_mov_b32_e32 v65, v239
	v_lshl_add_u64 v[66:67], v[122:123], 0, s[6:7]
	s_mov_b32 s2, 0x480000
	s_mov_b64 s[6:7], 0x480000
	s_nop 0
	v_pk_mul_f32 v[60:61], v[44:45], v[60:61]
	v_pk_mul_f32 v[52:53], v[52:53], v[64:65]
	v_pk_mul_f32 v[50:51], v[50:51], v[62:63]
	v_pk_mul_f32 v[44:45], v[42:43], v[58:59]
	v_cvt_pk_bf16_f32 v42, v50, v51
	v_cvt_pk_bf16_f32 v43, v52, v53
	v_cvt_pk_bf16_f32 v44, v44, v45
	v_cvt_pk_bf16_f32 v45, v60, v61
	global_store_dwordx4 v[66:67], v[42:45], off offset:256
	s_nop 1
	v_mov_b32_e32 v42, v200
	v_mov_b32_e32 v43, v201
	v_mov_b32_e32 v44, v202
	v_mov_b32_e32 v45, v203
	s_nop 0
	s_nop 1
	v_mov_b32_e32 v50, v220
	v_mov_b32_e32 v51, v221
	v_mov_b32_e32 v52, v222
	v_mov_b32_e32 v53, v223
	s_nop 0
	v_pk_mul_f32 v[48:49], v[48:49], v[44:45]
	v_pk_mul_f32 v[52:53], v[56:57], v[52:53]
	v_pk_mul_f32 v[50:51], v[54:55], v[50:51]
	v_pk_mul_f32 v[44:45], v[46:47], v[42:43]
	v_add_co_u32_e32 v46, vcc, s2, v122
	v_cvt_pk_bf16_f32 v42, v50, v51
	v_cvt_pk_bf16_f32 v43, v52, v53
	v_cvt_pk_bf16_f32 v44, v44, v45
	v_cvt_pk_bf16_f32 v45, v48, v49
	v_addc_co_u32_e32 v47, vcc, 0, v123, vcc
	global_store_dwordx4 v[46:47], v[42:45], off
	s_nop 1
	v_mov_b32_e32 v42, v228
	v_mov_b32_e32 v43, v229
	v_mov_b32_e32 v44, v230
	v_mov_b32_e32 v45, v231
	s_nop 0
	s_nop 1
	v_mov_b32_e32 v46, v236
	v_mov_b32_e32 v47, v237
	v_mov_b32_e32 v48, v238
	v_mov_b32_e32 v49, v239
	v_lshl_add_u64 v[50:51], v[122:123], 0, s[6:7]
	s_mov_b32 s2, 0x500000
	s_mov_b64 s[6:7], 0x500000
	s_nop 0
	v_pk_mul_f32 v[44:45], v[28:29], v[44:45]
	v_pk_mul_f32 v[36:37], v[36:37], v[48:49]
	v_pk_mul_f32 v[34:35], v[34:35], v[46:47]
	v_pk_mul_f32 v[28:29], v[26:27], v[42:43]
	v_cvt_pk_bf16_f32 v26, v34, v35
	v_cvt_pk_bf16_f32 v27, v36, v37
	v_cvt_pk_bf16_f32 v28, v28, v29
	v_cvt_pk_bf16_f32 v29, v44, v45
	global_store_dwordx4 v[50:51], v[26:29], off offset:256
	s_nop 1
	v_mov_b32_e32 v26, v200
	v_mov_b32_e32 v27, v201
	v_mov_b32_e32 v28, v202
	v_mov_b32_e32 v29, v203
	s_nop 0
	s_nop 1
	v_mov_b32_e32 v34, v220
	v_mov_b32_e32 v35, v221
	v_mov_b32_e32 v36, v222
	v_mov_b32_e32 v37, v223
	s_nop 0
	v_pk_mul_f32 v[32:33], v[32:33], v[28:29]
	v_pk_mul_f32 v[36:37], v[40:41], v[36:37]
	v_pk_mul_f32 v[34:35], v[38:39], v[34:35]
	v_pk_mul_f32 v[28:29], v[30:31], v[26:27]
	v_add_co_u32_e32 v30, vcc, s2, v122
	v_cvt_pk_bf16_f32 v26, v34, v35
	v_cvt_pk_bf16_f32 v27, v36, v37
	v_cvt_pk_bf16_f32 v28, v28, v29
	v_cvt_pk_bf16_f32 v29, v32, v33
	v_addc_co_u32_e32 v31, vcc, 0, v123, vcc
	global_store_dwordx4 v[30:31], v[26:29], off
	s_nop 1
	v_mov_b32_e32 v26, v228
	v_mov_b32_e32 v27, v229
	v_mov_b32_e32 v28, v230
	v_mov_b32_e32 v29, v231
	s_nop 0
	s_nop 1
	v_mov_b32_e32 v30, v236
	v_mov_b32_e32 v31, v237
	v_mov_b32_e32 v32, v238
	v_mov_b32_e32 v33, v239
	v_lshl_add_u64 v[34:35], v[122:123], 0, s[6:7]
	s_mov_b32 s2, 0x580000
	s_mov_b64 s[6:7], 0x580000
	s_nop 0
	v_pk_mul_f32 v[28:29], v[12:13], v[28:29]
	v_pk_mul_f32 v[20:21], v[20:21], v[32:33]
	v_pk_mul_f32 v[18:19], v[18:19], v[30:31]
	v_pk_mul_f32 v[12:13], v[10:11], v[26:27]
	v_cvt_pk_bf16_f32 v10, v18, v19
	v_cvt_pk_bf16_f32 v11, v20, v21
	v_cvt_pk_bf16_f32 v12, v12, v13
	v_cvt_pk_bf16_f32 v13, v28, v29
	global_store_dwordx4 v[34:35], v[10:13], off offset:256
	s_nop 1
	v_mov_b32_e32 v10, v200
	v_mov_b32_e32 v11, v201
	v_mov_b32_e32 v12, v202
	v_mov_b32_e32 v13, v203
	s_nop 0
	s_nop 1
	v_mov_b32_e32 v18, v220
	v_mov_b32_e32 v19, v221
	v_mov_b32_e32 v20, v222
	v_mov_b32_e32 v21, v223
	s_nop 0
	v_pk_mul_f32 v[16:17], v[16:17], v[12:13]
	v_pk_mul_f32 v[20:21], v[24:25], v[20:21]
	v_pk_mul_f32 v[18:19], v[22:23], v[18:19]
	v_pk_mul_f32 v[12:13], v[14:15], v[10:11]
	v_add_co_u32_e32 v14, vcc, s2, v122
	v_cvt_pk_bf16_f32 v10, v18, v19
	v_cvt_pk_bf16_f32 v11, v20, v21
	v_cvt_pk_bf16_f32 v12, v12, v13
	v_cvt_pk_bf16_f32 v13, v16, v17
	v_addc_co_u32_e32 v15, vcc, 0, v123, vcc
	global_store_dwordx4 v[14:15], v[10:13], off
	s_nop 1
	v_mov_b32_e32 v10, v228
	v_mov_b32_e32 v11, v229
	v_mov_b32_e32 v12, v230
	v_mov_b32_e32 v13, v231
	s_nop 0
	s_nop 1
	v_mov_b32_e32 v14, v236
	v_mov_b32_e32 v15, v237
	v_mov_b32_e32 v16, v238
	v_mov_b32_e32 v17, v239
	v_lshl_add_u64 v[18:19], v[122:123], 0, s[6:7]
	s_and_b64 vcc, exec, s[0:1]
	s_nop 0
	v_pk_mul_f32 v[12:13], v[4:5], v[12:13]
	v_pk_mul_f32 v[8:9], v[8:9], v[16:17]
	v_pk_mul_f32 v[6:7], v[6:7], v[14:15]
	v_pk_mul_f32 v[4:5], v[2:3], v[10:11]
	v_cvt_pk_bf16_f32 v2, v6, v7
	v_cvt_pk_bf16_f32 v3, v8, v9
	v_cvt_pk_bf16_f32 v4, v4, v5
	v_cvt_pk_bf16_f32 v5, v12, v13
	global_store_dwordx4 v[18:19], v[2:5], off offset:256
	s_cbranch_vccz .LBB0_491
	v_readlane_b32 s0, v254, 12
	s_waitcnt vmcnt(0)
	v_readlane_b32 s1, v254, 13
	v_readlane_b32 s84, v251, 38
	v_readlane_b32 s18, v253, 0
	s_andn2_b64 vcc, exec, s[0:1]
	v_readlane_b32 s85, v251, 39
	v_readlane_b32 s86, v251, 40
	v_readlane_b32 s87, v251, 41
	v_readlane_b32 s14, v250, 63
	v_readlane_b32 s19, v253, 1
	s_cbranch_vccnz .LBB0_504
	s_barrier

.LBB0_655:
	s_add_u32 s2, s68, 0xfff80080
	s_addc_u32 s17, s69, -1
	s_add_i32 s26, 0, 0x10000
	v_add_u32_e32 v156, s26, v141
	ds_read_b128 v[144:147], v156
	ds_read_b128 v[148:151], v156 offset:1024
	ds_read_b128 v[152:155], v156 offset:2048
	ds_read_b128 v[156:159], v156 offset:3072
	s_cmp_eq_u32 s44, 28
	s_cselect_b32 s73, s55, s17
	s_cselect_b32 s72, s83, s2
	s_cselect_b32 s71, s24, s92
	s_cselect_b32 s70, s25, s43
	v_lshl_add_u64 v[164:165], s[68:69], 0, v[136:137]
	s_add_i32 m0, s58, 0xc000
	ds_read_b128 v[160:163], v143
	ds_read_b128 v[188:191], v143 offset:1024
	ds_read_b128 v[192:195], v143 offset:2048
	ds_read_b128 v[196:199], v143 offset:3072
	ds_read_b128 v[200:203], v143 offset:4096
	ds_read_b128 v[216:219], v143 offset:5120
	ds_read_b128 v[220:223], v143 offset:6144
	ds_read_b128 v[224:227], v143 offset:7168
	global_load_lds_dwordx4 v[164:165], off
	v_lshl_add_u64 v[164:165], s[68:69], 0, v[138:139]
	s_add_i32 m0, s58, 0xe000
	s_nop 0
	global_load_lds_dwordx4 v[164:165], off
	s_waitcnt lgkmcnt(8)
	s_barrier
	s_waitcnt lgkmcnt(7)
	v_mfma_f32_16x16x32_bf16 v[126:129], v[144:147], v[160:163], v[126:129]
	v_mfma_f32_16x16x32_bf16 v[122:125], v[152:155], v[160:163], v[122:125]
	s_waitcnt lgkmcnt(3)
	v_mfma_f32_16x16x32_bf16 v[118:121], v[144:147], v[192:195], v[118:121]
	v_mfma_f32_16x16x32_bf16 v[114:117], v[152:155], v[192:195], v[114:117]
	v_mfma_f32_16x16x32_bf16 v[102:105], v[144:147], v[200:203], v[102:105]
	v_mfma_f32_16x16x32_bf16 v[98:101], v[152:155], v[200:203], v[98:101]
	s_waitcnt lgkmcnt(0)
	v_mfma_f32_16x16x32_bf16 v[86:89], v[144:147], v[220:223], v[86:89]
	v_mfma_f32_16x16x32_bf16 v[82:85], v[152:155], v[220:223], v[82:85]
	v_mfma_f32_16x16x32_bf16 v[126:129], v[148:151], v[188:191], v[126:129]
	v_mfma_f32_16x16x32_bf16 v[122:125], v[156:159], v[188:191], v[122:125]
	v_mfma_f32_16x16x32_bf16 v[118:121], v[148:151], v[196:199], v[118:121]
	v_mfma_f32_16x16x32_bf16 v[114:117], v[156:159], v[196:199], v[114:117]
	v_mfma_f32_16x16x32_bf16 v[102:105], v[148:151], v[216:219], v[102:105]
	v_mfma_f32_16x16x32_bf16 v[98:101], v[156:159], v[216:219], v[98:101]
	v_mfma_f32_16x16x32_bf16 v[86:89], v[148:151], v[224:227], v[86:89]
	v_mfma_f32_16x16x32_bf16 v[82:85], v[156:159], v[224:227], v[82:85]
	s_barrier
	s_add_i32 s2, 0, 0x14000
	v_add_u32_e32 v164, s2, v141
	s_add_i32 s17, s26, s3
	ds_read_b128 v[228:231], v164
	ds_read_b128 v[232:235], v164 offset:1024
	ds_read_b128 v[236:239], v164 offset:2048
	ds_read_b128 v[240:243], v164 offset:3072
	v_lshl_add_u64 v[164:165], s[70:71], 0, v[0:1]
	s_mov_b32 m0, s17
	v_lshl_add_u64 v[204:205], s[70:71], 0, v[130:131]
	global_load_lds_dwordx4 v[164:165], off
	s_add_i32 m0, s17, 0x2000
	s_nop 0
	global_load_lds_dwordx4 v[204:205], off
	s_barrier
	s_waitcnt lgkmcnt(1)
	v_mfma_f32_16x16x32_bf16 v[110:113], v[228:231], v[160:163], v[110:113]
	v_mfma_f32_16x16x32_bf16 v[106:109], v[236:239], v[160:163], v[106:109]
	v_mfma_f32_16x16x32_bf16 v[94:97], v[228:231], v[192:195], v[94:97]
	v_mfma_f32_16x16x32_bf16 v[90:93], v[236:239], v[192:195], v[90:93]
	v_mfma_f32_16x16x32_bf16 v[78:81], v[228:231], v[200:203], v[78:81]
	v_mfma_f32_16x16x32_bf16 v[74:77], v[236:239], v[200:203], v[74:77]
	s_waitcnt lgkmcnt(0)
	v_mfma_f32_16x16x32_bf16 v[70:73], v[228:231], v[220:223], v[70:73]
	v_mfma_f32_16x16x32_bf16 v[66:69], v[236:239], v[220:223], v[66:69]
	v_mfma_f32_16x16x32_bf16 v[110:113], v[232:235], v[188:191], v[110:113]
	v_mfma_f32_16x16x32_bf16 v[106:109], v[240:243], v[188:191], v[106:109]
	v_mfma_f32_16x16x32_bf16 v[94:97], v[232:235], v[196:199], v[94:97]
	v_mfma_f32_16x16x32_bf16 v[90:93], v[240:243], v[196:199], v[90:93]
	v_mfma_f32_16x16x32_bf16 v[78:81], v[232:235], v[216:219], v[78:81]
	v_mfma_f32_16x16x32_bf16 v[74:77], v[240:243], v[216:219], v[74:77]
	v_mfma_f32_16x16x32_bf16 v[70:73], v[232:235], v[224:227], v[70:73]
	v_mfma_f32_16x16x32_bf16 v[66:69], v[240:243], v[224:227], v[66:69]
	s_mov_b32 m0, s58
	v_lshl_add_u64 v[244:245], s[72:73], 0, v[134:135]
	s_barrier
	ds_read_b128 v[160:163], v143 offset:16384
	ds_read_b128 v[188:191], v143 offset:17408
	ds_read_b128 v[192:195], v143 offset:18432
	ds_read_b128 v[196:199], v143 offset:19456
	ds_read_b128 v[200:203], v143 offset:20480
	ds_read_b128 v[216:219], v143 offset:21504
	ds_read_b128 v[220:223], v143 offset:22528
	ds_read_b128 v[224:227], v143 offset:23552
	global_load_lds_dwordx4 v[244:245], off
	v_lshl_add_u64 v[246:247], s[72:73], 0, v[132:133]
	s_mov_b32 m0, s74
	s_nop 0
	global_load_lds_dwordx4 v[246:247], off
	s_barrier
	s_waitcnt lgkmcnt(7)
	v_mfma_f32_16x16x32_bf16 v[62:65], v[144:147], v[160:163], v[62:65]
	v_mfma_f32_16x16x32_bf16 v[58:61], v[152:155], v[160:163], v[58:61]
	s_waitcnt lgkmcnt(3)
	v_mfma_f32_16x16x32_bf16 v[54:57], v[144:147], v[192:195], v[54:57]
	v_mfma_f32_16x16x32_bf16 v[50:53], v[152:155], v[192:195], v[50:53]
	v_mfma_f32_16x16x32_bf16 v[38:41], v[144:147], v[200:203], v[38:41]
	v_mfma_f32_16x16x32_bf16 v[34:37], v[152:155], v[200:203], v[34:37]
	s_waitcnt lgkmcnt(0)
	v_mfma_f32_16x16x32_bf16 v[22:25], v[144:147], v[220:223], v[22:25]
	v_mfma_f32_16x16x32_bf16 v[18:21], v[152:155], v[220:223], v[18:21]
	v_mfma_f32_16x16x32_bf16 v[62:65], v[148:151], v[188:191], v[62:65]
	v_mfma_f32_16x16x32_bf16 v[58:61], v[156:159], v[188:191], v[58:61]
	v_mfma_f32_16x16x32_bf16 v[54:57], v[148:151], v[196:199], v[54:57]
	v_mfma_f32_16x16x32_bf16 v[50:53], v[156:159], v[196:199], v[50:53]
	v_mfma_f32_16x16x32_bf16 v[38:41], v[148:151], v[216:219], v[38:41]
	v_mfma_f32_16x16x32_bf16 v[34:37], v[156:159], v[216:219], v[34:37]
	v_mfma_f32_16x16x32_bf16 v[22:25], v[148:151], v[224:227], v[22:25]
	v_mfma_f32_16x16x32_bf16 v[18:21], v[156:159], v[224:227], v[18:21]
	s_barrier
	s_add_u32 s26, s70, 0x80000
	s_addc_u32 s27, s71, 0
	s_add_i32 s2, s2, s3
	v_lshl_add_u64 v[144:145], s[26:27], 0, v[0:1]
	s_mov_b32 m0, s2
	s_nop 0
	global_load_lds_dwordx4 v[144:145], off
	v_lshl_add_u64 v[144:145], s[26:27], 0, v[130:131]
	s_add_i32 m0, s2, 0x2000
	s_nop 0
	global_load_lds_dwordx4 v[144:145], off
	s_waitcnt vmcnt(6)
	s_barrier
	v_mfma_f32_16x16x32_bf16 v[46:49], v[228:231], v[160:163], v[46:49]
	v_mfma_f32_16x16x32_bf16 v[42:45], v[236:239], v[160:163], v[42:45]
	v_mfma_f32_16x16x32_bf16 v[30:33], v[228:231], v[192:195], v[30:33]
	v_mfma_f32_16x16x32_bf16 v[26:29], v[236:239], v[192:195], v[26:29]
	v_mfma_f32_16x16x32_bf16 v[14:17], v[228:231], v[200:203], v[14:17]
	v_mfma_f32_16x16x32_bf16 v[10:13], v[236:239], v[200:203], v[10:13]
	v_mfma_f32_16x16x32_bf16 v[6:9], v[228:231], v[220:223], v[6:9]
	v_mfma_f32_16x16x32_bf16 v[2:5], v[236:239], v[220:223], v[2:5]
	v_mfma_f32_16x16x32_bf16 v[46:49], v[232:235], v[188:191], v[46:49]
	v_mfma_f32_16x16x32_bf16 v[42:45], v[240:243], v[188:191], v[42:45]
	v_mfma_f32_16x16x32_bf16 v[30:33], v[232:235], v[196:199], v[30:33]
	v_mfma_f32_16x16x32_bf16 v[26:29], v[240:243], v[196:199], v[26:29]
	v_mfma_f32_16x16x32_bf16 v[14:17], v[232:235], v[216:219], v[14:17]
	v_mfma_f32_16x16x32_bf16 v[10:13], v[240:243], v[216:219], v[10:13]
	v_mfma_f32_16x16x32_bf16 v[6:9], v[232:235], v[224:227], v[6:9]
	v_mfma_f32_16x16x32_bf16 v[2:5], v[240:243], v[224:227], v[2:5]
	s_add_i32 s2, 0, 0x18000
	v_add_u32_e32 v156, s2, v141
	s_barrier
	ds_read_b128 v[144:147], v156
	ds_read_b128 v[148:151], v156 offset:1024
	ds_read_b128 v[152:155], v156 offset:2048
	ds_read_b128 v[156:159], v156 offset:3072
	s_add_u32 s26, s72, 0x80000
	s_addc_u32 s27, s73, 0
	s_mov_b32 m0, s75
	v_lshl_add_u64 v[228:229], s[26:27], 0, v[134:135]
	ds_read_b128 v[160:163], v143 offset:32768
	ds_read_b128 v[188:191], v143 offset:33792
	ds_read_b128 v[192:195], v143 offset:34816
	ds_read_b128 v[196:199], v143 offset:35840
	ds_read_b128 v[200:203], v143 offset:36864
	ds_read_b128 v[216:219], v143 offset:37888
	ds_read_b128 v[220:223], v143 offset:38912
	ds_read_b128 v[224:227], v143 offset:39936
	global_load_lds_dwordx4 v[228:229], off
	v_lshl_add_u64 v[228:229], s[26:27], 0, v[132:133]
	s_mov_b32 m0, s79
	s_nop 0
	global_load_lds_dwordx4 v[228:229], off
	s_waitcnt lgkmcnt(8)
	s_barrier
	s_waitcnt lgkmcnt(7)
	v_mfma_f32_16x16x32_bf16 v[126:129], v[144:147], v[160:163], v[126:129]
	v_mfma_f32_16x16x32_bf16 v[122:125], v[152:155], v[160:163], v[122:125]
	s_waitcnt lgkmcnt(3)
	v_mfma_f32_16x16x32_bf16 v[118:121], v[144:147], v[192:195], v[118:121]
	v_mfma_f32_16x16x32_bf16 v[114:117], v[152:155], v[192:195], v[114:117]
	v_mfma_f32_16x16x32_bf16 v[102:105], v[144:147], v[200:203], v[102:105]
	v_mfma_f32_16x16x32_bf16 v[98:101], v[152:155], v[200:203], v[98:101]
	s_waitcnt lgkmcnt(0)
	v_mfma_f32_16x16x32_bf16 v[86:89], v[144:147], v[220:223], v[86:89]
	v_mfma_f32_16x16x32_bf16 v[82:85], v[152:155], v[220:223], v[82:85]
	v_mfma_f32_16x16x32_bf16 v[126:129], v[148:151], v[188:191], v[126:129]
	v_mfma_f32_16x16x32_bf16 v[122:125], v[156:159], v[188:191], v[122:125]
	v_mfma_f32_16x16x32_bf16 v[118:121], v[148:151], v[196:199], v[118:121]
	v_mfma_f32_16x16x32_bf16 v[114:117], v[156:159], v[196:199], v[114:117]
	v_mfma_f32_16x16x32_bf16 v[102:105], v[148:151], v[216:219], v[102:105]
	v_mfma_f32_16x16x32_bf16 v[98:101], v[156:159], v[216:219], v[98:101]
	v_mfma_f32_16x16x32_bf16 v[86:89], v[148:151], v[224:227], v[86:89]
	v_mfma_f32_16x16x32_bf16 v[82:85], v[156:159], v[224:227], v[82:85]
	s_barrier
	s_add_i32 s17, 0, 0x1c000
	s_add_i32 s2, s2, s3
	v_add_u32_e32 v206, s17, v141
	v_lshl_add_u64 v[164:165], v[164:165], 0, s[28:29]
	s_mov_b32 m0, s2
	ds_read_b128 v[228:231], v206
	ds_read_b128 v[232:235], v206 offset:1024
	ds_read_b128 v[236:239], v206 offset:2048
	ds_read_b128 v[240:243], v206 offset:3072
	global_load_lds_dwordx4 v[164:165], off
	v_lshl_add_u64 v[164:165], v[204:205], 0, s[28:29]
	s_add_i32 m0, s2, 0x2000
	s_nop 0
	global_load_lds_dwordx4 v[164:165], off
	s_barrier
	s_waitcnt lgkmcnt(1)
	v_mfma_f32_16x16x32_bf16 v[110:113], v[228:231], v[160:163], v[110:113]
	v_mfma_f32_16x16x32_bf16 v[106:109], v[236:239], v[160:163], v[106:109]
	v_mfma_f32_16x16x32_bf16 v[94:97], v[228:231], v[192:195], v[94:97]
	v_mfma_f32_16x16x32_bf16 v[90:93], v[236:239], v[192:195], v[90:93]
	v_mfma_f32_16x16x32_bf16 v[78:81], v[228:231], v[200:203], v[78:81]
	v_mfma_f32_16x16x32_bf16 v[74:77], v[236:239], v[200:203], v[74:77]
	s_waitcnt lgkmcnt(0)
	v_mfma_f32_16x16x32_bf16 v[70:73], v[228:231], v[220:223], v[70:73]
	v_mfma_f32_16x16x32_bf16 v[66:69], v[236:239], v[220:223], v[66:69]
	v_mfma_f32_16x16x32_bf16 v[110:113], v[232:235], v[188:191], v[110:113]
	v_mfma_f32_16x16x32_bf16 v[106:109], v[240:243], v[188:191], v[106:109]
	v_mfma_f32_16x16x32_bf16 v[94:97], v[232:235], v[196:199], v[94:97]
	v_mfma_f32_16x16x32_bf16 v[90:93], v[240:243], v[196:199], v[90:93]
	v_mfma_f32_16x16x32_bf16 v[78:81], v[232:235], v[216:219], v[78:81]
	v_mfma_f32_16x16x32_bf16 v[74:77], v[240:243], v[216:219], v[74:77]
	v_mfma_f32_16x16x32_bf16 v[70:73], v[232:235], v[224:227], v[70:73]
	v_mfma_f32_16x16x32_bf16 v[66:69], v[240:243], v[224:227], v[66:69]
	s_mov_b32 m0, s80
	v_lshl_add_u64 v[164:165], v[244:245], 0, s[28:29]
	s_barrier
	ds_read_b128 v[160:163], v143 offset:49152
	ds_read_b128 v[188:191], v143 offset:50176
	ds_read_b128 v[192:195], v143 offset:51200
	ds_read_b128 v[196:199], v143 offset:52224
	ds_read_b128 v[200:203], v143 offset:53248
	ds_read_b128 v[216:219], v143 offset:54272
	ds_read_b128 v[220:223], v143 offset:55296
	ds_read_b128 v[224:227], v143 offset:56320
	global_load_lds_dwordx4 v[164:165], off
	v_lshl_add_u64 v[164:165], v[246:247], 0, s[28:29]
	s_mov_b32 m0, s81
	s_nop 0
	global_load_lds_dwordx4 v[164:165], off
	s_barrier
	s_waitcnt lgkmcnt(7)
	v_mfma_f32_16x16x32_bf16 v[62:65], v[144:147], v[160:163], v[62:65]
	v_mfma_f32_16x16x32_bf16 v[58:61], v[152:155], v[160:163], v[58:61]
	s_waitcnt lgkmcnt(3)
	v_mfma_f32_16x16x32_bf16 v[54:57], v[144:147], v[192:195], v[54:57]
	v_mfma_f32_16x16x32_bf16 v[50:53], v[152:155], v[192:195], v[50:53]
	v_mfma_f32_16x16x32_bf16 v[38:41], v[144:147], v[200:203], v[38:41]
	v_mfma_f32_16x16x32_bf16 v[34:37], v[152:155], v[200:203], v[34:37]
	s_waitcnt lgkmcnt(0)
	v_mfma_f32_16x16x32_bf16 v[22:25], v[144:147], v[220:223], v[22:25]
	v_mfma_f32_16x16x32_bf16 v[18:21], v[152:155], v[220:223], v[18:21]
	v_mfma_f32_16x16x32_bf16 v[62:65], v[148:151], v[188:191], v[62:65]
	v_mfma_f32_16x16x32_bf16 v[58:61], v[156:159], v[188:191], v[58:61]
	v_mfma_f32_16x16x32_bf16 v[54:57], v[148:151], v[196:199], v[54:57]
	v_mfma_f32_16x16x32_bf16 v[50:53], v[156:159], v[196:199], v[50:53]
	v_mfma_f32_16x16x32_bf16 v[38:41], v[148:151], v[216:219], v[38:41]
	v_mfma_f32_16x16x32_bf16 v[34:37], v[156:159], v[216:219], v[34:37]
	v_mfma_f32_16x16x32_bf16 v[22:25], v[148:151], v[224:227], v[22:25]
	v_mfma_f32_16x16x32_bf16 v[18:21], v[156:159], v[224:227], v[18:21]
	s_barrier
	s_add_u32 s26, s70, 0x80080
	s_addc_u32 s27, s71, 0
	s_add_i32 s2, s17, s3
	v_lshl_add_u64 v[144:145], s[26:27], 0, v[0:1]
	s_mov_b32 m0, s2
	s_nop 0
	global_load_lds_dwordx4 v[144:145], off
	v_lshl_add_u64 v[144:145], s[26:27], 0, v[130:131]
	s_add_i32 m0, s2, 0x2000
	s_nop 0
	global_load_lds_dwordx4 v[144:145], off
	s_waitcnt vmcnt(6)
	s_barrier
	v_mfma_f32_16x16x32_bf16 v[46:49], v[228:231], v[160:163], v[46:49]
	v_mfma_f32_16x16x32_bf16 v[42:45], v[236:239], v[160:163], v[42:45]
	v_mfma_f32_16x16x32_bf16 v[30:33], v[228:231], v[192:195], v[30:33]
	v_mfma_f32_16x16x32_bf16 v[26:29], v[236:239], v[192:195], v[26:29]
	v_mfma_f32_16x16x32_bf16 v[14:17], v[228:231], v[200:203], v[14:17]
	v_mfma_f32_16x16x32_bf16 v[10:13], v[236:239], v[200:203], v[10:13]
	v_mfma_f32_16x16x32_bf16 v[6:9], v[228:231], v[220:223], v[6:9]
	v_mfma_f32_16x16x32_bf16 v[2:5], v[236:239], v[220:223], v[2:5]
	v_mfma_f32_16x16x32_bf16 v[46:49], v[232:235], v[188:191], v[46:49]
	v_mfma_f32_16x16x32_bf16 v[42:45], v[240:243], v[188:191], v[42:45]
	v_mfma_f32_16x16x32_bf16 v[30:33], v[232:235], v[196:199], v[30:33]
	v_mfma_f32_16x16x32_bf16 v[26:29], v[240:243], v[196:199], v[26:29]
	v_mfma_f32_16x16x32_bf16 v[14:17], v[232:235], v[216:219], v[14:17]
	v_mfma_f32_16x16x32_bf16 v[10:13], v[240:243], v[216:219], v[10:13]
	v_mfma_f32_16x16x32_bf16 v[6:9], v[232:235], v[224:227], v[6:9]
	v_mfma_f32_16x16x32_bf16 v[2:5], v[240:243], v[224:227], v[2:5]
	s_add_i32 s44, s44, 2
	s_add_u32 s68, s68, 0x100
	s_addc_u32 s69, s69, 0
	s_add_u32 s43, s43, 0x100
	s_addc_u32 s92, s92, 0
	s_cmp_gt_u32 s44, 29
	s_barrier
	s_cbranch_scc0 .LBB0_655
	v_lshl_add_u32 v144, s47, 8, v140
	v_lshl_or_b32 v146, s46, 8, v142
	v_ashrrev_i32_e32 v145, 31, v144
	v_cvt_pk_bf16_f32 v126, v126, v127
	v_cvt_pk_bf16_f32 v127, v128, v129
	v_cvt_pk_bf16_f32 v128, v122, v123
	v_lshlrev_b64 v[122:123], 12, v[144:145]
	v_ashrrev_i32_e32 v147, 31, v146
	v_cvt_pk_bf16_f32 v129, v124, v125
	v_lshl_add_u64 v[122:123], s[22:23], 0, v[122:123]
	v_lshlrev_b64 v[124:125], 1, v[146:147]
	v_lshl_add_u64 v[122:123], v[122:123], 0, v[124:125]
	v_cvt_pk_bf16_f32 v110, v110, v111
	v_cvt_pk_bf16_f32 v111, v112, v113
	v_cvt_pk_bf16_f32 v112, v106, v107
	v_cvt_pk_bf16_f32 v113, v108, v109
	global_store_dwordx4 v[122:123], v[110:113], off offset:256
	v_cvt_pk_bf16_f32 v94, v94, v95
	v_cvt_pk_bf16_f32 v95, v96, v97
	v_or_b32_e32 v110, 16, v144
	v_ashrrev_i32_e32 v111, 31, v110
	v_lshlrev_b64 v[110:111], 12, v[110:111]
	v_lshl_add_u64 v[110:111], s[22:23], 0, v[110:111]
	v_lshl_add_u64 v[110:111], v[110:111], 0, v[124:125]
	v_cvt_pk_bf16_f32 v96, v90, v91
	v_cvt_pk_bf16_f32 v97, v92, v93
	global_store_dwordx4 v[110:111], v[94:97], off offset:256
	s_mov_b32 s2, 0x80000
	v_cvt_pk_bf16_f32 v62, v62, v63
	v_or_b32_e32 v94, 32, v144
	v_ashrrev_i32_e32 v95, 31, v94
	v_cvt_pk_bf16_f32 v63, v64, v65
	v_cvt_pk_bf16_f32 v65, v60, v61
	s_mov_b64 s[4:5], 0x80000
	v_add_co_u32_e32 v60, vcc, s2, v122
	v_lshlrev_b64 v[94:95], 12, v[94:95]
	v_cvt_pk_bf16_f32 v64, v58, v59
	v_lshl_add_u64 v[58:59], v[122:123], 0, s[4:5]
	v_addc_co_u32_e32 v61, vcc, 0, v123, vcc
	v_cvt_pk_bf16_f32 v46, v46, v47
	v_cvt_pk_bf16_f32 v47, v48, v49
	v_cvt_pk_bf16_f32 v48, v42, v43
	v_cvt_pk_bf16_f32 v49, v44, v45
	s_mov_b32 s2, 0x90000
	v_lshl_add_u64 v[94:95], s[22:23], 0, v[94:95]
	global_store_dwordx4 v[58:59], v[46:49], off offset:256
	s_mov_b64 s[4:5], 0x90000
	v_lshl_add_u64 v[94:95], v[94:95], 0, v[124:125]
	v_add_co_u32_e32 v48, vcc, s2, v122
	v_cvt_pk_bf16_f32 v78, v78, v79
	v_cvt_pk_bf16_f32 v79, v80, v81
	v_cvt_pk_bf16_f32 v80, v74, v75
	v_cvt_pk_bf16_f32 v81, v76, v77
	v_lshl_add_u64 v[46:47], v[122:123], 0, s[4:5]
	v_addc_co_u32_e32 v49, vcc, 0, v123, vcc
	v_cvt_pk_bf16_f32 v30, v30, v31
	v_cvt_pk_bf16_f32 v31, v32, v33
	v_cvt_pk_bf16_f32 v32, v26, v27
	v_cvt_pk_bf16_f32 v33, v28, v29
	s_mov_b32 s2, 0xa0000
	global_store_dwordx4 v[94:95], v[78:81], off offset:256
	global_store_dwordx4 v[46:47], v[30:33], off offset:256
	s_mov_b64 s[4:5], 0xa0000
	v_or_b32_e32 v78, 48, v144
	v_add_co_u32_e32 v32, vcc, s2, v122
	v_ashrrev_i32_e32 v79, 31, v78
	v_lshl_add_u64 v[30:31], v[122:123], 0, s[4:5]
	v_addc_co_u32_e32 v33, vcc, 0, v123, vcc
	v_cvt_pk_bf16_f32 v14, v14, v15
	v_cvt_pk_bf16_f32 v15, v16, v17
	v_cvt_pk_bf16_f32 v16, v10, v11
	v_cvt_pk_bf16_f32 v17, v12, v13
	s_mov_b32 s2, 0xb0000
	v_lshlrev_b64 v[78:79], 12, v[78:79]
	global_store_dwordx4 v[30:31], v[14:17], off offset:256
	v_lshl_add_u64 v[78:79], s[22:23], 0, v[78:79]
	s_mov_b64 s[4:5], 0xb0000
	v_add_co_u32_e32 v16, vcc, s2, v122
	v_cvt_pk_bf16_f32 v106, v118, v119
	s_nop 0
	v_addc_co_u32_e32 v17, vcc, 0, v123, vcc
	v_cvt_pk_bf16_f32 v107, v120, v121
	v_cvt_pk_bf16_f32 v108, v114, v115
	v_cvt_pk_bf16_f32 v109, v116, v117
	v_cvt_pk_bf16_f32 v90, v102, v103
	v_cvt_pk_bf16_f32 v91, v104, v105
	v_cvt_pk_bf16_f32 v92, v98, v99
	v_cvt_pk_bf16_f32 v93, v100, v101
	v_cvt_pk_bf16_f32 v74, v86, v87
	v_cvt_pk_bf16_f32 v75, v88, v89
	v_cvt_pk_bf16_f32 v76, v82, v83
	v_cvt_pk_bf16_f32 v77, v84, v85
	v_lshl_add_u64 v[78:79], v[78:79], 0, v[124:125]
	v_cvt_pk_bf16_f32 v70, v70, v71
	v_cvt_pk_bf16_f32 v71, v72, v73
	v_cvt_pk_bf16_f32 v72, v66, v67
	v_cvt_pk_bf16_f32 v73, v68, v69
	v_cvt_pk_bf16_f32 v42, v54, v55
	v_cvt_pk_bf16_f32 v43, v56, v57
	v_cvt_pk_bf16_f32 v44, v50, v51
	v_cvt_pk_bf16_f32 v45, v52, v53
	v_cvt_pk_bf16_f32 v26, v38, v39
	v_cvt_pk_bf16_f32 v27, v40, v41
	v_cvt_pk_bf16_f32 v28, v34, v35
	v_cvt_pk_bf16_f32 v29, v36, v37
	v_cvt_pk_bf16_f32 v10, v22, v23
	v_cvt_pk_bf16_f32 v11, v24, v25
	v_cvt_pk_bf16_f32 v12, v18, v19
	v_cvt_pk_bf16_f32 v13, v20, v21
	v_lshl_add_u64 v[14:15], v[122:123], 0, s[4:5]
	v_cvt_pk_bf16_f32 v6, v6, v7
	v_cvt_pk_bf16_f32 v7, v8, v9
	v_cvt_pk_bf16_f32 v8, v2, v3
	v_cvt_pk_bf16_f32 v9, v4, v5
	s_and_b64 vcc, exec, s[0:1]
	s_mov_b32 s46, s42
	s_mov_b32 s47, s54
	s_mov_b64 s[70:71], s[64:65]
	s_mov_b64 s[68:69], s[62:63]
	global_store_dwordx4 v[122:123], v[126:129], off
	global_store_dwordx4 v[110:111], v[106:109], off
	global_store_dwordx4 v[94:95], v[90:93], off
	global_store_dwordx4 v[78:79], v[74:77], off
	global_store_dwordx4 v[78:79], v[70:73], off offset:256
	global_store_dwordx4 v[60:61], v[62:65], off
	global_store_dwordx4 v[48:49], v[42:45], off
	global_store_dwordx4 v[32:33], v[26:29], off
	global_store_dwordx4 v[16:17], v[10:13], off
	global_store_dwordx4 v[14:15], v[6:9], off offset:256
	s_cbranch_vccz .LBB0_652
	v_readlane_b32 s0, v254, 12
	s_waitcnt vmcnt(0)
	v_readlane_b32 s1, v254, 13
	v_readlane_b32 s84, v251, 38
	s_andn2_b64 vcc, exec, s[0:1]
	v_readlane_b32 s85, v251, 39
	v_readlane_b32 s86, v251, 40
	v_readlane_b32 s87, v251, 41
	s_cbranch_vccnz .LBB0_659
	s_barrier

.LBB0_724:
	s_add_u32 s2, s68, 0xfff80080
	s_addc_u32 s17, s69, -1
	s_add_i32 s26, 0, 0x10000
	v_add_u32_e32 v156, s26, v141
	ds_read_b128 v[144:147], v156
	ds_read_b128 v[148:151], v156 offset:1024
	ds_read_b128 v[152:155], v156 offset:2048
	ds_read_b128 v[156:159], v156 offset:3072
	s_cmp_eq_u32 s83, 28
	s_cselect_b32 s73, s55, s17
	s_cselect_b32 s72, s81, s2
	s_cselect_b32 s71, s24, s82
	s_cselect_b32 s70, s25, s43
	v_lshl_add_u64 v[164:165], s[68:69], 0, v[136:137]
	s_add_i32 m0, s58, 0xc000
	ds_read_b128 v[160:163], v143
	ds_read_b128 v[188:191], v143 offset:1024
	ds_read_b128 v[192:195], v143 offset:2048
	ds_read_b128 v[196:199], v143 offset:3072
	ds_read_b128 v[200:203], v143 offset:4096
	ds_read_b128 v[216:219], v143 offset:5120
	ds_read_b128 v[220:223], v143 offset:6144
	ds_read_b128 v[224:227], v143 offset:7168
	global_load_lds_dwordx4 v[164:165], off
	v_lshl_add_u64 v[164:165], s[68:69], 0, v[138:139]
	s_add_i32 m0, s58, 0xe000
	s_nop 0
	global_load_lds_dwordx4 v[164:165], off
	s_waitcnt lgkmcnt(8)
	s_barrier
	s_waitcnt lgkmcnt(7)
	v_mfma_f32_16x16x32_bf16 v[126:129], v[144:147], v[160:163], v[126:129]
	v_mfma_f32_16x16x32_bf16 v[122:125], v[152:155], v[160:163], v[122:125]
	s_waitcnt lgkmcnt(3)
	v_mfma_f32_16x16x32_bf16 v[118:121], v[144:147], v[192:195], v[118:121]
	v_mfma_f32_16x16x32_bf16 v[114:117], v[152:155], v[192:195], v[114:117]
	v_mfma_f32_16x16x32_bf16 v[102:105], v[144:147], v[200:203], v[102:105]
	v_mfma_f32_16x16x32_bf16 v[98:101], v[152:155], v[200:203], v[98:101]
	s_waitcnt lgkmcnt(0)
	v_mfma_f32_16x16x32_bf16 v[86:89], v[144:147], v[220:223], v[86:89]
	v_mfma_f32_16x16x32_bf16 v[82:85], v[152:155], v[220:223], v[82:85]
	v_mfma_f32_16x16x32_bf16 v[126:129], v[148:151], v[188:191], v[126:129]
	v_mfma_f32_16x16x32_bf16 v[122:125], v[156:159], v[188:191], v[122:125]
	v_mfma_f32_16x16x32_bf16 v[118:121], v[148:151], v[196:199], v[118:121]
	v_mfma_f32_16x16x32_bf16 v[114:117], v[156:159], v[196:199], v[114:117]
	v_mfma_f32_16x16x32_bf16 v[102:105], v[148:151], v[216:219], v[102:105]
	v_mfma_f32_16x16x32_bf16 v[98:101], v[156:159], v[216:219], v[98:101]
	v_mfma_f32_16x16x32_bf16 v[86:89], v[148:151], v[224:227], v[86:89]
	v_mfma_f32_16x16x32_bf16 v[82:85], v[156:159], v[224:227], v[82:85]
	s_barrier
	s_add_i32 s2, 0, 0x14000
	v_add_u32_e32 v164, s2, v141
	s_add_i32 s17, s26, s3
	ds_read_b128 v[228:231], v164
	ds_read_b128 v[232:235], v164 offset:1024
	ds_read_b128 v[236:239], v164 offset:2048
	ds_read_b128 v[240:243], v164 offset:3072
	v_lshl_add_u64 v[164:165], s[70:71], 0, v[0:1]
	s_mov_b32 m0, s17
	v_lshl_add_u64 v[204:205], s[70:71], 0, v[130:131]
	global_load_lds_dwordx4 v[164:165], off
	s_add_i32 m0, s17, 0x2000
	s_nop 0
	global_load_lds_dwordx4 v[204:205], off
	s_barrier
	s_waitcnt lgkmcnt(1)
	v_mfma_f32_16x16x32_bf16 v[110:113], v[228:231], v[160:163], v[110:113]
	v_mfma_f32_16x16x32_bf16 v[106:109], v[236:239], v[160:163], v[106:109]
	v_mfma_f32_16x16x32_bf16 v[94:97], v[228:231], v[192:195], v[94:97]
	v_mfma_f32_16x16x32_bf16 v[90:93], v[236:239], v[192:195], v[90:93]
	v_mfma_f32_16x16x32_bf16 v[78:81], v[228:231], v[200:203], v[78:81]
	v_mfma_f32_16x16x32_bf16 v[74:77], v[236:239], v[200:203], v[74:77]
	s_waitcnt lgkmcnt(0)
	v_mfma_f32_16x16x32_bf16 v[70:73], v[228:231], v[220:223], v[70:73]
	v_mfma_f32_16x16x32_bf16 v[66:69], v[236:239], v[220:223], v[66:69]
	v_mfma_f32_16x16x32_bf16 v[110:113], v[232:235], v[188:191], v[110:113]
	v_mfma_f32_16x16x32_bf16 v[106:109], v[240:243], v[188:191], v[106:109]
	v_mfma_f32_16x16x32_bf16 v[94:97], v[232:235], v[196:199], v[94:97]
	v_mfma_f32_16x16x32_bf16 v[90:93], v[240:243], v[196:199], v[90:93]
	v_mfma_f32_16x16x32_bf16 v[78:81], v[232:235], v[216:219], v[78:81]
	v_mfma_f32_16x16x32_bf16 v[74:77], v[240:243], v[216:219], v[74:77]
	v_mfma_f32_16x16x32_bf16 v[70:73], v[232:235], v[224:227], v[70:73]
	v_mfma_f32_16x16x32_bf16 v[66:69], v[240:243], v[224:227], v[66:69]
	s_mov_b32 m0, s58
	v_lshl_add_u64 v[244:245], s[72:73], 0, v[134:135]
	s_barrier
	ds_read_b128 v[160:163], v143 offset:16384
	ds_read_b128 v[188:191], v143 offset:17408
	ds_read_b128 v[192:195], v143 offset:18432
	ds_read_b128 v[196:199], v143 offset:19456
	ds_read_b128 v[200:203], v143 offset:20480
	ds_read_b128 v[216:219], v143 offset:21504
	ds_read_b128 v[220:223], v143 offset:22528
	ds_read_b128 v[224:227], v143 offset:23552
	global_load_lds_dwordx4 v[244:245], off
	v_lshl_add_u64 v[246:247], s[72:73], 0, v[132:133]
	s_mov_b32 m0, s74
	s_nop 0
	global_load_lds_dwordx4 v[246:247], off
	s_barrier
	s_waitcnt lgkmcnt(7)
	v_mfma_f32_16x16x32_bf16 v[62:65], v[144:147], v[160:163], v[62:65]
	v_mfma_f32_16x16x32_bf16 v[58:61], v[152:155], v[160:163], v[58:61]
	s_waitcnt lgkmcnt(3)
	v_mfma_f32_16x16x32_bf16 v[54:57], v[144:147], v[192:195], v[54:57]
	v_mfma_f32_16x16x32_bf16 v[50:53], v[152:155], v[192:195], v[50:53]
	v_mfma_f32_16x16x32_bf16 v[38:41], v[144:147], v[200:203], v[38:41]
	v_mfma_f32_16x16x32_bf16 v[34:37], v[152:155], v[200:203], v[34:37]
	s_waitcnt lgkmcnt(0)
	v_mfma_f32_16x16x32_bf16 v[22:25], v[144:147], v[220:223], v[22:25]
	v_mfma_f32_16x16x32_bf16 v[18:21], v[152:155], v[220:223], v[18:21]
	v_mfma_f32_16x16x32_bf16 v[62:65], v[148:151], v[188:191], v[62:65]
	v_mfma_f32_16x16x32_bf16 v[58:61], v[156:159], v[188:191], v[58:61]
	v_mfma_f32_16x16x32_bf16 v[54:57], v[148:151], v[196:199], v[54:57]
	v_mfma_f32_16x16x32_bf16 v[50:53], v[156:159], v[196:199], v[50:53]
	v_mfma_f32_16x16x32_bf16 v[38:41], v[148:151], v[216:219], v[38:41]
	v_mfma_f32_16x16x32_bf16 v[34:37], v[156:159], v[216:219], v[34:37]
	v_mfma_f32_16x16x32_bf16 v[22:25], v[148:151], v[224:227], v[22:25]
	v_mfma_f32_16x16x32_bf16 v[18:21], v[156:159], v[224:227], v[18:21]
	s_barrier
	s_add_u32 s44, s70, 0x80000
	s_addc_u32 s45, s71, 0
	s_add_i32 s2, s2, s3
	v_lshl_add_u64 v[144:145], s[44:45], 0, v[0:1]
	s_mov_b32 m0, s2
	s_nop 0
	global_load_lds_dwordx4 v[144:145], off
	v_lshl_add_u64 v[144:145], s[44:45], 0, v[130:131]
	s_add_i32 m0, s2, 0x2000
	s_nop 0
	global_load_lds_dwordx4 v[144:145], off
	s_waitcnt vmcnt(6)
	s_barrier
	v_mfma_f32_16x16x32_bf16 v[46:49], v[228:231], v[160:163], v[46:49]
	v_mfma_f32_16x16x32_bf16 v[42:45], v[236:239], v[160:163], v[42:45]
	v_mfma_f32_16x16x32_bf16 v[30:33], v[228:231], v[192:195], v[30:33]
	v_mfma_f32_16x16x32_bf16 v[26:29], v[236:239], v[192:195], v[26:29]
	v_mfma_f32_16x16x32_bf16 v[14:17], v[228:231], v[200:203], v[14:17]
	v_mfma_f32_16x16x32_bf16 v[10:13], v[236:239], v[200:203], v[10:13]
	v_mfma_f32_16x16x32_bf16 v[6:9], v[228:231], v[220:223], v[6:9]
	v_mfma_f32_16x16x32_bf16 v[2:5], v[236:239], v[220:223], v[2:5]
	v_mfma_f32_16x16x32_bf16 v[46:49], v[232:235], v[188:191], v[46:49]
	v_mfma_f32_16x16x32_bf16 v[42:45], v[240:243], v[188:191], v[42:45]
	v_mfma_f32_16x16x32_bf16 v[30:33], v[232:235], v[196:199], v[30:33]
	v_mfma_f32_16x16x32_bf16 v[26:29], v[240:243], v[196:199], v[26:29]
	v_mfma_f32_16x16x32_bf16 v[14:17], v[232:235], v[216:219], v[14:17]
	v_mfma_f32_16x16x32_bf16 v[10:13], v[240:243], v[216:219], v[10:13]
	v_mfma_f32_16x16x32_bf16 v[6:9], v[232:235], v[224:227], v[6:9]
	v_mfma_f32_16x16x32_bf16 v[2:5], v[240:243], v[224:227], v[2:5]
	s_add_i32 s2, 0, 0x18000
	v_add_u32_e32 v156, s2, v141
	s_barrier
	ds_read_b128 v[144:147], v156
	ds_read_b128 v[148:151], v156 offset:1024
	ds_read_b128 v[152:155], v156 offset:2048
	ds_read_b128 v[156:159], v156 offset:3072
	s_add_u32 s44, s72, 0x80000
	s_addc_u32 s45, s73, 0
	s_mov_b32 m0, s75
	v_lshl_add_u64 v[228:229], s[44:45], 0, v[134:135]
	ds_read_b128 v[160:163], v143 offset:32768
	ds_read_b128 v[188:191], v143 offset:33792
	ds_read_b128 v[192:195], v143 offset:34816
	ds_read_b128 v[196:199], v143 offset:35840
	ds_read_b128 v[200:203], v143 offset:36864
	ds_read_b128 v[216:219], v143 offset:37888
	ds_read_b128 v[220:223], v143 offset:38912
	ds_read_b128 v[224:227], v143 offset:39936
	global_load_lds_dwordx4 v[228:229], off
	v_lshl_add_u64 v[228:229], s[44:45], 0, v[132:133]
	s_mov_b32 m0, s77
	s_nop 0
	global_load_lds_dwordx4 v[228:229], off
	s_waitcnt lgkmcnt(8)
	s_barrier
	s_waitcnt lgkmcnt(7)
	v_mfma_f32_16x16x32_bf16 v[126:129], v[144:147], v[160:163], v[126:129]
	v_mfma_f32_16x16x32_bf16 v[122:125], v[152:155], v[160:163], v[122:125]
	s_waitcnt lgkmcnt(3)
	v_mfma_f32_16x16x32_bf16 v[118:121], v[144:147], v[192:195], v[118:121]
	v_mfma_f32_16x16x32_bf16 v[114:117], v[152:155], v[192:195], v[114:117]
	v_mfma_f32_16x16x32_bf16 v[102:105], v[144:147], v[200:203], v[102:105]
	v_mfma_f32_16x16x32_bf16 v[98:101], v[152:155], v[200:203], v[98:101]
	s_waitcnt lgkmcnt(0)
	v_mfma_f32_16x16x32_bf16 v[86:89], v[144:147], v[220:223], v[86:89]
	v_mfma_f32_16x16x32_bf16 v[82:85], v[152:155], v[220:223], v[82:85]
	v_mfma_f32_16x16x32_bf16 v[126:129], v[148:151], v[188:191], v[126:129]
	v_mfma_f32_16x16x32_bf16 v[122:125], v[156:159], v[188:191], v[122:125]
	v_mfma_f32_16x16x32_bf16 v[118:121], v[148:151], v[196:199], v[118:121]
	v_mfma_f32_16x16x32_bf16 v[114:117], v[156:159], v[196:199], v[114:117]
	v_mfma_f32_16x16x32_bf16 v[102:105], v[148:151], v[216:219], v[102:105]
	v_mfma_f32_16x16x32_bf16 v[98:101], v[156:159], v[216:219], v[98:101]
	v_mfma_f32_16x16x32_bf16 v[86:89], v[148:151], v[224:227], v[86:89]
	v_mfma_f32_16x16x32_bf16 v[82:85], v[156:159], v[224:227], v[82:85]
	s_barrier
	s_add_i32 s17, 0, 0x1c000
	s_add_i32 s2, s2, s3
	v_add_u32_e32 v206, s17, v141
	v_lshl_add_u64 v[164:165], v[164:165], 0, s[28:29]
	s_mov_b32 m0, s2
	ds_read_b128 v[228:231], v206
	ds_read_b128 v[232:235], v206 offset:1024
	ds_read_b128 v[236:239], v206 offset:2048
	ds_read_b128 v[240:243], v206 offset:3072
	global_load_lds_dwordx4 v[164:165], off
	v_lshl_add_u64 v[164:165], v[204:205], 0, s[28:29]
	s_add_i32 m0, s2, 0x2000
	s_nop 0
	global_load_lds_dwordx4 v[164:165], off
	s_barrier
	s_waitcnt lgkmcnt(1)
	v_mfma_f32_16x16x32_bf16 v[110:113], v[228:231], v[160:163], v[110:113]
	v_mfma_f32_16x16x32_bf16 v[106:109], v[236:239], v[160:163], v[106:109]
	v_mfma_f32_16x16x32_bf16 v[94:97], v[228:231], v[192:195], v[94:97]
	v_mfma_f32_16x16x32_bf16 v[90:93], v[236:239], v[192:195], v[90:93]
	v_mfma_f32_16x16x32_bf16 v[78:81], v[228:231], v[200:203], v[78:81]
	v_mfma_f32_16x16x32_bf16 v[74:77], v[236:239], v[200:203], v[74:77]
	s_waitcnt lgkmcnt(0)
	v_mfma_f32_16x16x32_bf16 v[70:73], v[228:231], v[220:223], v[70:73]
	v_mfma_f32_16x16x32_bf16 v[66:69], v[236:239], v[220:223], v[66:69]
	v_mfma_f32_16x16x32_bf16 v[110:113], v[232:235], v[188:191], v[110:113]
	v_mfma_f32_16x16x32_bf16 v[106:109], v[240:243], v[188:191], v[106:109]
	v_mfma_f32_16x16x32_bf16 v[94:97], v[232:235], v[196:199], v[94:97]
	v_mfma_f32_16x16x32_bf16 v[90:93], v[240:243], v[196:199], v[90:93]
	v_mfma_f32_16x16x32_bf16 v[78:81], v[232:235], v[216:219], v[78:81]
	v_mfma_f32_16x16x32_bf16 v[74:77], v[240:243], v[216:219], v[74:77]
	v_mfma_f32_16x16x32_bf16 v[70:73], v[232:235], v[224:227], v[70:73]
	v_mfma_f32_16x16x32_bf16 v[66:69], v[240:243], v[224:227], v[66:69]
	s_mov_b32 m0, s78
	v_lshl_add_u64 v[164:165], v[244:245], 0, s[28:29]
	s_barrier
	ds_read_b128 v[160:163], v143 offset:49152
	ds_read_b128 v[188:191], v143 offset:50176
	ds_read_b128 v[192:195], v143 offset:51200
	ds_read_b128 v[196:199], v143 offset:52224
	ds_read_b128 v[200:203], v143 offset:53248
	ds_read_b128 v[216:219], v143 offset:54272
	ds_read_b128 v[220:223], v143 offset:55296
	ds_read_b128 v[224:227], v143 offset:56320
	global_load_lds_dwordx4 v[164:165], off
	v_lshl_add_u64 v[164:165], v[246:247], 0, s[28:29]
	s_mov_b32 m0, s79
	s_nop 0
	global_load_lds_dwordx4 v[164:165], off
	s_barrier
	s_waitcnt lgkmcnt(7)
	v_mfma_f32_16x16x32_bf16 v[62:65], v[144:147], v[160:163], v[62:65]
	v_mfma_f32_16x16x32_bf16 v[58:61], v[152:155], v[160:163], v[58:61]
	s_waitcnt lgkmcnt(3)
	v_mfma_f32_16x16x32_bf16 v[54:57], v[144:147], v[192:195], v[54:57]
	v_mfma_f32_16x16x32_bf16 v[50:53], v[152:155], v[192:195], v[50:53]
	v_mfma_f32_16x16x32_bf16 v[38:41], v[144:147], v[200:203], v[38:41]
	v_mfma_f32_16x16x32_bf16 v[34:37], v[152:155], v[200:203], v[34:37]
	s_waitcnt lgkmcnt(0)
	v_mfma_f32_16x16x32_bf16 v[22:25], v[144:147], v[220:223], v[22:25]
	v_mfma_f32_16x16x32_bf16 v[18:21], v[152:155], v[220:223], v[18:21]
	v_mfma_f32_16x16x32_bf16 v[62:65], v[148:151], v[188:191], v[62:65]
	v_mfma_f32_16x16x32_bf16 v[58:61], v[156:159], v[188:191], v[58:61]
	v_mfma_f32_16x16x32_bf16 v[54:57], v[148:151], v[196:199], v[54:57]
	v_mfma_f32_16x16x32_bf16 v[50:53], v[156:159], v[196:199], v[50:53]
	v_mfma_f32_16x16x32_bf16 v[38:41], v[148:151], v[216:219], v[38:41]
	v_mfma_f32_16x16x32_bf16 v[34:37], v[156:159], v[216:219], v[34:37]
	v_mfma_f32_16x16x32_bf16 v[22:25], v[148:151], v[224:227], v[22:25]
	v_mfma_f32_16x16x32_bf16 v[18:21], v[156:159], v[224:227], v[18:21]
	s_barrier
	s_add_u32 s44, s70, 0x80080
	s_addc_u32 s45, s71, 0
	s_add_i32 s2, s17, s3
	v_lshl_add_u64 v[144:145], s[44:45], 0, v[0:1]
	s_mov_b32 m0, s2
	s_nop 0
	global_load_lds_dwordx4 v[144:145], off
	v_lshl_add_u64 v[144:145], s[44:45], 0, v[130:131]
	s_add_i32 m0, s2, 0x2000
	s_nop 0
	global_load_lds_dwordx4 v[144:145], off
	s_waitcnt vmcnt(6)
	s_barrier
	v_mfma_f32_16x16x32_bf16 v[46:49], v[228:231], v[160:163], v[46:49]
	v_mfma_f32_16x16x32_bf16 v[42:45], v[236:239], v[160:163], v[42:45]
	v_mfma_f32_16x16x32_bf16 v[30:33], v[228:231], v[192:195], v[30:33]
	v_mfma_f32_16x16x32_bf16 v[26:29], v[236:239], v[192:195], v[26:29]
	v_mfma_f32_16x16x32_bf16 v[14:17], v[228:231], v[200:203], v[14:17]
	v_mfma_f32_16x16x32_bf16 v[10:13], v[236:239], v[200:203], v[10:13]
	v_mfma_f32_16x16x32_bf16 v[6:9], v[228:231], v[220:223], v[6:9]
	v_mfma_f32_16x16x32_bf16 v[2:5], v[236:239], v[220:223], v[2:5]
	v_mfma_f32_16x16x32_bf16 v[46:49], v[232:235], v[188:191], v[46:49]
	v_mfma_f32_16x16x32_bf16 v[42:45], v[240:243], v[188:191], v[42:45]
	v_mfma_f32_16x16x32_bf16 v[30:33], v[232:235], v[196:199], v[30:33]
	v_mfma_f32_16x16x32_bf16 v[26:29], v[240:243], v[196:199], v[26:29]
	v_mfma_f32_16x16x32_bf16 v[14:17], v[232:235], v[216:219], v[14:17]
	v_mfma_f32_16x16x32_bf16 v[10:13], v[240:243], v[216:219], v[10:13]
	v_mfma_f32_16x16x32_bf16 v[6:9], v[232:235], v[224:227], v[6:9]
	v_mfma_f32_16x16x32_bf16 v[2:5], v[240:243], v[224:227], v[2:5]
	s_add_i32 s83, s83, 2
	s_add_u32 s68, s68, 0x100
	s_addc_u32 s69, s69, 0
	s_add_u32 s43, s43, 0x100
	s_addc_u32 s82, s82, 0
	s_cmp_gt_u32 s83, 29
	s_barrier
	s_cbranch_scc0 .LBB0_724
	v_lshl_add_u32 v146, s47, 8, v140
	v_lshl_or_b32 v144, s46, 8, v142
	v_cvt_pk_bf16_f32 v126, v126, v127
	v_cvt_pk_bf16_f32 v127, v128, v129
	v_cvt_pk_bf16_f32 v128, v122, v123
	v_mov_b64_e32 v[122:123], s[22:23]
	v_ashrrev_i32_e32 v145, 31, v144
	v_cvt_pk_bf16_f32 v70, v70, v71
	v_cvt_pk_bf16_f32 v71, v72, v73
	v_cvt_pk_bf16_f32 v72, v66, v67
	v_add_u32_e32 v66, 0x80, v146
	v_cvt_pk_bf16_f32 v129, v124, v125
	v_mad_i64_i32 v[124:125], s[24:25], v146, s48, v[122:123]
	v_lshlrev_b64 v[144:145], 1, v[144:145]
	v_cvt_pk_bf16_f32 v62, v62, v63
	v_cvt_pk_bf16_f32 v63, v64, v65
	v_cvt_pk_bf16_f32 v64, v58, v59
	v_mad_i64_i32 v[58:59], s[24:25], v66, s48, v[122:123]
	v_lshl_add_u64 v[124:125], v[124:125], 0, v[144:145]
	v_cvt_pk_bf16_f32 v110, v110, v111
	v_cvt_pk_bf16_f32 v111, v112, v113
	v_cvt_pk_bf16_f32 v112, v106, v107
	v_cvt_pk_bf16_f32 v113, v108, v109
	v_lshl_add_u64 v[58:59], v[58:59], 0, v[144:145]
	v_cvt_pk_bf16_f32 v46, v46, v47
	v_cvt_pk_bf16_f32 v47, v48, v49
	v_cvt_pk_bf16_f32 v48, v42, v43
	v_cvt_pk_bf16_f32 v49, v44, v45
	global_store_dwordx4 v[124:125], v[110:113], off offset:256
	global_store_dwordx4 v[58:59], v[46:49], off offset:256
	v_cvt_pk_bf16_f32 v94, v94, v95
	v_or_b32_e32 v110, 16, v146
	v_add_u32_e32 v46, 0x90, v146
	v_mad_i64_i32 v[110:111], s[24:25], v110, s48, v[122:123]
	v_mad_i64_i32 v[46:47], s[24:25], v46, s48, v[122:123]
	v_lshl_add_u64 v[110:111], v[110:111], 0, v[144:145]
	v_cvt_pk_bf16_f32 v95, v96, v97
	v_cvt_pk_bf16_f32 v96, v90, v91
	v_cvt_pk_bf16_f32 v97, v92, v93
	v_lshl_add_u64 v[46:47], v[46:47], 0, v[144:145]
	v_cvt_pk_bf16_f32 v30, v30, v31
	v_cvt_pk_bf16_f32 v31, v32, v33
	v_cvt_pk_bf16_f32 v32, v26, v27
	v_cvt_pk_bf16_f32 v33, v28, v29
	global_store_dwordx4 v[110:111], v[94:97], off offset:256
	global_store_dwordx4 v[46:47], v[30:33], off offset:256
	v_cvt_pk_bf16_f32 v78, v78, v79
	v_or_b32_e32 v94, 32, v146
	v_add_u32_e32 v30, 0xa0, v146
	v_mad_i64_i32 v[94:95], s[24:25], v94, s48, v[122:123]
	v_mad_i64_i32 v[30:31], s[24:25], v30, s48, v[122:123]
	v_lshl_add_u64 v[94:95], v[94:95], 0, v[144:145]
	v_cvt_pk_bf16_f32 v79, v80, v81
	v_cvt_pk_bf16_f32 v80, v74, v75
	v_cvt_pk_bf16_f32 v81, v76, v77
	v_lshl_add_u64 v[30:31], v[30:31], 0, v[144:145]
	v_cvt_pk_bf16_f32 v14, v14, v15
	v_cvt_pk_bf16_f32 v15, v16, v17
	v_cvt_pk_bf16_f32 v16, v10, v11
	v_cvt_pk_bf16_f32 v17, v12, v13
	global_store_dwordx4 v[94:95], v[78:81], off offset:256
	global_store_dwordx4 v[30:31], v[14:17], off offset:256
	v_cvt_pk_bf16_f32 v106, v118, v119
	v_or_b32_e32 v78, 48, v146
	v_add_u32_e32 v14, 0xb0, v146
	v_mad_i64_i32 v[78:79], s[24:25], v78, s48, v[122:123]
	v_mad_i64_i32 v[14:15], s[24:25], v14, s48, v[122:123]
	v_cvt_pk_bf16_f32 v107, v120, v121
	v_cvt_pk_bf16_f32 v108, v114, v115
	v_cvt_pk_bf16_f32 v109, v116, v117
	v_cvt_pk_bf16_f32 v90, v102, v103
	v_cvt_pk_bf16_f32 v91, v104, v105
	v_cvt_pk_bf16_f32 v92, v98, v99
	v_cvt_pk_bf16_f32 v93, v100, v101
	v_cvt_pk_bf16_f32 v74, v86, v87
	v_cvt_pk_bf16_f32 v75, v88, v89
	v_cvt_pk_bf16_f32 v76, v82, v83
	v_cvt_pk_bf16_f32 v77, v84, v85
	v_lshl_add_u64 v[78:79], v[78:79], 0, v[144:145]
	v_cvt_pk_bf16_f32 v73, v68, v69
	v_cvt_pk_bf16_f32 v65, v60, v61
	v_cvt_pk_bf16_f32 v42, v54, v55
	v_cvt_pk_bf16_f32 v43, v56, v57
	v_cvt_pk_bf16_f32 v44, v50, v51
	v_cvt_pk_bf16_f32 v45, v52, v53
	v_cvt_pk_bf16_f32 v26, v38, v39
	v_cvt_pk_bf16_f32 v27, v40, v41
	v_cvt_pk_bf16_f32 v28, v34, v35
	v_cvt_pk_bf16_f32 v29, v36, v37
	v_cvt_pk_bf16_f32 v10, v22, v23
	v_cvt_pk_bf16_f32 v11, v24, v25
	v_cvt_pk_bf16_f32 v12, v18, v19
	v_cvt_pk_bf16_f32 v13, v20, v21
	v_lshl_add_u64 v[14:15], v[14:15], 0, v[144:145]
	v_cvt_pk_bf16_f32 v6, v6, v7
	v_cvt_pk_bf16_f32 v7, v8, v9
	v_cvt_pk_bf16_f32 v8, v2, v3
	v_cvt_pk_bf16_f32 v9, v4, v5
	s_and_b64 vcc, exec, s[0:1]
	s_mov_b32 s46, s42
	s_mov_b32 s47, s54
	s_mov_b64 s[70:71], s[64:65]
	s_mov_b64 s[68:69], s[62:63]
	global_store_dwordx4 v[124:125], v[126:129], off
	global_store_dwordx4 v[110:111], v[106:109], off
	global_store_dwordx4 v[94:95], v[90:93], off
	global_store_dwordx4 v[78:79], v[74:77], off
	global_store_dwordx4 v[78:79], v[70:73], off offset:256
	global_store_dwordx4 v[58:59], v[62:65], off
	global_store_dwordx4 v[46:47], v[42:45], off
	global_store_dwordx4 v[30:31], v[26:29], off
	global_store_dwordx4 v[14:15], v[10:13], off
	global_store_dwordx4 v[14:15], v[6:9], off offset:256
	s_cbranch_vccz .LBB0_721
	v_readlane_b32 s0, v254, 12
	s_waitcnt vmcnt(0)
	v_readlane_b32 s1, v254, 13
	s_andn2_b64 vcc, exec, s[0:1]
	s_cbranch_vccnz .LBB0_728
	s_barrier

.LBB0_977:
	s_add_u32 s2, s70, 0xfffc0080
	s_addc_u32 s17, s71, -1
	s_add_i32 s26, 0, 0x10000
	v_add_u32_e32 v152, s26, v163
	ds_read_b128 v[130:133], v152
	ds_read_b128 v[134:137], v152 offset:1024
	ds_read_b128 v[148:151], v152 offset:2048
	ds_read_b128 v[152:155], v152 offset:3072
	s_cmp_eq_u32 s44, 12
	s_cselect_b32 s75, s41, s17
	s_cselect_b32 s74, s24, s2
	s_cselect_b32 s73, s25, vcc_hi
	s_cselect_b32 s72, s93, vcc_lo
	v_lshl_add_u64 v[160:161], s[70:71], 0, v[144:145]
	s_add_i32 m0, s58, 0xc000
	ds_read_b128 v[156:159], v165
	ds_read_b128 v[188:191], v165 offset:1024
	ds_read_b128 v[192:195], v165 offset:2048
	ds_read_b128 v[196:199], v165 offset:3072
	ds_read_b128 v[200:203], v165 offset:4096
	ds_read_b128 v[216:219], v165 offset:5120
	ds_read_b128 v[220:223], v165 offset:6144
	ds_read_b128 v[224:227], v165 offset:7168
	global_load_lds_dwordx4 v[160:161], off
	v_lshl_add_u64 v[160:161], s[70:71], 0, v[146:147]
	s_add_i32 m0, s58, 0xe000
	s_nop 0
	global_load_lds_dwordx4 v[160:161], off
	s_waitcnt lgkmcnt(8)
	s_barrier
	s_waitcnt lgkmcnt(7)
	v_mfma_f32_16x16x32_bf16 v[126:129], v[130:133], v[156:159], v[126:129]
	v_mfma_f32_16x16x32_bf16 v[122:125], v[148:151], v[156:159], v[122:125]
	s_waitcnt lgkmcnt(3)
	v_mfma_f32_16x16x32_bf16 v[110:113], v[130:133], v[192:195], v[110:113]
	v_mfma_f32_16x16x32_bf16 v[106:109], v[148:151], v[192:195], v[106:109]
	v_mfma_f32_16x16x32_bf16 v[94:97], v[130:133], v[200:203], v[94:97]
	v_mfma_f32_16x16x32_bf16 v[90:93], v[148:151], v[200:203], v[90:93]
	s_waitcnt lgkmcnt(0)
	v_mfma_f32_16x16x32_bf16 v[78:81], v[130:133], v[220:223], v[78:81]
	v_mfma_f32_16x16x32_bf16 v[74:77], v[148:151], v[220:223], v[74:77]
	v_mfma_f32_16x16x32_bf16 v[126:129], v[134:137], v[188:191], v[126:129]
	v_mfma_f32_16x16x32_bf16 v[122:125], v[152:155], v[188:191], v[122:125]
	v_mfma_f32_16x16x32_bf16 v[110:113], v[134:137], v[196:199], v[110:113]
	v_mfma_f32_16x16x32_bf16 v[106:109], v[152:155], v[196:199], v[106:109]
	v_mfma_f32_16x16x32_bf16 v[94:97], v[134:137], v[216:219], v[94:97]
	v_mfma_f32_16x16x32_bf16 v[90:93], v[152:155], v[216:219], v[90:93]
	v_mfma_f32_16x16x32_bf16 v[78:81], v[134:137], v[224:227], v[78:81]
	v_mfma_f32_16x16x32_bf16 v[74:77], v[152:155], v[224:227], v[74:77]
	s_barrier
	s_add_i32 s2, 0, 0x14000
	v_add_u32_e32 v160, s2, v163
	s_add_i32 s17, s26, s3
	ds_read_b128 v[228:231], v160
	ds_read_b128 v[232:235], v160 offset:1024
	ds_read_b128 v[236:239], v160 offset:2048
	ds_read_b128 v[240:243], v160 offset:3072
	v_lshl_add_u64 v[160:161], s[72:73], 0, v[0:1]
	s_mov_b32 m0, s17
	v_lshl_add_u64 v[204:205], s[72:73], 0, v[138:139]
	global_load_lds_dwordx4 v[160:161], off
	s_add_i32 m0, s17, 0x2000
	s_nop 0
	global_load_lds_dwordx4 v[204:205], off
	s_barrier
	s_waitcnt lgkmcnt(1)
	v_mfma_f32_16x16x32_bf16 v[118:121], v[228:231], v[156:159], v[118:121]
	v_mfma_f32_16x16x32_bf16 v[114:117], v[236:239], v[156:159], v[114:117]
	v_mfma_f32_16x16x32_bf16 v[102:105], v[228:231], v[192:195], v[102:105]
	v_mfma_f32_16x16x32_bf16 v[98:101], v[236:239], v[192:195], v[98:101]
	v_mfma_f32_16x16x32_bf16 v[86:89], v[228:231], v[200:203], v[86:89]
	v_mfma_f32_16x16x32_bf16 v[82:85], v[236:239], v[200:203], v[82:85]
	s_waitcnt lgkmcnt(0)
	v_mfma_f32_16x16x32_bf16 v[70:73], v[228:231], v[220:223], v[70:73]
	v_mfma_f32_16x16x32_bf16 v[66:69], v[236:239], v[220:223], v[66:69]
	v_mfma_f32_16x16x32_bf16 v[118:121], v[232:235], v[188:191], v[118:121]
	v_mfma_f32_16x16x32_bf16 v[114:117], v[240:243], v[188:191], v[114:117]
	v_mfma_f32_16x16x32_bf16 v[102:105], v[232:235], v[196:199], v[102:105]
	v_mfma_f32_16x16x32_bf16 v[98:101], v[240:243], v[196:199], v[98:101]
	v_mfma_f32_16x16x32_bf16 v[86:89], v[232:235], v[216:219], v[86:89]
	v_mfma_f32_16x16x32_bf16 v[82:85], v[240:243], v[216:219], v[82:85]
	v_mfma_f32_16x16x32_bf16 v[70:73], v[232:235], v[224:227], v[70:73]
	v_mfma_f32_16x16x32_bf16 v[66:69], v[240:243], v[224:227], v[66:69]
	s_mov_b32 m0, s58
	v_lshl_add_u64 v[244:245], s[74:75], 0, v[142:143]
	s_barrier
	ds_read_b128 v[156:159], v165 offset:16384
	ds_read_b128 v[188:191], v165 offset:17408
	ds_read_b128 v[192:195], v165 offset:18432
	ds_read_b128 v[196:199], v165 offset:19456
	ds_read_b128 v[200:203], v165 offset:20480
	ds_read_b128 v[216:219], v165 offset:21504
	ds_read_b128 v[220:223], v165 offset:22528
	ds_read_b128 v[224:227], v165 offset:23552
	global_load_lds_dwordx4 v[244:245], off
	v_lshl_add_u64 v[246:247], s[74:75], 0, v[140:141]
	s_mov_b32 m0, s76
	s_nop 0
	global_load_lds_dwordx4 v[246:247], off
	s_barrier
	s_waitcnt lgkmcnt(7)
	v_mfma_f32_16x16x32_bf16 v[62:65], v[130:133], v[156:159], v[62:65]
	v_mfma_f32_16x16x32_bf16 v[58:61], v[148:151], v[156:159], v[58:61]
	s_waitcnt lgkmcnt(3)
	v_mfma_f32_16x16x32_bf16 v[46:49], v[130:133], v[192:195], v[46:49]
	v_mfma_f32_16x16x32_bf16 v[42:45], v[148:151], v[192:195], v[42:45]
	v_mfma_f32_16x16x32_bf16 v[30:33], v[130:133], v[200:203], v[30:33]
	v_mfma_f32_16x16x32_bf16 v[26:29], v[148:151], v[200:203], v[26:29]
	s_waitcnt lgkmcnt(0)
	v_mfma_f32_16x16x32_bf16 v[14:17], v[130:133], v[220:223], v[14:17]
	v_mfma_f32_16x16x32_bf16 v[10:13], v[148:151], v[220:223], v[10:13]
	v_mfma_f32_16x16x32_bf16 v[62:65], v[134:137], v[188:191], v[62:65]
	v_mfma_f32_16x16x32_bf16 v[58:61], v[152:155], v[188:191], v[58:61]
	v_mfma_f32_16x16x32_bf16 v[46:49], v[134:137], v[196:199], v[46:49]
	v_mfma_f32_16x16x32_bf16 v[42:45], v[152:155], v[196:199], v[42:45]
	v_mfma_f32_16x16x32_bf16 v[30:33], v[134:137], v[216:219], v[30:33]
	v_mfma_f32_16x16x32_bf16 v[26:29], v[152:155], v[216:219], v[26:29]
	v_mfma_f32_16x16x32_bf16 v[14:17], v[134:137], v[224:227], v[14:17]
	v_mfma_f32_16x16x32_bf16 v[10:13], v[152:155], v[224:227], v[10:13]
	s_barrier
	s_add_u32 s26, s72, 0x40000
	s_addc_u32 s27, s73, 0
	s_add_i32 s2, s2, s3
	v_lshl_add_u64 v[130:131], s[26:27], 0, v[0:1]
	s_mov_b32 m0, s2
	s_nop 0
	global_load_lds_dwordx4 v[130:131], off
	v_lshl_add_u64 v[130:131], s[26:27], 0, v[138:139]
	s_add_i32 m0, s2, 0x2000
	s_nop 0
	global_load_lds_dwordx4 v[130:131], off
	s_waitcnt vmcnt(6)
	s_barrier
	v_mfma_f32_16x16x32_bf16 v[54:57], v[228:231], v[156:159], v[54:57]
	v_mfma_f32_16x16x32_bf16 v[50:53], v[236:239], v[156:159], v[50:53]
	v_mfma_f32_16x16x32_bf16 v[38:41], v[228:231], v[192:195], v[38:41]
	v_mfma_f32_16x16x32_bf16 v[34:37], v[236:239], v[192:195], v[34:37]
	v_mfma_f32_16x16x32_bf16 v[22:25], v[228:231], v[200:203], v[22:25]
	v_mfma_f32_16x16x32_bf16 v[18:21], v[236:239], v[200:203], v[18:21]
	v_mfma_f32_16x16x32_bf16 v[6:9], v[228:231], v[220:223], v[6:9]
	v_mfma_f32_16x16x32_bf16 v[2:5], v[236:239], v[220:223], v[2:5]
	v_mfma_f32_16x16x32_bf16 v[54:57], v[232:235], v[188:191], v[54:57]
	v_mfma_f32_16x16x32_bf16 v[50:53], v[240:243], v[188:191], v[50:53]
	v_mfma_f32_16x16x32_bf16 v[38:41], v[232:235], v[196:199], v[38:41]
	v_mfma_f32_16x16x32_bf16 v[34:37], v[240:243], v[196:199], v[34:37]
	v_mfma_f32_16x16x32_bf16 v[22:25], v[232:235], v[216:219], v[22:25]
	v_mfma_f32_16x16x32_bf16 v[18:21], v[240:243], v[216:219], v[18:21]
	v_mfma_f32_16x16x32_bf16 v[6:9], v[232:235], v[224:227], v[6:9]
	v_mfma_f32_16x16x32_bf16 v[2:5], v[240:243], v[224:227], v[2:5]
	s_add_i32 s2, 0, 0x18000
	v_add_u32_e32 v152, s2, v163
	s_barrier
	ds_read_b128 v[130:133], v152
	ds_read_b128 v[134:137], v152 offset:1024
	ds_read_b128 v[148:151], v152 offset:2048
	ds_read_b128 v[152:155], v152 offset:3072
	s_add_u32 s26, s74, 0x40000
	s_addc_u32 s27, s75, 0
	s_mov_b32 m0, s77
	v_lshl_add_u64 v[228:229], s[26:27], 0, v[142:143]
	ds_read_b128 v[156:159], v165 offset:32768
	ds_read_b128 v[188:191], v165 offset:33792
	ds_read_b128 v[192:195], v165 offset:34816
	ds_read_b128 v[196:199], v165 offset:35840
	ds_read_b128 v[200:203], v165 offset:36864
	ds_read_b128 v[216:219], v165 offset:37888
	ds_read_b128 v[220:223], v165 offset:38912
	ds_read_b128 v[224:227], v165 offset:39936
	global_load_lds_dwordx4 v[228:229], off
	v_lshl_add_u64 v[228:229], s[26:27], 0, v[140:141]
	s_mov_b32 m0, s78
	s_nop 0
	global_load_lds_dwordx4 v[228:229], off
	s_waitcnt lgkmcnt(8)
	s_barrier
	s_waitcnt lgkmcnt(7)
	v_mfma_f32_16x16x32_bf16 v[126:129], v[130:133], v[156:159], v[126:129]
	v_mfma_f32_16x16x32_bf16 v[122:125], v[148:151], v[156:159], v[122:125]
	s_waitcnt lgkmcnt(3)
	v_mfma_f32_16x16x32_bf16 v[110:113], v[130:133], v[192:195], v[110:113]
	v_mfma_f32_16x16x32_bf16 v[106:109], v[148:151], v[192:195], v[106:109]
	v_mfma_f32_16x16x32_bf16 v[94:97], v[130:133], v[200:203], v[94:97]
	v_mfma_f32_16x16x32_bf16 v[90:93], v[148:151], v[200:203], v[90:93]
	s_waitcnt lgkmcnt(0)
	v_mfma_f32_16x16x32_bf16 v[78:81], v[130:133], v[220:223], v[78:81]
	v_mfma_f32_16x16x32_bf16 v[74:77], v[148:151], v[220:223], v[74:77]
	v_mfma_f32_16x16x32_bf16 v[126:129], v[134:137], v[188:191], v[126:129]
	v_mfma_f32_16x16x32_bf16 v[122:125], v[152:155], v[188:191], v[122:125]
	v_mfma_f32_16x16x32_bf16 v[110:113], v[134:137], v[196:199], v[110:113]
	v_mfma_f32_16x16x32_bf16 v[106:109], v[152:155], v[196:199], v[106:109]
	v_mfma_f32_16x16x32_bf16 v[94:97], v[134:137], v[216:219], v[94:97]
	v_mfma_f32_16x16x32_bf16 v[90:93], v[152:155], v[216:219], v[90:93]
	v_mfma_f32_16x16x32_bf16 v[78:81], v[134:137], v[224:227], v[78:81]
	v_mfma_f32_16x16x32_bf16 v[74:77], v[152:155], v[224:227], v[74:77]
	s_barrier
	s_add_i32 s17, 0, 0x1c000
	s_add_i32 s2, s2, s3
	v_add_u32_e32 v206, s17, v163
	v_lshl_add_u64 v[160:161], v[160:161], 0, s[28:29]
	s_mov_b32 m0, s2
	ds_read_b128 v[228:231], v206
	ds_read_b128 v[232:235], v206 offset:1024
	ds_read_b128 v[236:239], v206 offset:2048
	ds_read_b128 v[240:243], v206 offset:3072
	global_load_lds_dwordx4 v[160:161], off
	v_lshl_add_u64 v[160:161], v[204:205], 0, s[28:29]
	s_add_i32 m0, s2, 0x2000
	s_nop 0
	global_load_lds_dwordx4 v[160:161], off
	s_barrier
	s_waitcnt lgkmcnt(1)
	v_mfma_f32_16x16x32_bf16 v[118:121], v[228:231], v[156:159], v[118:121]
	v_mfma_f32_16x16x32_bf16 v[114:117], v[236:239], v[156:159], v[114:117]
	v_mfma_f32_16x16x32_bf16 v[102:105], v[228:231], v[192:195], v[102:105]
	v_mfma_f32_16x16x32_bf16 v[98:101], v[236:239], v[192:195], v[98:101]
	v_mfma_f32_16x16x32_bf16 v[86:89], v[228:231], v[200:203], v[86:89]
	v_mfma_f32_16x16x32_bf16 v[82:85], v[236:239], v[200:203], v[82:85]
	s_waitcnt lgkmcnt(0)
	v_mfma_f32_16x16x32_bf16 v[70:73], v[228:231], v[220:223], v[70:73]
	v_mfma_f32_16x16x32_bf16 v[66:69], v[236:239], v[220:223], v[66:69]
	v_mfma_f32_16x16x32_bf16 v[118:121], v[232:235], v[188:191], v[118:121]
	v_mfma_f32_16x16x32_bf16 v[114:117], v[240:243], v[188:191], v[114:117]
	v_mfma_f32_16x16x32_bf16 v[102:105], v[232:235], v[196:199], v[102:105]
	v_mfma_f32_16x16x32_bf16 v[98:101], v[240:243], v[196:199], v[98:101]
	v_mfma_f32_16x16x32_bf16 v[86:89], v[232:235], v[216:219], v[86:89]
	v_mfma_f32_16x16x32_bf16 v[82:85], v[240:243], v[216:219], v[82:85]
	v_mfma_f32_16x16x32_bf16 v[70:73], v[232:235], v[224:227], v[70:73]
	v_mfma_f32_16x16x32_bf16 v[66:69], v[240:243], v[224:227], v[66:69]
	s_mov_b32 m0, s79
	v_lshl_add_u64 v[160:161], v[244:245], 0, s[28:29]
	s_barrier
	ds_read_b128 v[156:159], v165 offset:49152
	ds_read_b128 v[188:191], v165 offset:50176
	ds_read_b128 v[192:195], v165 offset:51200
	ds_read_b128 v[196:199], v165 offset:52224
	ds_read_b128 v[200:203], v165 offset:53248
	ds_read_b128 v[216:219], v165 offset:54272
	ds_read_b128 v[220:223], v165 offset:55296
	ds_read_b128 v[224:227], v165 offset:56320
	global_load_lds_dwordx4 v[160:161], off
	v_lshl_add_u64 v[160:161], v[246:247], 0, s[28:29]
	s_mov_b32 m0, s83
	s_nop 0
	global_load_lds_dwordx4 v[160:161], off
	s_barrier
	s_waitcnt lgkmcnt(7)
	v_mfma_f32_16x16x32_bf16 v[62:65], v[130:133], v[156:159], v[62:65]
	v_mfma_f32_16x16x32_bf16 v[58:61], v[148:151], v[156:159], v[58:61]
	s_waitcnt lgkmcnt(3)
	v_mfma_f32_16x16x32_bf16 v[46:49], v[130:133], v[192:195], v[46:49]
	v_mfma_f32_16x16x32_bf16 v[42:45], v[148:151], v[192:195], v[42:45]
	v_mfma_f32_16x16x32_bf16 v[30:33], v[130:133], v[200:203], v[30:33]
	v_mfma_f32_16x16x32_bf16 v[26:29], v[148:151], v[200:203], v[26:29]
	s_waitcnt lgkmcnt(0)
	v_mfma_f32_16x16x32_bf16 v[14:17], v[130:133], v[220:223], v[14:17]
	v_mfma_f32_16x16x32_bf16 v[10:13], v[148:151], v[220:223], v[10:13]
	v_mfma_f32_16x16x32_bf16 v[62:65], v[134:137], v[188:191], v[62:65]
	v_mfma_f32_16x16x32_bf16 v[58:61], v[152:155], v[188:191], v[58:61]
	v_mfma_f32_16x16x32_bf16 v[46:49], v[134:137], v[196:199], v[46:49]
	v_mfma_f32_16x16x32_bf16 v[42:45], v[152:155], v[196:199], v[42:45]
	v_mfma_f32_16x16x32_bf16 v[30:33], v[134:137], v[216:219], v[30:33]
	v_mfma_f32_16x16x32_bf16 v[26:29], v[152:155], v[216:219], v[26:29]
	v_mfma_f32_16x16x32_bf16 v[14:17], v[134:137], v[224:227], v[14:17]
	v_mfma_f32_16x16x32_bf16 v[10:13], v[152:155], v[224:227], v[10:13]
	s_barrier
	s_add_u32 s26, s72, 0x40080
	s_addc_u32 s27, s73, 0
	s_add_i32 s2, s17, s3
	v_lshl_add_u64 v[130:131], s[26:27], 0, v[0:1]
	s_mov_b32 m0, s2
	s_nop 0
	global_load_lds_dwordx4 v[130:131], off
	v_lshl_add_u64 v[130:131], s[26:27], 0, v[138:139]
	s_add_i32 m0, s2, 0x2000
	s_nop 0
	global_load_lds_dwordx4 v[130:131], off
	s_waitcnt vmcnt(6)
	s_barrier
	v_mfma_f32_16x16x32_bf16 v[54:57], v[228:231], v[156:159], v[54:57]
	v_mfma_f32_16x16x32_bf16 v[50:53], v[236:239], v[156:159], v[50:53]
	v_mfma_f32_16x16x32_bf16 v[38:41], v[228:231], v[192:195], v[38:41]
	v_mfma_f32_16x16x32_bf16 v[34:37], v[236:239], v[192:195], v[34:37]
	v_mfma_f32_16x16x32_bf16 v[22:25], v[228:231], v[200:203], v[22:25]
	v_mfma_f32_16x16x32_bf16 v[18:21], v[236:239], v[200:203], v[18:21]
	v_mfma_f32_16x16x32_bf16 v[6:9], v[228:231], v[220:223], v[6:9]
	v_mfma_f32_16x16x32_bf16 v[2:5], v[236:239], v[220:223], v[2:5]
	v_mfma_f32_16x16x32_bf16 v[54:57], v[232:235], v[188:191], v[54:57]
	v_mfma_f32_16x16x32_bf16 v[50:53], v[240:243], v[188:191], v[50:53]
	v_mfma_f32_16x16x32_bf16 v[38:41], v[232:235], v[196:199], v[38:41]
	v_mfma_f32_16x16x32_bf16 v[34:37], v[240:243], v[196:199], v[34:37]
	v_mfma_f32_16x16x32_bf16 v[22:25], v[232:235], v[216:219], v[22:25]
	v_mfma_f32_16x16x32_bf16 v[18:21], v[240:243], v[216:219], v[18:21]
	v_mfma_f32_16x16x32_bf16 v[6:9], v[232:235], v[224:227], v[6:9]
	v_mfma_f32_16x16x32_bf16 v[2:5], v[240:243], v[224:227], v[2:5]
	s_add_i32 s44, s44, 2
	s_add_u32 s70, s70, 0x100
	s_addc_u32 s71, s71, 0
	s_add_u32 vcc_lo, vcc_lo, 0x100
	s_addc_u32 vcc_hi, vcc_hi, 0
	s_cmp_gt_u32 s44, 13
	s_barrier
	s_cbranch_scc0 .LBB0_977
	v_lshl_add_u32 v152, s47, 8, v162
	v_lshl_or_b32 v130, s46, 8, v164
	v_ashrrev_i32_e32 v153, 31, v152
	v_lshlrev_b64 v[136:137], 11, v[152:153]
	v_ashrrev_i32_e32 v131, 31, v130
	v_lshl_add_u64 v[136:137], s[56:57], 0, v[136:137]
	v_lshlrev_b64 v[150:151], 1, v[130:131]
	v_mov_b64_e32 v[154:155], s[22:23]
	v_lshl_add_u64 v[156:157], v[136:137], 0, v[150:151]
	v_mad_i64_i32 v[136:137], s[24:25], v152, s48, v[154:155]
	v_lshl_add_u64 v[160:161], v[136:137], 0, s[94:95]
	v_lshl_add_u64 v[148:149], v[130:131], 2, s[54:55]
	v_lshl_add_u64 v[136:137], v[160:161], 0, v[150:151]
	global_load_dwordx4 v[132:135], v[148:149], off offset:16
	global_load_dwordx4 v[188:191], v[148:149], off
	global_load_dwordx4 v[192:195], v[156:157], off
	global_load_dwordx4 v[196:199], v[136:137], off
	s_and_b64 vcc, exec, s[6:7]
	s_mov_b32 s46, s92
	s_mov_b32 s47, s40
	s_mov_b64 s[72:73], s[68:69]
	s_mov_b64 s[70:71], s[42:43]
	v_readlane_b32 s93, v251, 60
	s_waitcnt vmcnt(0)
	v_add_f32_e32 v122, v122, v132
	v_add_f32_e32 v126, v126, v188
	v_add_f32_e32 v127, v127, v189
	v_lshlrev_b32_e32 v158, 16, v196
	v_mul_f32_e32 v131, 0xbfb8aa3b, v158
	v_exp_f32_e32 v131, v131
	v_and_b32_e32 v159, 0xffff0000, v196
	v_mul_f32_e32 v126, 0xbfb8aa3b, v126
	v_mul_f32_e32 v127, 0xbfb8aa3b, v127
	v_add_f32_e32 v131, 1.0, v131
	v_rcp_f32_e32 v188, v131
	v_mul_f32_e32 v131, 0xbfb8aa3b, v159
	v_exp_f32_e32 v126, v126
	v_exp_f32_e32 v127, v127
	v_exp_f32_e32 v131, v131
	v_lshlrev_b32_e32 v136, 16, v192
	v_add_f32_e32 v126, 1.0, v126
	v_add_f32_e32 v127, 1.0, v127
	v_add_f32_e32 v131, 1.0, v131
	v_rcp_f32_e32 v126, v126
	v_rcp_f32_e32 v127, v127
	v_rcp_f32_e32 v189, v131
	v_and_b32_e32 v137, 0xffff0000, v192
	v_add_f32_e32 v123, v123, v133
	v_pk_mul_f32 v[126:127], v[126:127], v[136:137]
	v_pk_mul_f32 v[136:137], v[188:189], v[158:159]
	v_mul_f32_e32 v122, 0xbfb8aa3b, v122
	v_pk_mul_f32 v[126:127], v[126:127], v[136:137]
	v_lshlrev_b32_e32 v136, 16, v198
	v_mul_f32_e32 v131, 0xbfb8aa3b, v136
	v_exp_f32_e32 v131, v131
	v_and_b32_e32 v137, 0xffff0000, v198
	v_mul_f32_e32 v123, 0xbfb8aa3b, v123
	v_exp_f32_e32 v122, v122
	v_add_f32_e32 v131, 1.0, v131
	v_rcp_f32_e32 v158, v131
	v_mul_f32_e32 v131, 0xbfb8aa3b, v137
	v_exp_f32_e32 v123, v123
	v_exp_f32_e32 v131, v131
	v_add_f32_e32 v122, 1.0, v122
	v_rcp_f32_e32 v122, v122
	v_add_f32_e32 v123, 1.0, v123
	v_add_f32_e32 v131, 1.0, v131
	v_rcp_f32_e32 v123, v123
	v_rcp_f32_e32 v159, v131
	v_lshlrev_b32_e32 v132, 16, v194
	v_and_b32_e32 v133, 0xffff0000, v194
	v_pk_mul_f32 v[122:123], v[122:123], v[132:133]
	v_pk_mul_f32 v[132:133], v[158:159], v[136:137]
	v_lshlrev_b32_e32 v136, 16, v197
	v_pk_mul_f32 v[132:133], v[122:123], v[132:133]
	v_add_f32_e32 v123, v124, v134
	v_mul_f32_e32 v123, 0xbfb8aa3b, v123
	v_exp_f32_e32 v123, v123
	v_add_f32_e32 v122, v128, v190
	v_mul_f32_e32 v122, 0xbfb8aa3b, v122
	v_exp_f32_e32 v122, v122
	v_add_f32_e32 v123, 1.0, v123
	v_rcp_f32_e32 v124, v123
	v_add_f32_e32 v123, v129, v191
	v_mul_f32_e32 v123, 0xbfb8aa3b, v123
	v_exp_f32_e32 v123, v123
	v_add_f32_e32 v122, 1.0, v122
	v_rcp_f32_e32 v122, v122
	v_lshlrev_b32_e32 v128, 16, v193
	v_add_f32_e32 v123, 1.0, v123
	v_rcp_f32_e32 v123, v123
	v_and_b32_e32 v129, 0xffff0000, v193
	v_and_b32_e32 v137, 0xffff0000, v197
	v_mul_f32_e32 v131, 0xbfb8aa3b, v136
	v_pk_mul_f32 v[122:123], v[122:123], v[128:129]
	v_mul_f32_e32 v128, 0xbfb8aa3b, v137
	v_exp_f32_e32 v131, v131
	v_exp_f32_e32 v128, v128
	v_lshlrev_b32_e32 v134, 16, v199
	v_add_f32_e32 v131, 1.0, v131
	v_add_f32_e32 v128, 1.0, v128
	v_rcp_f32_e32 v158, v131
	v_rcp_f32_e32 v159, v128
	v_mul_f32_e32 v131, 0xbfb8aa3b, v134
	v_exp_f32_e32 v131, v131
	v_pk_mul_f32 v[128:129], v[158:159], v[136:137]
	s_nop 0
	v_pk_mul_f32 v[128:129], v[122:123], v[128:129]
	v_add_f32_e32 v122, v125, v135
	v_mul_f32_e32 v122, 0xbfb8aa3b, v122
	v_exp_f32_e32 v122, v122
	v_and_b32_e32 v123, 0xffff0000, v195
	v_and_b32_e32 v135, 0xffff0000, v199
	v_add_f32_e32 v131, 1.0, v131
	v_add_f32_e32 v122, 1.0, v122
	v_rcp_f32_e32 v125, v122
	v_lshlrev_b32_e32 v122, 16, v195
	v_rcp_f32_e32 v136, v131
	v_pk_mul_f32 v[122:123], v[124:125], v[122:123]
	v_mul_f32_e32 v124, 0xbfb8aa3b, v135
	v_exp_f32_e32 v124, v124
	s_nop 0
	v_add_f32_e32 v124, 1.0, v124
	v_rcp_f32_e32 v137, v124
	s_nop 0
	v_pk_mul_f32 v[124:125], v[136:137], v[134:135]
	s_nop 0
	v_pk_mul_f32 v[134:135], v[122:123], v[124:125]
	v_cvt_pk_bf16_f32 v122, v126, v127
	v_lshlrev_b64 v[126:127], 12, v[152:153]
	v_lshl_add_u64 v[126:127], s[36:37], 0, v[126:127]
	v_cvt_pk_bf16_f32 v123, v128, v129
	v_cvt_pk_bf16_f32 v124, v132, v133
	v_cvt_pk_bf16_f32 v125, v134, v135
	v_lshl_add_u64 v[158:159], v[126:127], 0, v[150:151]
	v_or_b32_e32 v126, 0x80, v130
	global_store_dwordx4 v[158:159], v[122:125], off offset:2048
	v_ashrrev_i32_e32 v127, 31, v126
	global_load_dwordx4 v[130:133], v[148:149], off offset:528
	global_load_dwordx4 v[134:137], v[148:149], off offset:512
	global_load_dwordx4 v[122:125], v[156:157], off offset:256
	v_lshlrev_b64 v[156:157], 1, v[126:127]
	v_lshl_add_u64 v[126:127], v[160:161], 0, v[156:157]
	global_load_dwordx4 v[126:129], v[126:127], off
	s_waitcnt vmcnt(0)
	v_add_f32_e32 v114, v114, v130
	v_add_f32_e32 v118, v118, v134
	v_add_f32_e32 v119, v119, v135
	v_lshlrev_b32_e32 v134, 16, v122
	v_and_b32_e32 v135, 0xffff0000, v122
	v_lshlrev_b32_e32 v160, 16, v126
	v_mul_f32_e32 v122, 0xbfb8aa3b, v160
	v_exp_f32_e32 v122, v122
	v_and_b32_e32 v161, 0xffff0000, v126
	v_mul_f32_e32 v118, 0xbfb8aa3b, v118
	v_mul_f32_e32 v119, 0xbfb8aa3b, v119
	v_add_f32_e32 v122, 1.0, v122
	v_rcp_f32_e32 v188, v122
	v_mul_f32_e32 v122, 0xbfb8aa3b, v161
	v_exp_f32_e32 v118, v118
	v_exp_f32_e32 v119, v119
	v_exp_f32_e32 v122, v122
	v_add_f32_e32 v120, v120, v136
	v_add_f32_e32 v118, 1.0, v118
	v_add_f32_e32 v119, 1.0, v119
	v_add_f32_e32 v122, 1.0, v122
	v_rcp_f32_e32 v118, v118
	v_rcp_f32_e32 v119, v119
	v_rcp_f32_e32 v189, v122
	v_add_f32_e32 v121, v121, v137
	v_mul_f32_e32 v120, 0xbfb8aa3b, v120
	v_pk_mul_f32 v[118:119], v[118:119], v[134:135]
	v_pk_mul_f32 v[134:135], v[188:189], v[160:161]
	v_mul_f32_e32 v121, 0xbfb8aa3b, v121
	v_pk_mul_f32 v[118:119], v[118:119], v[134:135]
	v_lshlrev_b32_e32 v134, 16, v128
	v_mul_f32_e32 v122, 0xbfb8aa3b, v134
	v_exp_f32_e32 v122, v122
	v_exp_f32_e32 v120, v120
	v_exp_f32_e32 v121, v121
	v_and_b32_e32 v135, 0xffff0000, v128
	v_add_f32_e32 v122, 1.0, v122
	v_rcp_f32_e32 v160, v122
	v_mul_f32_e32 v122, 0xbfb8aa3b, v135
	v_add_f32_e32 v115, v115, v131
	v_exp_f32_e32 v122, v122
	v_mul_f32_e32 v114, 0xbfb8aa3b, v114
	v_mul_f32_e32 v115, 0xbfb8aa3b, v115
	v_add_f32_e32 v120, 1.0, v120
	v_add_f32_e32 v121, 1.0, v121
	v_exp_f32_e32 v114, v114
	v_exp_f32_e32 v115, v115
	v_rcp_f32_e32 v120, v120
	v_rcp_f32_e32 v121, v121
	v_add_f32_e32 v122, 1.0, v122
	v_rcp_f32_e32 v161, v122
	v_lshlrev_b32_e32 v122, 16, v123
	v_and_b32_e32 v123, 0xffff0000, v123
	v_lshlrev_b32_e32 v126, 16, v127
	v_and_b32_e32 v127, 0xffff0000, v127
	v_add_f32_e32 v114, 1.0, v114
	v_add_f32_e32 v115, 1.0, v115
	v_lshlrev_b32_e32 v130, 16, v124
	v_and_b32_e32 v131, 0xffff0000, v124
	v_mul_f32_e32 v124, 0xbfb8aa3b, v126
	v_pk_mul_f32 v[120:121], v[120:121], v[122:123]
	v_mul_f32_e32 v122, 0xbfb8aa3b, v127
	v_rcp_f32_e32 v114, v114
	v_rcp_f32_e32 v115, v115
	v_add_f32_e32 v116, v116, v132
	v_exp_f32_e32 v124, v124
	v_exp_f32_e32 v122, v122
	v_add_f32_e32 v117, v117, v133
	v_mul_f32_e32 v116, 0xbfb8aa3b, v116
	v_mul_f32_e32 v117, 0xbfb8aa3b, v117
	v_exp_f32_e32 v116, v116
	v_exp_f32_e32 v117, v117
	v_pk_mul_f32 v[114:115], v[114:115], v[130:131]
	v_pk_mul_f32 v[130:131], v[160:161], v[134:135]
	v_add_f32_e32 v124, 1.0, v124
	v_add_f32_e32 v122, 1.0, v122
	v_pk_mul_f32 v[114:115], v[114:115], v[130:131]
	v_rcp_f32_e32 v130, v124
	v_rcp_f32_e32 v131, v122
	v_add_f32_e32 v116, 1.0, v116
	v_add_f32_e32 v117, 1.0, v117
	v_rcp_f32_e32 v116, v116
	v_rcp_f32_e32 v117, v117
	v_pk_mul_f32 v[122:123], v[130:131], v[126:127]
	v_lshlrev_b32_e32 v124, 16, v129
	v_pk_mul_f32 v[120:121], v[120:121], v[122:123]
	v_lshlrev_b32_e32 v122, 16, v125
	v_and_b32_e32 v123, 0xffff0000, v125
	v_and_b32_e32 v125, 0xffff0000, v129
	v_mul_f32_e32 v126, 0xbfb8aa3b, v124
	v_pk_mul_f32 v[116:117], v[116:117], v[122:123]
	v_mul_f32_e32 v122, 0xbfb8aa3b, v125
	v_exp_f32_e32 v126, v126
	v_exp_f32_e32 v122, v122
	v_or_b32_e32 v132, 16, v152
	v_ashrrev_i32_e32 v133, 31, v132
	v_add_f32_e32 v126, 1.0, v126
	v_add_f32_e32 v122, 1.0, v122
	v_rcp_f32_e32 v126, v126
	v_rcp_f32_e32 v127, v122
	s_nop 0
	v_pk_mul_f32 v[122:123], v[126:127], v[124:125]
	s_nop 0
	v_pk_mul_f32 v[122:123], v[116:117], v[122:123]
	v_cvt_pk_bf16_f32 v116, v118, v119
	v_cvt_pk_bf16_f32 v117, v120, v121
	v_cvt_pk_bf16_f32 v118, v114, v115
	v_cvt_pk_bf16_f32 v119, v122, v123
	global_store_dwordx4 v[158:159], v[116:119], off offset:2304
	global_load_dwordx4 v[114:117], v[148:149], off offset:16
	s_nop 0
	global_load_dwordx4 v[120:123], v[148:149], off
	v_lshlrev_b64 v[118:119], 11, v[132:133]
	v_lshl_add_u64 v[118:119], s[56:57], 0, v[118:119]
	v_lshl_add_u64 v[134:135], v[118:119], 0, v[150:151]
	v_mad_i64_i32 v[118:119], s[24:25], v132, s48, v[154:155]
	v_lshl_add_u64 v[118:119], v[118:119], 0, s[94:95]
	v_lshl_add_u64 v[128:129], v[118:119], 0, v[150:151]
	global_load_dwordx4 v[124:127], v[134:135], off
	v_lshl_add_u64 v[118:119], v[118:119], 0, v[156:157]
	global_load_dwordx4 v[128:131], v[128:129], off
	s_waitcnt vmcnt(0)
	v_add_f32_e32 v106, v106, v114
	v_add_f32_e32 v110, v110, v120
	v_add_f32_e32 v111, v111, v121
	v_mul_f32_e32 v110, 0xbfb8aa3b, v110
	v_mul_f32_e32 v111, 0xbfb8aa3b, v111
	v_exp_f32_e32 v110, v110
	v_exp_f32_e32 v111, v111
	v_add_f32_e32 v107, v107, v115
	v_mul_f32_e32 v106, 0xbfb8aa3b, v106
	v_mul_f32_e32 v107, 0xbfb8aa3b, v107
	v_exp_f32_e32 v106, v106
	v_lshlrev_b32_e32 v136, 16, v128
	v_mul_f32_e32 v114, 0xbfb8aa3b, v136
	v_exp_f32_e32 v114, v114
	v_and_b32_e32 v137, 0xffff0000, v128
	v_exp_f32_e32 v107, v107
	v_add_f32_e32 v110, 1.0, v110
	v_add_f32_e32 v114, 1.0, v114
	v_rcp_f32_e32 v158, v114
	v_mul_f32_e32 v114, 0xbfb8aa3b, v137
	v_exp_f32_e32 v114, v114
	v_add_f32_e32 v111, 1.0, v111
	v_rcp_f32_e32 v110, v110
	v_rcp_f32_e32 v111, v111
	v_add_f32_e32 v114, 1.0, v114
	v_rcp_f32_e32 v159, v114
	v_add_f32_e32 v106, 1.0, v106
	v_add_f32_e32 v107, 1.0, v107
	v_rcp_f32_e32 v106, v106
	v_rcp_f32_e32 v107, v107
	v_lshlrev_b32_e32 v120, 16, v124
	v_and_b32_e32 v121, 0xffff0000, v124
	v_pk_mul_f32 v[110:111], v[110:111], v[120:121]
	v_pk_mul_f32 v[120:121], v[158:159], v[136:137]
	v_lshlrev_b32_e32 v114, 16, v126
	v_pk_mul_f32 v[110:111], v[110:111], v[120:121]
	v_and_b32_e32 v115, 0xffff0000, v126
	v_lshlrev_b32_e32 v120, 16, v130
	v_and_b32_e32 v121, 0xffff0000, v130
	v_mul_f32_e32 v124, 0xbfb8aa3b, v120
	v_pk_mul_f32 v[106:107], v[106:107], v[114:115]
	v_mul_f32_e32 v114, 0xbfb8aa3b, v121
	v_exp_f32_e32 v124, v124
	v_exp_f32_e32 v114, v114
	v_add_f32_e32 v124, 1.0, v124
	v_add_f32_e32 v114, 1.0, v114
	v_rcp_f32_e32 v136, v124
	v_rcp_f32_e32 v137, v114
	s_nop 0
	v_pk_mul_f32 v[114:115], v[136:137], v[120:121]
	s_nop 0
	v_pk_mul_f32 v[114:115], v[106:107], v[114:115]
	v_add_f32_e32 v107, v108, v116
	v_mul_f32_e32 v107, 0xbfb8aa3b, v107
	v_exp_f32_e32 v107, v107
	v_add_f32_e32 v106, v112, v122
	v_mul_f32_e32 v106, 0xbfb8aa3b, v106
	v_exp_f32_e32 v106, v106
	v_add_f32_e32 v107, 1.0, v107
	v_rcp_f32_e32 v108, v107
	v_add_f32_e32 v107, v113, v123
	v_mul_f32_e32 v107, 0xbfb8aa3b, v107
	v_exp_f32_e32 v107, v107
	v_add_f32_e32 v106, 1.0, v106
	v_rcp_f32_e32 v106, v106
	v_lshlrev_b32_e32 v112, 16, v125
	v_add_f32_e32 v107, 1.0, v107
	v_rcp_f32_e32 v107, v107
	v_and_b32_e32 v113, 0xffff0000, v125
	v_lshlrev_b32_e32 v120, 16, v129
	v_and_b32_e32 v121, 0xffff0000, v129
	v_mul_f32_e32 v116, 0xbfb8aa3b, v120
	v_pk_mul_f32 v[106:107], v[106:107], v[112:113]
	v_mul_f32_e32 v112, 0xbfb8aa3b, v121
	v_exp_f32_e32 v116, v116
	v_exp_f32_e32 v112, v112
	v_add_f32_e32 v116, 1.0, v116
	v_add_f32_e32 v112, 1.0, v112
	v_rcp_f32_e32 v122, v116
	v_rcp_f32_e32 v123, v112
	v_lshlrev_b32_e32 v116, 16, v131
	v_pk_mul_f32 v[112:113], v[122:123], v[120:121]
	s_nop 0
	v_pk_mul_f32 v[112:113], v[106:107], v[112:113]
	v_add_f32_e32 v106, v109, v117
	v_mul_f32_e32 v106, 0xbfb8aa3b, v106
	v_exp_f32_e32 v106, v106
	v_and_b32_e32 v107, 0xffff0000, v127
	v_and_b32_e32 v117, 0xffff0000, v131
	v_mul_f32_e32 v120, 0xbfb8aa3b, v116
	v_add_f32_e32 v106, 1.0, v106
	v_rcp_f32_e32 v109, v106
	v_lshlrev_b32_e32 v106, 16, v127
	v_exp_f32_e32 v120, v120
	v_pk_mul_f32 v[106:107], v[108:109], v[106:107]
	v_mul_f32_e32 v108, 0xbfb8aa3b, v117
	v_exp_f32_e32 v108, v108
	v_add_f32_e32 v120, 1.0, v120
	v_rcp_f32_e32 v120, v120
	v_add_f32_e32 v108, 1.0, v108
	v_rcp_f32_e32 v121, v108
	s_nop 0
	v_pk_mul_f32 v[108:109], v[120:121], v[116:117]
	s_nop 0
	v_pk_mul_f32 v[116:117], v[106:107], v[108:109]
	v_cvt_pk_bf16_f32 v106, v110, v111
	v_lshlrev_b64 v[110:111], 12, v[132:133]
	v_lshl_add_u64 v[110:111], s[36:37], 0, v[110:111]
	v_cvt_pk_bf16_f32 v107, v112, v113
	v_cvt_pk_bf16_f32 v108, v114, v115
	v_cvt_pk_bf16_f32 v109, v116, v117
	v_lshl_add_u64 v[122:123], v[110:111], 0, v[150:151]
	global_store_dwordx4 v[122:123], v[106:109], off offset:2048
	global_load_dwordx4 v[110:113], v[148:149], off offset:528
	global_load_dwordx4 v[114:117], v[148:149], off offset:512
	s_nop 0
	global_load_dwordx4 v[106:109], v[134:135], off offset:256
	s_waitcnt vmcnt(0)
	v_add_f32_e32 v98, v98, v110
	global_load_dwordx4 v[118:121], v[118:119], off
	v_add_f32_e32 v102, v102, v114
	v_add_f32_e32 v103, v103, v115
	v_lshlrev_b32_e32 v114, 16, v106
	v_and_b32_e32 v115, 0xffff0000, v106
	v_mul_f32_e32 v102, 0xbfb8aa3b, v102
	v_mul_f32_e32 v103, 0xbfb8aa3b, v103
	v_exp_f32_e32 v102, v102
	v_exp_f32_e32 v103, v103
	v_add_f32_e32 v99, v99, v111
	v_mul_f32_e32 v98, 0xbfb8aa3b, v98
	v_add_f32_e32 v102, 1.0, v102
	v_add_f32_e32 v103, 1.0, v103
	v_rcp_f32_e32 v102, v102
	v_rcp_f32_e32 v103, v103
	v_mul_f32_e32 v99, 0xbfb8aa3b, v99
	v_exp_f32_e32 v98, v98
	v_exp_f32_e32 v99, v99
	v_pk_mul_f32 v[102:103], v[102:103], v[114:115]
	v_lshlrev_b32_e32 v110, 16, v108
	v_add_f32_e32 v98, 1.0, v98
	v_add_f32_e32 v99, 1.0, v99
	v_rcp_f32_e32 v98, v98
	v_rcp_f32_e32 v99, v99
	v_and_b32_e32 v111, 0xffff0000, v108
	v_pk_mul_f32 v[98:99], v[98:99], v[110:111]
	s_waitcnt vmcnt(0)
	v_lshlrev_b32_e32 v124, 16, v118
	v_mul_f32_e32 v106, 0xbfb8aa3b, v124
	v_exp_f32_e32 v106, v106
	v_and_b32_e32 v125, 0xffff0000, v118
	v_or_b32_e32 v118, 32, v152
	v_add_f32_e32 v106, 1.0, v106
	v_rcp_f32_e32 v126, v106
	v_mul_f32_e32 v106, 0xbfb8aa3b, v125
	v_exp_f32_e32 v106, v106
	s_nop 0
	v_add_f32_e32 v106, 1.0, v106
	v_rcp_f32_e32 v127, v106
	s_nop 0
	v_pk_mul_f32 v[114:115], v[126:127], v[124:125]
	s_nop 0
	v_pk_mul_f32 v[102:103], v[102:103], v[114:115]
	v_lshlrev_b32_e32 v114, 16, v120
	v_mul_f32_e32 v106, 0xbfb8aa3b, v114
	v_exp_f32_e32 v106, v106
	v_and_b32_e32 v115, 0xffff0000, v120
	v_add_f32_e32 v106, 1.0, v106
	v_rcp_f32_e32 v124, v106
	v_mul_f32_e32 v106, 0xbfb8aa3b, v115
	v_exp_f32_e32 v106, v106
	s_nop 0
	v_add_f32_e32 v106, 1.0, v106
	v_rcp_f32_e32 v125, v106
	v_lshlrev_b32_e32 v106, 16, v119
	v_mul_f32_e32 v108, 0xbfb8aa3b, v106
	v_exp_f32_e32 v108, v108
	v_pk_mul_f32 v[110:111], v[124:125], v[114:115]
	v_add_f32_e32 v108, 1.0, v108
	v_pk_mul_f32 v[110:111], v[98:99], v[110:111]
	v_add_f32_e32 v99, v100, v112
	v_mul_f32_e32 v99, 0xbfb8aa3b, v99
	v_exp_f32_e32 v99, v99
	v_add_f32_e32 v98, v104, v116
	v_mul_f32_e32 v98, 0xbfb8aa3b, v98
	v_exp_f32_e32 v98, v98
	v_add_f32_e32 v99, 1.0, v99
	v_rcp_f32_e32 v100, v99
	v_add_f32_e32 v99, v105, v117
	v_mul_f32_e32 v99, 0xbfb8aa3b, v99
	v_exp_f32_e32 v99, v99
	v_add_f32_e32 v98, 1.0, v98
	v_rcp_f32_e32 v98, v98
	v_lshlrev_b32_e32 v104, 16, v107
	v_add_f32_e32 v99, 1.0, v99
	v_rcp_f32_e32 v99, v99
	v_and_b32_e32 v105, 0xffff0000, v107
	v_and_b32_e32 v107, 0xffff0000, v119
	v_rcp_f32_e32 v114, v108
	v_pk_mul_f32 v[98:99], v[98:99], v[104:105]
	v_mul_f32_e32 v104, 0xbfb8aa3b, v107
	v_exp_f32_e32 v104, v104
	v_ashrrev_i32_e32 v119, 31, v118
	v_add_f32_e32 v104, 1.0, v104
	v_rcp_f32_e32 v115, v104
	s_nop 0
	v_pk_mul_f32 v[104:105], v[114:115], v[106:107]
	s_nop 0
	v_pk_mul_f32 v[104:105], v[98:99], v[104:105]
	v_add_f32_e32 v98, v101, v113
	v_mul_f32_e32 v98, 0xbfb8aa3b, v98
	v_exp_f32_e32 v98, v98
	v_and_b32_e32 v99, 0xffff0000, v109
	v_lshlrev_b32_e32 v106, 16, v121
	v_and_b32_e32 v107, 0xffff0000, v121
	v_add_f32_e32 v98, 1.0, v98
	v_rcp_f32_e32 v101, v98
	v_lshlrev_b32_e32 v98, 16, v109
	v_mul_f32_e32 v108, 0xbfb8aa3b, v106
	v_exp_f32_e32 v108, v108
	v_pk_mul_f32 v[98:99], v[100:101], v[98:99]
	v_mul_f32_e32 v100, 0xbfb8aa3b, v107
	v_exp_f32_e32 v100, v100
	v_add_f32_e32 v108, 1.0, v108
	v_rcp_f32_e32 v108, v108
	v_add_f32_e32 v100, 1.0, v100
	v_rcp_f32_e32 v109, v100
	s_nop 0
	v_pk_mul_f32 v[100:101], v[108:109], v[106:107]
	s_nop 0
	v_pk_mul_f32 v[106:107], v[98:99], v[100:101]
	v_cvt_pk_bf16_f32 v98, v102, v103
	v_cvt_pk_bf16_f32 v99, v104, v105
	v_cvt_pk_bf16_f32 v100, v110, v111
	v_cvt_pk_bf16_f32 v101, v106, v107
	global_store_dwordx4 v[122:123], v[98:101], off offset:2304
	global_load_dwordx4 v[102:105], v[148:149], off offset:16
	global_load_dwordx4 v[106:109], v[148:149], off
	v_lshlrev_b64 v[98:99], 11, v[118:119]
	v_lshl_add_u64 v[98:99], s[56:57], 0, v[98:99]
	v_lshl_add_u64 v[100:101], v[98:99], 0, v[150:151]
	v_mad_i64_i32 v[98:99], s[24:25], v118, s48, v[154:155]
	v_lshl_add_u64 v[98:99], v[98:99], 0, s[94:95]
	v_lshl_add_u64 v[114:115], v[98:99], 0, v[150:151]
	global_load_dwordx4 v[110:113], v[100:101], off
	v_lshl_add_u64 v[98:99], v[98:99], 0, v[156:157]
	global_load_dwordx4 v[114:117], v[114:115], off
	s_waitcnt vmcnt(0)
	v_add_f32_e32 v90, v90, v102
	v_add_f32_e32 v94, v94, v106
	v_add_f32_e32 v95, v95, v107
	v_mul_f32_e32 v94, 0xbfb8aa3b, v94
	v_mul_f32_e32 v95, 0xbfb8aa3b, v95
	v_exp_f32_e32 v94, v94
	v_exp_f32_e32 v95, v95
	v_add_f32_e32 v91, v91, v103
	v_mul_f32_e32 v90, 0xbfb8aa3b, v90
	v_mul_f32_e32 v91, 0xbfb8aa3b, v91
	v_exp_f32_e32 v90, v90
	v_lshlrev_b32_e32 v120, 16, v114
	v_mul_f32_e32 v102, 0xbfb8aa3b, v120
	v_exp_f32_e32 v102, v102
	v_and_b32_e32 v121, 0xffff0000, v114
	v_exp_f32_e32 v91, v91
	v_add_f32_e32 v94, 1.0, v94
	v_add_f32_e32 v102, 1.0, v102
	v_rcp_f32_e32 v122, v102
	v_mul_f32_e32 v102, 0xbfb8aa3b, v121
	v_exp_f32_e32 v102, v102
	v_add_f32_e32 v95, 1.0, v95
	v_rcp_f32_e32 v94, v94
	v_rcp_f32_e32 v95, v95
	v_add_f32_e32 v102, 1.0, v102
	v_rcp_f32_e32 v123, v102
	v_add_f32_e32 v90, 1.0, v90
	v_add_f32_e32 v91, 1.0, v91
	v_rcp_f32_e32 v90, v90
	v_rcp_f32_e32 v91, v91
	v_lshlrev_b32_e32 v106, 16, v110
	v_and_b32_e32 v107, 0xffff0000, v110
	v_pk_mul_f32 v[94:95], v[94:95], v[106:107]
	v_pk_mul_f32 v[106:107], v[122:123], v[120:121]
	v_lshlrev_b32_e32 v102, 16, v112
	v_pk_mul_f32 v[94:95], v[94:95], v[106:107]
	v_and_b32_e32 v103, 0xffff0000, v112
	v_lshlrev_b32_e32 v106, 16, v116
	v_and_b32_e32 v107, 0xffff0000, v116
	v_mul_f32_e32 v110, 0xbfb8aa3b, v106
	v_pk_mul_f32 v[90:91], v[90:91], v[102:103]
	v_mul_f32_e32 v102, 0xbfb8aa3b, v107
	v_exp_f32_e32 v110, v110
	v_exp_f32_e32 v102, v102
	v_add_f32_e32 v110, 1.0, v110
	v_add_f32_e32 v102, 1.0, v102
	v_rcp_f32_e32 v120, v110
	v_rcp_f32_e32 v121, v102
	s_nop 0
	v_pk_mul_f32 v[102:103], v[120:121], v[106:107]
	s_nop 0
	v_pk_mul_f32 v[102:103], v[90:91], v[102:103]
	v_add_f32_e32 v91, v92, v104
	v_mul_f32_e32 v91, 0xbfb8aa3b, v91
	v_exp_f32_e32 v91, v91
	v_add_f32_e32 v90, v96, v108
	v_mul_f32_e32 v90, 0xbfb8aa3b, v90
	v_exp_f32_e32 v90, v90
	v_add_f32_e32 v91, 1.0, v91
	v_rcp_f32_e32 v92, v91
	v_add_f32_e32 v91, v97, v109
	v_mul_f32_e32 v91, 0xbfb8aa3b, v91
	v_exp_f32_e32 v91, v91
	v_add_f32_e32 v90, 1.0, v90
	v_rcp_f32_e32 v90, v90
	v_lshlrev_b32_e32 v96, 16, v111
	v_add_f32_e32 v91, 1.0, v91
	v_rcp_f32_e32 v91, v91
	v_and_b32_e32 v97, 0xffff0000, v111
	v_lshlrev_b32_e32 v106, 16, v115
	v_and_b32_e32 v107, 0xffff0000, v115
	v_mul_f32_e32 v104, 0xbfb8aa3b, v106
	v_pk_mul_f32 v[90:91], v[90:91], v[96:97]
	v_mul_f32_e32 v96, 0xbfb8aa3b, v107
	v_exp_f32_e32 v104, v104
	v_exp_f32_e32 v96, v96
	v_add_f32_e32 v104, 1.0, v104
	v_add_f32_e32 v96, 1.0, v96
	v_rcp_f32_e32 v108, v104
	v_rcp_f32_e32 v109, v96
	v_lshlrev_b32_e32 v104, 16, v117
	v_pk_mul_f32 v[96:97], v[108:109], v[106:107]
	s_nop 0
	v_pk_mul_f32 v[96:97], v[90:91], v[96:97]
	v_add_f32_e32 v90, v93, v105
	v_mul_f32_e32 v90, 0xbfb8aa3b, v90
	v_exp_f32_e32 v90, v90
	v_and_b32_e32 v91, 0xffff0000, v113
	v_and_b32_e32 v105, 0xffff0000, v117
	v_mul_f32_e32 v106, 0xbfb8aa3b, v104
	v_add_f32_e32 v90, 1.0, v90
	v_rcp_f32_e32 v93, v90
	v_lshlrev_b32_e32 v90, 16, v113
	v_exp_f32_e32 v106, v106
	v_pk_mul_f32 v[90:91], v[92:93], v[90:91]
	v_mul_f32_e32 v92, 0xbfb8aa3b, v105
	v_exp_f32_e32 v92, v92
	v_add_f32_e32 v106, 1.0, v106
	v_rcp_f32_e32 v106, v106
	v_add_f32_e32 v92, 1.0, v92
	v_rcp_f32_e32 v107, v92
	s_nop 0
	v_pk_mul_f32 v[92:93], v[106:107], v[104:105]
	s_nop 0
	v_pk_mul_f32 v[104:105], v[90:91], v[92:93]
	v_cvt_pk_bf16_f32 v90, v94, v95
	v_lshlrev_b64 v[94:95], 12, v[118:119]
	v_lshl_add_u64 v[94:95], s[36:37], 0, v[94:95]
	v_cvt_pk_bf16_f32 v91, v96, v97
	v_cvt_pk_bf16_f32 v92, v102, v103
	v_cvt_pk_bf16_f32 v93, v104, v105
	v_lshl_add_u64 v[106:107], v[94:95], 0, v[150:151]
	global_store_dwordx4 v[106:107], v[90:93], off offset:2048
	global_load_dwordx4 v[90:93], v[148:149], off offset:528
	s_nop 0
	global_load_dwordx4 v[94:97], v[148:149], off offset:512
	global_load_dwordx4 v[102:105], v[100:101], off offset:256
	s_waitcnt vmcnt(0)
	v_add_f32_e32 v82, v82, v90
	global_load_dwordx4 v[98:101], v[98:99], off
	v_add_f32_e32 v86, v86, v94
	v_add_f32_e32 v87, v87, v95
	v_mul_f32_e32 v86, 0xbfb8aa3b, v86
	v_mul_f32_e32 v87, 0xbfb8aa3b, v87
	v_exp_f32_e32 v86, v86
	v_exp_f32_e32 v87, v87
	v_add_f32_e32 v83, v83, v91
	v_mul_f32_e32 v82, 0xbfb8aa3b, v82
	v_mul_f32_e32 v83, 0xbfb8aa3b, v83
	v_exp_f32_e32 v82, v82
	v_exp_f32_e32 v83, v83
	v_add_f32_e32 v86, 1.0, v86
	v_add_f32_e32 v87, 1.0, v87
	v_rcp_f32_e32 v86, v86
	v_rcp_f32_e32 v87, v87
	v_add_f32_e32 v82, 1.0, v82
	v_add_f32_e32 v83, 1.0, v83
	v_rcp_f32_e32 v82, v82
	v_rcp_f32_e32 v83, v83
	v_lshlrev_b32_e32 v94, 16, v102
	v_and_b32_e32 v95, 0xffff0000, v102
	v_pk_mul_f32 v[86:87], v[86:87], v[94:95]
	v_and_b32_e32 v91, 0xffff0000, v104
	v_or_b32_e32 v102, 48, v152
	s_waitcnt vmcnt(0)
	v_lshlrev_b32_e32 v108, 16, v98
	v_mul_f32_e32 v90, 0xbfb8aa3b, v108
	v_exp_f32_e32 v90, v90
	v_and_b32_e32 v109, 0xffff0000, v98
	v_add_f32_e32 v90, 1.0, v90
	v_rcp_f32_e32 v110, v90
	v_mul_f32_e32 v90, 0xbfb8aa3b, v109
	v_exp_f32_e32 v90, v90
	s_nop 0
	v_add_f32_e32 v90, 1.0, v90
	v_rcp_f32_e32 v111, v90
	v_lshlrev_b32_e32 v90, 16, v104
	v_pk_mul_f32 v[82:83], v[82:83], v[90:91]
	v_pk_mul_f32 v[94:95], v[110:111], v[108:109]
	s_nop 0
	v_pk_mul_f32 v[86:87], v[86:87], v[94:95]
	v_lshlrev_b32_e32 v94, 16, v100
	v_and_b32_e32 v95, 0xffff0000, v100
	v_mul_f32_e32 v98, 0xbfb8aa3b, v94
	v_mul_f32_e32 v90, 0xbfb8aa3b, v95
	v_exp_f32_e32 v98, v98
	v_exp_f32_e32 v90, v90
	v_add_f32_e32 v98, 1.0, v98
	v_add_f32_e32 v90, 1.0, v90
	v_rcp_f32_e32 v108, v98
	v_rcp_f32_e32 v109, v90
	s_nop 0
	v_pk_mul_f32 v[90:91], v[108:109], v[94:95]
	s_nop 0
	v_pk_mul_f32 v[90:91], v[82:83], v[90:91]
	v_add_f32_e32 v83, v84, v92
	v_mul_f32_e32 v83, 0xbfb8aa3b, v83
	v_exp_f32_e32 v83, v83
	v_add_f32_e32 v82, v88, v96
	v_mul_f32_e32 v82, 0xbfb8aa3b, v82
	v_exp_f32_e32 v82, v82
	v_add_f32_e32 v83, 1.0, v83
	v_rcp_f32_e32 v84, v83
	v_add_f32_e32 v83, v89, v97
	v_mul_f32_e32 v83, 0xbfb8aa3b, v83
	v_exp_f32_e32 v83, v83
	v_add_f32_e32 v82, 1.0, v82
	v_rcp_f32_e32 v82, v82
	v_lshlrev_b32_e32 v88, 16, v103
	v_add_f32_e32 v83, 1.0, v83
	v_rcp_f32_e32 v83, v83
	v_and_b32_e32 v89, 0xffff0000, v103
	v_lshlrev_b32_e32 v94, 16, v99
	v_and_b32_e32 v95, 0xffff0000, v99
	v_mul_f32_e32 v92, 0xbfb8aa3b, v94
	v_pk_mul_f32 v[82:83], v[82:83], v[88:89]
	v_mul_f32_e32 v88, 0xbfb8aa3b, v95
	v_exp_f32_e32 v92, v92
	v_exp_f32_e32 v88, v88
	v_ashrrev_i32_e32 v103, 31, v102
	v_add_f32_e32 v92, 1.0, v92
	v_add_f32_e32 v88, 1.0, v88
	v_rcp_f32_e32 v96, v92
	v_rcp_f32_e32 v97, v88
	v_lshlrev_b32_e32 v92, 16, v101
	v_pk_mul_f32 v[88:89], v[96:97], v[94:95]
	s_nop 0
	v_pk_mul_f32 v[88:89], v[82:83], v[88:89]
	v_add_f32_e32 v82, v85, v93
	v_mul_f32_e32 v82, 0xbfb8aa3b, v82
	v_exp_f32_e32 v82, v82
	v_and_b32_e32 v83, 0xffff0000, v105
	v_and_b32_e32 v93, 0xffff0000, v101
	v_mul_f32_e32 v94, 0xbfb8aa3b, v92
	v_add_f32_e32 v82, 1.0, v82
	v_rcp_f32_e32 v85, v82
	v_lshlrev_b32_e32 v82, 16, v105
	v_exp_f32_e32 v94, v94
	v_pk_mul_f32 v[82:83], v[84:85], v[82:83]
	v_mul_f32_e32 v84, 0xbfb8aa3b, v93
	v_exp_f32_e32 v84, v84
	v_add_f32_e32 v94, 1.0, v94
	v_rcp_f32_e32 v94, v94
	v_add_f32_e32 v84, 1.0, v84
	v_rcp_f32_e32 v95, v84
	s_nop 0
	v_pk_mul_f32 v[84:85], v[94:95], v[92:93]
	s_nop 0
	v_pk_mul_f32 v[92:93], v[82:83], v[84:85]
	v_cvt_pk_bf16_f32 v82, v86, v87
	v_cvt_pk_bf16_f32 v83, v88, v89
	v_cvt_pk_bf16_f32 v84, v90, v91
	v_cvt_pk_bf16_f32 v85, v92, v93
	global_store_dwordx4 v[106:107], v[82:85], off offset:2304
	global_load_dwordx4 v[86:89], v[148:149], off offset:16
	global_load_dwordx4 v[90:93], v[148:149], off
	v_lshlrev_b64 v[82:83], 11, v[102:103]
	v_lshl_add_u64 v[82:83], s[56:57], 0, v[82:83]
	v_lshl_add_u64 v[84:85], v[82:83], 0, v[150:151]
	v_mad_i64_i32 v[82:83], s[24:25], v102, s48, v[154:155]
	v_lshl_add_u64 v[82:83], v[82:83], 0, s[94:95]
	v_lshl_add_u64 v[98:99], v[82:83], 0, v[150:151]
	global_load_dwordx4 v[94:97], v[84:85], off
	v_lshl_add_u64 v[82:83], v[82:83], 0, v[156:157]
	global_load_dwordx4 v[98:101], v[98:99], off
	s_waitcnt vmcnt(0)
	v_add_f32_e32 v74, v74, v86
	v_add_f32_e32 v78, v78, v90
	v_add_f32_e32 v79, v79, v91
	v_mul_f32_e32 v78, 0xbfb8aa3b, v78
	v_mul_f32_e32 v79, 0xbfb8aa3b, v79
	v_exp_f32_e32 v78, v78
	v_exp_f32_e32 v79, v79
	v_add_f32_e32 v75, v75, v87
	v_mul_f32_e32 v74, 0xbfb8aa3b, v74
	v_mul_f32_e32 v75, 0xbfb8aa3b, v75
	v_exp_f32_e32 v74, v74
	v_lshlrev_b32_e32 v104, 16, v98
	v_mul_f32_e32 v86, 0xbfb8aa3b, v104
	v_exp_f32_e32 v86, v86
	v_and_b32_e32 v105, 0xffff0000, v98
	v_exp_f32_e32 v75, v75
	v_add_f32_e32 v78, 1.0, v78
	v_add_f32_e32 v86, 1.0, v86
	v_rcp_f32_e32 v106, v86
	v_mul_f32_e32 v86, 0xbfb8aa3b, v105
	v_exp_f32_e32 v86, v86
	v_add_f32_e32 v79, 1.0, v79
	v_rcp_f32_e32 v78, v78
	v_rcp_f32_e32 v79, v79
	v_add_f32_e32 v86, 1.0, v86
	v_rcp_f32_e32 v107, v86
	v_add_f32_e32 v74, 1.0, v74
	v_add_f32_e32 v75, 1.0, v75
	v_rcp_f32_e32 v74, v74
	v_rcp_f32_e32 v75, v75
	v_lshlrev_b32_e32 v90, 16, v94
	v_and_b32_e32 v91, 0xffff0000, v94
	v_pk_mul_f32 v[78:79], v[78:79], v[90:91]
	v_pk_mul_f32 v[90:91], v[106:107], v[104:105]
	v_lshlrev_b32_e32 v86, 16, v96
	v_pk_mul_f32 v[78:79], v[78:79], v[90:91]
	v_and_b32_e32 v87, 0xffff0000, v96
	v_lshlrev_b32_e32 v90, 16, v100
	v_and_b32_e32 v91, 0xffff0000, v100
	v_mul_f32_e32 v94, 0xbfb8aa3b, v90
	v_pk_mul_f32 v[74:75], v[74:75], v[86:87]
	v_mul_f32_e32 v86, 0xbfb8aa3b, v91
	v_exp_f32_e32 v94, v94
	v_exp_f32_e32 v86, v86
	v_add_f32_e32 v94, 1.0, v94
	v_add_f32_e32 v86, 1.0, v86
	v_rcp_f32_e32 v104, v94
	v_rcp_f32_e32 v105, v86
	s_nop 0
	v_pk_mul_f32 v[86:87], v[104:105], v[90:91]
	s_nop 0
	v_pk_mul_f32 v[86:87], v[74:75], v[86:87]
	v_add_f32_e32 v75, v76, v88
	v_mul_f32_e32 v75, 0xbfb8aa3b, v75
	v_exp_f32_e32 v75, v75
	v_add_f32_e32 v74, v80, v92
	v_mul_f32_e32 v74, 0xbfb8aa3b, v74
	v_exp_f32_e32 v74, v74
	v_add_f32_e32 v75, 1.0, v75
	v_rcp_f32_e32 v76, v75
	v_add_f32_e32 v75, v81, v93
	v_mul_f32_e32 v75, 0xbfb8aa3b, v75
	v_exp_f32_e32 v75, v75
	v_add_f32_e32 v74, 1.0, v74
	v_rcp_f32_e32 v74, v74
	v_lshlrev_b32_e32 v80, 16, v95
	v_add_f32_e32 v75, 1.0, v75
	v_rcp_f32_e32 v75, v75
	v_and_b32_e32 v81, 0xffff0000, v95
	v_lshlrev_b32_e32 v90, 16, v99
	v_and_b32_e32 v91, 0xffff0000, v99
	v_mul_f32_e32 v88, 0xbfb8aa3b, v90
	v_pk_mul_f32 v[74:75], v[74:75], v[80:81]
	v_mul_f32_e32 v80, 0xbfb8aa3b, v91
	v_exp_f32_e32 v88, v88
	v_exp_f32_e32 v80, v80
	v_add_f32_e32 v88, 1.0, v88
	v_add_f32_e32 v80, 1.0, v80
	v_rcp_f32_e32 v92, v88
	v_rcp_f32_e32 v93, v80
	v_lshlrev_b32_e32 v88, 16, v101
	v_pk_mul_f32 v[80:81], v[92:93], v[90:91]
	s_nop 0
	v_pk_mul_f32 v[80:81], v[74:75], v[80:81]
	v_add_f32_e32 v74, v77, v89
	v_mul_f32_e32 v74, 0xbfb8aa3b, v74
	v_exp_f32_e32 v74, v74
	v_and_b32_e32 v75, 0xffff0000, v97
	v_and_b32_e32 v89, 0xffff0000, v101
	v_mul_f32_e32 v90, 0xbfb8aa3b, v88
	v_add_f32_e32 v74, 1.0, v74
	v_rcp_f32_e32 v77, v74
	v_lshlrev_b32_e32 v74, 16, v97
	v_exp_f32_e32 v90, v90
	v_pk_mul_f32 v[74:75], v[76:77], v[74:75]
	v_mul_f32_e32 v76, 0xbfb8aa3b, v89
	v_exp_f32_e32 v76, v76
	v_add_f32_e32 v90, 1.0, v90
	v_rcp_f32_e32 v90, v90
	v_add_f32_e32 v76, 1.0, v76
	v_rcp_f32_e32 v91, v76
	s_nop 0
	v_pk_mul_f32 v[76:77], v[90:91], v[88:89]
	s_nop 0
	v_pk_mul_f32 v[88:89], v[74:75], v[76:77]
	v_cvt_pk_bf16_f32 v74, v78, v79
	v_lshlrev_b64 v[78:79], 12, v[102:103]
	v_lshl_add_u64 v[78:79], s[36:37], 0, v[78:79]
	v_cvt_pk_bf16_f32 v75, v80, v81
	v_cvt_pk_bf16_f32 v76, v86, v87
	v_cvt_pk_bf16_f32 v77, v88, v89
	v_lshl_add_u64 v[90:91], v[78:79], 0, v[150:151]
	global_store_dwordx4 v[90:91], v[74:77], off offset:2048
	global_load_dwordx4 v[74:77], v[148:149], off offset:528
	s_nop 0
	global_load_dwordx4 v[78:81], v[148:149], off offset:512
	global_load_dwordx4 v[86:89], v[84:85], off offset:256
	s_waitcnt vmcnt(0)
	v_add_f32_e32 v66, v66, v74
	global_load_dwordx4 v[82:85], v[82:83], off
	v_add_f32_e32 v70, v70, v78
	v_add_f32_e32 v71, v71, v79
	v_mul_f32_e32 v70, 0xbfb8aa3b, v70
	v_mul_f32_e32 v71, 0xbfb8aa3b, v71
	v_exp_f32_e32 v70, v70
	v_exp_f32_e32 v71, v71
	v_add_f32_e32 v67, v67, v75
	v_mul_f32_e32 v66, 0xbfb8aa3b, v66
	v_mul_f32_e32 v67, 0xbfb8aa3b, v67
	v_exp_f32_e32 v66, v66
	v_exp_f32_e32 v67, v67
	v_add_f32_e32 v70, 1.0, v70
	v_add_f32_e32 v71, 1.0, v71
	v_rcp_f32_e32 v70, v70
	v_rcp_f32_e32 v71, v71
	v_add_f32_e32 v66, 1.0, v66
	v_add_f32_e32 v67, 1.0, v67
	v_rcp_f32_e32 v66, v66
	v_rcp_f32_e32 v67, v67
	v_lshlrev_b32_e32 v78, 16, v86
	v_and_b32_e32 v79, 0xffff0000, v86
	v_pk_mul_f32 v[70:71], v[70:71], v[78:79]
	v_and_b32_e32 v75, 0xffff0000, v88
	v_add_u32_e32 v86, 0x80, v152
	s_waitcnt vmcnt(0)
	v_lshlrev_b32_e32 v92, 16, v82
	v_mul_f32_e32 v74, 0xbfb8aa3b, v92
	v_exp_f32_e32 v74, v74
	v_and_b32_e32 v93, 0xffff0000, v82
	v_add_f32_e32 v74, 1.0, v74
	v_rcp_f32_e32 v94, v74
	v_mul_f32_e32 v74, 0xbfb8aa3b, v93
	v_exp_f32_e32 v74, v74
	s_nop 0
	v_add_f32_e32 v74, 1.0, v74
	v_rcp_f32_e32 v95, v74
	v_lshlrev_b32_e32 v74, 16, v88
	v_pk_mul_f32 v[66:67], v[66:67], v[74:75]
	v_pk_mul_f32 v[78:79], v[94:95], v[92:93]
	s_nop 0
	v_pk_mul_f32 v[70:71], v[70:71], v[78:79]
	v_lshlrev_b32_e32 v78, 16, v84
	v_and_b32_e32 v79, 0xffff0000, v84
	v_mul_f32_e32 v82, 0xbfb8aa3b, v78
	v_mul_f32_e32 v74, 0xbfb8aa3b, v79
	v_exp_f32_e32 v82, v82
	v_exp_f32_e32 v74, v74
	v_add_f32_e32 v82, 1.0, v82
	v_add_f32_e32 v74, 1.0, v74
	v_rcp_f32_e32 v92, v82
	v_rcp_f32_e32 v93, v74
	s_nop 0
	v_pk_mul_f32 v[74:75], v[92:93], v[78:79]
	s_nop 0
	v_pk_mul_f32 v[74:75], v[66:67], v[74:75]
	v_add_f32_e32 v67, v68, v76
	v_mul_f32_e32 v67, 0xbfb8aa3b, v67
	v_exp_f32_e32 v67, v67
	v_add_f32_e32 v66, v72, v80
	v_mul_f32_e32 v66, 0xbfb8aa3b, v66
	v_exp_f32_e32 v66, v66
	v_add_f32_e32 v67, 1.0, v67
	v_rcp_f32_e32 v68, v67
	v_add_f32_e32 v67, v73, v81
	v_mul_f32_e32 v67, 0xbfb8aa3b, v67
	v_exp_f32_e32 v67, v67
	v_add_f32_e32 v66, 1.0, v66
	v_rcp_f32_e32 v66, v66
	v_lshlrev_b32_e32 v72, 16, v87
	v_add_f32_e32 v67, 1.0, v67
	v_rcp_f32_e32 v67, v67
	v_and_b32_e32 v73, 0xffff0000, v87
	v_lshlrev_b32_e32 v78, 16, v83
	v_and_b32_e32 v79, 0xffff0000, v83
	v_mul_f32_e32 v76, 0xbfb8aa3b, v78
	v_pk_mul_f32 v[66:67], v[66:67], v[72:73]
	v_mul_f32_e32 v72, 0xbfb8aa3b, v79
	v_exp_f32_e32 v76, v76
	v_exp_f32_e32 v72, v72
	v_ashrrev_i32_e32 v87, 31, v86
	v_add_f32_e32 v76, 1.0, v76
	v_add_f32_e32 v72, 1.0, v72
	v_rcp_f32_e32 v80, v76
	v_rcp_f32_e32 v81, v72
	v_lshlrev_b32_e32 v76, 16, v85
	v_pk_mul_f32 v[72:73], v[80:81], v[78:79]
	s_nop 0
	v_pk_mul_f32 v[72:73], v[66:67], v[72:73]
	v_add_f32_e32 v66, v69, v77
	v_mul_f32_e32 v66, 0xbfb8aa3b, v66
	v_exp_f32_e32 v66, v66
	v_and_b32_e32 v67, 0xffff0000, v89
	v_and_b32_e32 v77, 0xffff0000, v85
	v_mul_f32_e32 v78, 0xbfb8aa3b, v76
	v_add_f32_e32 v66, 1.0, v66
	v_rcp_f32_e32 v69, v66
	v_lshlrev_b32_e32 v66, 16, v89
	v_exp_f32_e32 v78, v78
	v_pk_mul_f32 v[66:67], v[68:69], v[66:67]
	v_mul_f32_e32 v68, 0xbfb8aa3b, v77
	v_exp_f32_e32 v68, v68
	v_add_f32_e32 v78, 1.0, v78
	v_rcp_f32_e32 v78, v78
	v_add_f32_e32 v68, 1.0, v68
	v_rcp_f32_e32 v79, v68
	s_nop 0
	v_pk_mul_f32 v[68:69], v[78:79], v[76:77]
	s_nop 0
	v_pk_mul_f32 v[76:77], v[66:67], v[68:69]
	v_cvt_pk_bf16_f32 v66, v70, v71
	v_cvt_pk_bf16_f32 v67, v72, v73
	v_cvt_pk_bf16_f32 v68, v74, v75
	v_cvt_pk_bf16_f32 v69, v76, v77
	global_store_dwordx4 v[90:91], v[66:69], off offset:2304
	global_load_dwordx4 v[70:73], v[148:149], off offset:16
	global_load_dwordx4 v[74:77], v[148:149], off
	v_lshlrev_b64 v[66:67], 11, v[86:87]
	v_lshl_add_u64 v[66:67], s[56:57], 0, v[66:67]
	v_lshl_add_u64 v[68:69], v[66:67], 0, v[150:151]
	v_mad_i64_i32 v[66:67], s[24:25], v86, s48, v[154:155]
	v_lshl_add_u64 v[66:67], v[66:67], 0, s[94:95]
	v_lshl_add_u64 v[82:83], v[66:67], 0, v[150:151]
	global_load_dwordx4 v[78:81], v[68:69], off
	v_lshl_add_u64 v[66:67], v[66:67], 0, v[156:157]
	global_load_dwordx4 v[82:85], v[82:83], off
	s_waitcnt vmcnt(0)
	v_add_f32_e32 v58, v58, v70
	v_add_f32_e32 v62, v62, v74
	v_add_f32_e32 v63, v63, v75
	v_mul_f32_e32 v62, 0xbfb8aa3b, v62
	v_mul_f32_e32 v63, 0xbfb8aa3b, v63
	v_exp_f32_e32 v62, v62
	v_exp_f32_e32 v63, v63
	v_add_f32_e32 v59, v59, v71
	v_mul_f32_e32 v58, 0xbfb8aa3b, v58
	v_mul_f32_e32 v59, 0xbfb8aa3b, v59
	v_exp_f32_e32 v58, v58
	v_lshlrev_b32_e32 v88, 16, v82
	v_mul_f32_e32 v70, 0xbfb8aa3b, v88
	v_exp_f32_e32 v70, v70
	v_and_b32_e32 v89, 0xffff0000, v82
	v_exp_f32_e32 v59, v59
	v_add_f32_e32 v62, 1.0, v62
	v_add_f32_e32 v70, 1.0, v70
	v_rcp_f32_e32 v90, v70
	v_mul_f32_e32 v70, 0xbfb8aa3b, v89
	v_exp_f32_e32 v70, v70
	v_add_f32_e32 v63, 1.0, v63
	v_rcp_f32_e32 v62, v62
	v_rcp_f32_e32 v63, v63
	v_add_f32_e32 v70, 1.0, v70
	v_rcp_f32_e32 v91, v70
	v_add_f32_e32 v58, 1.0, v58
	v_add_f32_e32 v59, 1.0, v59
	v_rcp_f32_e32 v58, v58
	v_rcp_f32_e32 v59, v59
	v_lshlrev_b32_e32 v74, 16, v78
	v_and_b32_e32 v75, 0xffff0000, v78
	v_pk_mul_f32 v[62:63], v[62:63], v[74:75]
	v_pk_mul_f32 v[74:75], v[90:91], v[88:89]
	v_lshlrev_b32_e32 v70, 16, v80
	v_pk_mul_f32 v[62:63], v[62:63], v[74:75]
	v_and_b32_e32 v71, 0xffff0000, v80
	v_lshlrev_b32_e32 v74, 16, v84
	v_and_b32_e32 v75, 0xffff0000, v84
	v_mul_f32_e32 v78, 0xbfb8aa3b, v74
	v_pk_mul_f32 v[58:59], v[58:59], v[70:71]
	v_mul_f32_e32 v70, 0xbfb8aa3b, v75
	v_exp_f32_e32 v78, v78
	v_exp_f32_e32 v70, v70
	v_add_f32_e32 v78, 1.0, v78
	v_add_f32_e32 v70, 1.0, v70
	v_rcp_f32_e32 v88, v78
	v_rcp_f32_e32 v89, v70
	s_nop 0
	v_pk_mul_f32 v[70:71], v[88:89], v[74:75]
	s_nop 0
	v_pk_mul_f32 v[70:71], v[58:59], v[70:71]
	v_add_f32_e32 v59, v60, v72
	v_mul_f32_e32 v59, 0xbfb8aa3b, v59
	v_exp_f32_e32 v59, v59
	v_add_f32_e32 v58, v64, v76
	v_mul_f32_e32 v58, 0xbfb8aa3b, v58
	v_exp_f32_e32 v58, v58
	v_add_f32_e32 v59, 1.0, v59
	v_rcp_f32_e32 v60, v59
	v_add_f32_e32 v59, v65, v77
	v_mul_f32_e32 v59, 0xbfb8aa3b, v59
	v_exp_f32_e32 v59, v59
	v_add_f32_e32 v58, 1.0, v58
	v_rcp_f32_e32 v58, v58
	v_lshlrev_b32_e32 v64, 16, v79
	v_add_f32_e32 v59, 1.0, v59
	v_rcp_f32_e32 v59, v59
	v_and_b32_e32 v65, 0xffff0000, v79
	v_lshlrev_b32_e32 v74, 16, v83
	v_and_b32_e32 v75, 0xffff0000, v83
	v_mul_f32_e32 v72, 0xbfb8aa3b, v74
	v_pk_mul_f32 v[58:59], v[58:59], v[64:65]
	v_mul_f32_e32 v64, 0xbfb8aa3b, v75
	v_exp_f32_e32 v72, v72
	v_exp_f32_e32 v64, v64
	v_add_f32_e32 v72, 1.0, v72
	v_add_f32_e32 v64, 1.0, v64
	v_rcp_f32_e32 v76, v72
	v_rcp_f32_e32 v77, v64
	v_lshlrev_b32_e32 v72, 16, v85
	v_pk_mul_f32 v[64:65], v[76:77], v[74:75]
	s_nop 0
	v_pk_mul_f32 v[64:65], v[58:59], v[64:65]
	v_add_f32_e32 v58, v61, v73
	v_mul_f32_e32 v58, 0xbfb8aa3b, v58
	v_exp_f32_e32 v58, v58
	v_and_b32_e32 v59, 0xffff0000, v81
	v_and_b32_e32 v73, 0xffff0000, v85
	v_mul_f32_e32 v74, 0xbfb8aa3b, v72
	v_add_f32_e32 v58, 1.0, v58
	v_rcp_f32_e32 v61, v58
	v_lshlrev_b32_e32 v58, 16, v81
	v_exp_f32_e32 v74, v74
	v_pk_mul_f32 v[58:59], v[60:61], v[58:59]
	v_mul_f32_e32 v60, 0xbfb8aa3b, v73
	v_exp_f32_e32 v60, v60
	v_add_f32_e32 v74, 1.0, v74
	v_rcp_f32_e32 v74, v74
	v_add_f32_e32 v60, 1.0, v60
	v_rcp_f32_e32 v75, v60
	s_nop 0
	v_pk_mul_f32 v[60:61], v[74:75], v[72:73]
	s_nop 0
	v_pk_mul_f32 v[72:73], v[58:59], v[60:61]
	v_cvt_pk_bf16_f32 v58, v62, v63
	v_lshlrev_b64 v[62:63], 12, v[86:87]
	v_lshl_add_u64 v[62:63], s[36:37], 0, v[62:63]
	v_cvt_pk_bf16_f32 v59, v64, v65
	v_cvt_pk_bf16_f32 v60, v70, v71
	v_cvt_pk_bf16_f32 v61, v72, v73
	v_lshl_add_u64 v[74:75], v[62:63], 0, v[150:151]
	global_store_dwordx4 v[74:75], v[58:61], off offset:2048
	global_load_dwordx4 v[58:61], v[148:149], off offset:528
	s_nop 0
	global_load_dwordx4 v[62:65], v[148:149], off offset:512
	global_load_dwordx4 v[70:73], v[68:69], off offset:256
	s_waitcnt vmcnt(0)
	v_add_f32_e32 v50, v50, v58
	global_load_dwordx4 v[66:69], v[66:67], off
	v_add_f32_e32 v54, v54, v62
	v_add_f32_e32 v55, v55, v63
	v_mul_f32_e32 v54, 0xbfb8aa3b, v54
	v_mul_f32_e32 v55, 0xbfb8aa3b, v55
	v_exp_f32_e32 v54, v54
	v_exp_f32_e32 v55, v55
	v_add_f32_e32 v51, v51, v59
	v_mul_f32_e32 v50, 0xbfb8aa3b, v50
	v_mul_f32_e32 v51, 0xbfb8aa3b, v51
	v_exp_f32_e32 v50, v50
	v_exp_f32_e32 v51, v51
	v_add_f32_e32 v54, 1.0, v54
	v_add_f32_e32 v55, 1.0, v55
	v_rcp_f32_e32 v54, v54
	v_rcp_f32_e32 v55, v55
	v_add_f32_e32 v50, 1.0, v50
	v_add_f32_e32 v51, 1.0, v51
	v_rcp_f32_e32 v50, v50
	v_rcp_f32_e32 v51, v51
	v_lshlrev_b32_e32 v62, 16, v70
	v_and_b32_e32 v63, 0xffff0000, v70
	v_pk_mul_f32 v[54:55], v[54:55], v[62:63]
	v_and_b32_e32 v59, 0xffff0000, v72
	v_add_u32_e32 v70, 0x90, v152
	s_waitcnt vmcnt(0)
	v_lshlrev_b32_e32 v76, 16, v66
	v_mul_f32_e32 v58, 0xbfb8aa3b, v76
	v_exp_f32_e32 v58, v58
	v_and_b32_e32 v77, 0xffff0000, v66
	v_add_f32_e32 v58, 1.0, v58
	v_rcp_f32_e32 v78, v58
	v_mul_f32_e32 v58, 0xbfb8aa3b, v77
	v_exp_f32_e32 v58, v58
	s_nop 0
	v_add_f32_e32 v58, 1.0, v58
	v_rcp_f32_e32 v79, v58
	v_lshlrev_b32_e32 v58, 16, v72
	v_pk_mul_f32 v[50:51], v[50:51], v[58:59]
	v_pk_mul_f32 v[62:63], v[78:79], v[76:77]
	s_nop 0
	v_pk_mul_f32 v[54:55], v[54:55], v[62:63]
	v_lshlrev_b32_e32 v62, 16, v68
	v_and_b32_e32 v63, 0xffff0000, v68
	v_mul_f32_e32 v66, 0xbfb8aa3b, v62
	v_mul_f32_e32 v58, 0xbfb8aa3b, v63
	v_exp_f32_e32 v66, v66
	v_exp_f32_e32 v58, v58
	v_add_f32_e32 v66, 1.0, v66
	v_add_f32_e32 v58, 1.0, v58
	v_rcp_f32_e32 v76, v66
	v_rcp_f32_e32 v77, v58
	s_nop 0
	v_pk_mul_f32 v[58:59], v[76:77], v[62:63]
	s_nop 0
	v_pk_mul_f32 v[58:59], v[50:51], v[58:59]
	v_add_f32_e32 v51, v52, v60
	v_mul_f32_e32 v51, 0xbfb8aa3b, v51
	v_exp_f32_e32 v51, v51
	v_add_f32_e32 v50, v56, v64
	v_mul_f32_e32 v50, 0xbfb8aa3b, v50
	v_exp_f32_e32 v50, v50
	v_add_f32_e32 v51, 1.0, v51
	v_rcp_f32_e32 v52, v51
	v_add_f32_e32 v51, v57, v65
	v_mul_f32_e32 v51, 0xbfb8aa3b, v51
	v_exp_f32_e32 v51, v51
	v_add_f32_e32 v50, 1.0, v50
	v_rcp_f32_e32 v50, v50
	v_lshlrev_b32_e32 v56, 16, v71
	v_add_f32_e32 v51, 1.0, v51
	v_rcp_f32_e32 v51, v51
	v_and_b32_e32 v57, 0xffff0000, v71
	v_lshlrev_b32_e32 v62, 16, v67
	v_and_b32_e32 v63, 0xffff0000, v67
	v_mul_f32_e32 v60, 0xbfb8aa3b, v62
	v_pk_mul_f32 v[50:51], v[50:51], v[56:57]
	v_mul_f32_e32 v56, 0xbfb8aa3b, v63
	v_exp_f32_e32 v60, v60
	v_exp_f32_e32 v56, v56
	v_ashrrev_i32_e32 v71, 31, v70
	v_add_f32_e32 v60, 1.0, v60
	v_add_f32_e32 v56, 1.0, v56
	v_rcp_f32_e32 v64, v60
	v_rcp_f32_e32 v65, v56
	v_lshlrev_b32_e32 v60, 16, v69
	v_pk_mul_f32 v[56:57], v[64:65], v[62:63]
	s_nop 0
	v_pk_mul_f32 v[56:57], v[50:51], v[56:57]
	v_add_f32_e32 v50, v53, v61
	v_mul_f32_e32 v50, 0xbfb8aa3b, v50
	v_exp_f32_e32 v50, v50
	v_and_b32_e32 v51, 0xffff0000, v73
	v_and_b32_e32 v61, 0xffff0000, v69
	v_mul_f32_e32 v62, 0xbfb8aa3b, v60
	v_add_f32_e32 v50, 1.0, v50
	v_rcp_f32_e32 v53, v50
	v_lshlrev_b32_e32 v50, 16, v73
	v_exp_f32_e32 v62, v62
	v_pk_mul_f32 v[50:51], v[52:53], v[50:51]
	v_mul_f32_e32 v52, 0xbfb8aa3b, v61
	v_exp_f32_e32 v52, v52
	v_add_f32_e32 v62, 1.0, v62
	v_rcp_f32_e32 v62, v62
	v_add_f32_e32 v52, 1.0, v52
	v_rcp_f32_e32 v63, v52
	s_nop 0
	v_pk_mul_f32 v[52:53], v[62:63], v[60:61]
	s_nop 0
	v_pk_mul_f32 v[60:61], v[50:51], v[52:53]
	v_cvt_pk_bf16_f32 v50, v54, v55
	v_cvt_pk_bf16_f32 v51, v56, v57
	v_cvt_pk_bf16_f32 v52, v58, v59
	v_cvt_pk_bf16_f32 v53, v60, v61
	global_store_dwordx4 v[74:75], v[50:53], off offset:2304
	global_load_dwordx4 v[54:57], v[148:149], off offset:16
	global_load_dwordx4 v[58:61], v[148:149], off
	v_lshlrev_b64 v[50:51], 11, v[70:71]
	v_lshl_add_u64 v[50:51], s[56:57], 0, v[50:51]
	v_lshl_add_u64 v[52:53], v[50:51], 0, v[150:151]
	v_mad_i64_i32 v[50:51], s[24:25], v70, s48, v[154:155]
	v_lshl_add_u64 v[50:51], v[50:51], 0, s[94:95]
	v_lshl_add_u64 v[66:67], v[50:51], 0, v[150:151]
	global_load_dwordx4 v[62:65], v[52:53], off
	v_lshl_add_u64 v[50:51], v[50:51], 0, v[156:157]
	global_load_dwordx4 v[66:69], v[66:67], off
	s_waitcnt vmcnt(0)
	v_add_f32_e32 v42, v42, v54
	v_add_f32_e32 v46, v46, v58
	v_add_f32_e32 v47, v47, v59
	v_mul_f32_e32 v46, 0xbfb8aa3b, v46
	v_mul_f32_e32 v47, 0xbfb8aa3b, v47
	v_exp_f32_e32 v46, v46
	v_exp_f32_e32 v47, v47
	v_add_f32_e32 v43, v43, v55
	v_mul_f32_e32 v42, 0xbfb8aa3b, v42
	v_mul_f32_e32 v43, 0xbfb8aa3b, v43
	v_exp_f32_e32 v42, v42
	v_lshlrev_b32_e32 v72, 16, v66
	v_mul_f32_e32 v54, 0xbfb8aa3b, v72
	v_exp_f32_e32 v54, v54
	v_and_b32_e32 v73, 0xffff0000, v66
	v_exp_f32_e32 v43, v43
	v_add_f32_e32 v46, 1.0, v46
	v_add_f32_e32 v54, 1.0, v54
	v_rcp_f32_e32 v74, v54
	v_mul_f32_e32 v54, 0xbfb8aa3b, v73
	v_exp_f32_e32 v54, v54
	v_add_f32_e32 v47, 1.0, v47
	v_rcp_f32_e32 v46, v46
	v_rcp_f32_e32 v47, v47
	v_add_f32_e32 v54, 1.0, v54
	v_rcp_f32_e32 v75, v54
	v_add_f32_e32 v42, 1.0, v42
	v_add_f32_e32 v43, 1.0, v43
	v_rcp_f32_e32 v42, v42
	v_rcp_f32_e32 v43, v43
	v_lshlrev_b32_e32 v58, 16, v62
	v_and_b32_e32 v59, 0xffff0000, v62
	v_pk_mul_f32 v[46:47], v[46:47], v[58:59]
	v_pk_mul_f32 v[58:59], v[74:75], v[72:73]
	v_lshlrev_b32_e32 v54, 16, v64
	v_pk_mul_f32 v[46:47], v[46:47], v[58:59]
	v_and_b32_e32 v55, 0xffff0000, v64
	v_lshlrev_b32_e32 v58, 16, v68
	v_and_b32_e32 v59, 0xffff0000, v68
	v_mul_f32_e32 v62, 0xbfb8aa3b, v58
	v_pk_mul_f32 v[42:43], v[42:43], v[54:55]
	v_mul_f32_e32 v54, 0xbfb8aa3b, v59
	v_exp_f32_e32 v62, v62
	v_exp_f32_e32 v54, v54
	v_add_f32_e32 v62, 1.0, v62
	v_add_f32_e32 v54, 1.0, v54
	v_rcp_f32_e32 v72, v62
	v_rcp_f32_e32 v73, v54
	s_nop 0
	v_pk_mul_f32 v[54:55], v[72:73], v[58:59]
	s_nop 0
	v_pk_mul_f32 v[54:55], v[42:43], v[54:55]
	v_add_f32_e32 v43, v44, v56
	v_mul_f32_e32 v43, 0xbfb8aa3b, v43
	v_exp_f32_e32 v43, v43
	v_add_f32_e32 v42, v48, v60
	v_mul_f32_e32 v42, 0xbfb8aa3b, v42
	v_exp_f32_e32 v42, v42
	v_add_f32_e32 v43, 1.0, v43
	v_rcp_f32_e32 v44, v43
	v_add_f32_e32 v43, v49, v61
	v_mul_f32_e32 v43, 0xbfb8aa3b, v43
	v_exp_f32_e32 v43, v43
	v_add_f32_e32 v42, 1.0, v42
	v_rcp_f32_e32 v42, v42
	v_lshlrev_b32_e32 v48, 16, v63
	v_add_f32_e32 v43, 1.0, v43
	v_rcp_f32_e32 v43, v43
	v_and_b32_e32 v49, 0xffff0000, v63
	v_lshlrev_b32_e32 v58, 16, v67
	v_and_b32_e32 v59, 0xffff0000, v67
	v_mul_f32_e32 v56, 0xbfb8aa3b, v58
	v_pk_mul_f32 v[42:43], v[42:43], v[48:49]
	v_mul_f32_e32 v48, 0xbfb8aa3b, v59
	v_exp_f32_e32 v56, v56
	v_exp_f32_e32 v48, v48
	v_add_f32_e32 v56, 1.0, v56
	v_add_f32_e32 v48, 1.0, v48
	v_rcp_f32_e32 v60, v56
	v_rcp_f32_e32 v61, v48
	v_lshlrev_b32_e32 v56, 16, v69
	v_pk_mul_f32 v[48:49], v[60:61], v[58:59]
	s_nop 0
	v_pk_mul_f32 v[48:49], v[42:43], v[48:49]
	v_add_f32_e32 v42, v45, v57
	v_mul_f32_e32 v42, 0xbfb8aa3b, v42
	v_exp_f32_e32 v42, v42
	v_and_b32_e32 v43, 0xffff0000, v65
	v_and_b32_e32 v57, 0xffff0000, v69
	v_mul_f32_e32 v58, 0xbfb8aa3b, v56
	v_add_f32_e32 v42, 1.0, v42
	v_rcp_f32_e32 v45, v42
	v_lshlrev_b32_e32 v42, 16, v65
	v_exp_f32_e32 v58, v58
	v_pk_mul_f32 v[42:43], v[44:45], v[42:43]
	v_mul_f32_e32 v44, 0xbfb8aa3b, v57
	v_exp_f32_e32 v44, v44
	v_add_f32_e32 v58, 1.0, v58
	v_rcp_f32_e32 v58, v58
	v_add_f32_e32 v44, 1.0, v44
	v_rcp_f32_e32 v59, v44
	s_nop 0
	v_pk_mul_f32 v[44:45], v[58:59], v[56:57]
	s_nop 0
	v_pk_mul_f32 v[56:57], v[42:43], v[44:45]
	v_cvt_pk_bf16_f32 v42, v46, v47
	v_lshlrev_b64 v[46:47], 12, v[70:71]
	v_lshl_add_u64 v[46:47], s[36:37], 0, v[46:47]
	v_cvt_pk_bf16_f32 v43, v48, v49
	v_cvt_pk_bf16_f32 v44, v54, v55
	v_cvt_pk_bf16_f32 v45, v56, v57
	v_lshl_add_u64 v[58:59], v[46:47], 0, v[150:151]
	global_store_dwordx4 v[58:59], v[42:45], off offset:2048
	global_load_dwordx4 v[42:45], v[148:149], off offset:528
	s_nop 0
	global_load_dwordx4 v[46:49], v[148:149], off offset:512
	global_load_dwordx4 v[54:57], v[52:53], off offset:256
	s_waitcnt vmcnt(0)
	v_add_f32_e32 v34, v34, v42
	global_load_dwordx4 v[50:53], v[50:51], off
	v_add_f32_e32 v38, v38, v46
	v_add_f32_e32 v39, v39, v47
	v_mul_f32_e32 v38, 0xbfb8aa3b, v38
	v_mul_f32_e32 v39, 0xbfb8aa3b, v39
	v_exp_f32_e32 v38, v38
	v_exp_f32_e32 v39, v39
	v_add_f32_e32 v35, v35, v43
	v_mul_f32_e32 v34, 0xbfb8aa3b, v34
	v_mul_f32_e32 v35, 0xbfb8aa3b, v35
	v_exp_f32_e32 v34, v34
	v_exp_f32_e32 v35, v35
	v_add_f32_e32 v38, 1.0, v38
	v_add_f32_e32 v39, 1.0, v39
	v_rcp_f32_e32 v38, v38
	v_rcp_f32_e32 v39, v39
	v_add_f32_e32 v34, 1.0, v34
	v_add_f32_e32 v35, 1.0, v35
	v_rcp_f32_e32 v34, v34
	v_rcp_f32_e32 v35, v35
	v_lshlrev_b32_e32 v46, 16, v54
	v_and_b32_e32 v47, 0xffff0000, v54
	v_pk_mul_f32 v[38:39], v[38:39], v[46:47]
	v_and_b32_e32 v43, 0xffff0000, v56
	v_add_u32_e32 v54, 0xa0, v152
	s_waitcnt vmcnt(0)
	v_lshlrev_b32_e32 v60, 16, v50
	v_mul_f32_e32 v42, 0xbfb8aa3b, v60
	v_exp_f32_e32 v42, v42
	v_and_b32_e32 v61, 0xffff0000, v50
	v_add_f32_e32 v42, 1.0, v42
	v_rcp_f32_e32 v62, v42
	v_mul_f32_e32 v42, 0xbfb8aa3b, v61
	v_exp_f32_e32 v42, v42
	s_nop 0
	v_add_f32_e32 v42, 1.0, v42
	v_rcp_f32_e32 v63, v42
	v_lshlrev_b32_e32 v42, 16, v56
	v_pk_mul_f32 v[34:35], v[34:35], v[42:43]
	v_pk_mul_f32 v[46:47], v[62:63], v[60:61]
	s_nop 0
	v_pk_mul_f32 v[38:39], v[38:39], v[46:47]
	v_lshlrev_b32_e32 v46, 16, v52
	v_and_b32_e32 v47, 0xffff0000, v52
	v_mul_f32_e32 v50, 0xbfb8aa3b, v46
	v_mul_f32_e32 v42, 0xbfb8aa3b, v47
	v_exp_f32_e32 v50, v50
	v_exp_f32_e32 v42, v42
	v_add_f32_e32 v50, 1.0, v50
	v_add_f32_e32 v42, 1.0, v42
	v_rcp_f32_e32 v60, v50
	v_rcp_f32_e32 v61, v42
	s_nop 0
	v_pk_mul_f32 v[42:43], v[60:61], v[46:47]
	s_nop 0
	v_pk_mul_f32 v[42:43], v[34:35], v[42:43]
	v_add_f32_e32 v35, v36, v44
	v_mul_f32_e32 v35, 0xbfb8aa3b, v35
	v_exp_f32_e32 v35, v35
	v_add_f32_e32 v34, v40, v48
	v_mul_f32_e32 v34, 0xbfb8aa3b, v34
	v_exp_f32_e32 v34, v34
	v_add_f32_e32 v35, 1.0, v35
	v_rcp_f32_e32 v36, v35
	v_add_f32_e32 v35, v41, v49
	v_mul_f32_e32 v35, 0xbfb8aa3b, v35
	v_exp_f32_e32 v35, v35
	v_add_f32_e32 v34, 1.0, v34
	v_rcp_f32_e32 v34, v34
	v_lshlrev_b32_e32 v40, 16, v55
	v_add_f32_e32 v35, 1.0, v35
	v_rcp_f32_e32 v35, v35
	v_and_b32_e32 v41, 0xffff0000, v55
	v_lshlrev_b32_e32 v46, 16, v51
	v_and_b32_e32 v47, 0xffff0000, v51
	v_mul_f32_e32 v44, 0xbfb8aa3b, v46
	v_pk_mul_f32 v[34:35], v[34:35], v[40:41]
	v_mul_f32_e32 v40, 0xbfb8aa3b, v47
	v_exp_f32_e32 v44, v44
	v_exp_f32_e32 v40, v40
	v_ashrrev_i32_e32 v55, 31, v54
	v_add_f32_e32 v44, 1.0, v44
	v_add_f32_e32 v40, 1.0, v40
	v_rcp_f32_e32 v48, v44
	v_rcp_f32_e32 v49, v40
	v_lshlrev_b32_e32 v44, 16, v53
	v_pk_mul_f32 v[40:41], v[48:49], v[46:47]
	s_nop 0
	v_pk_mul_f32 v[40:41], v[34:35], v[40:41]
	v_add_f32_e32 v34, v37, v45
	v_mul_f32_e32 v34, 0xbfb8aa3b, v34
	v_exp_f32_e32 v34, v34
	v_and_b32_e32 v35, 0xffff0000, v57
	v_and_b32_e32 v45, 0xffff0000, v53
	v_mul_f32_e32 v46, 0xbfb8aa3b, v44
	v_add_f32_e32 v34, 1.0, v34
	v_rcp_f32_e32 v37, v34
	v_lshlrev_b32_e32 v34, 16, v57
	v_exp_f32_e32 v46, v46
	v_pk_mul_f32 v[34:35], v[36:37], v[34:35]
	v_mul_f32_e32 v36, 0xbfb8aa3b, v45
	v_exp_f32_e32 v36, v36
	v_add_f32_e32 v46, 1.0, v46
	v_rcp_f32_e32 v46, v46
	v_add_f32_e32 v36, 1.0, v36
	v_rcp_f32_e32 v47, v36
	s_nop 0
	v_pk_mul_f32 v[36:37], v[46:47], v[44:45]
	s_nop 0
	v_pk_mul_f32 v[44:45], v[34:35], v[36:37]
	v_cvt_pk_bf16_f32 v34, v38, v39
	v_cvt_pk_bf16_f32 v35, v40, v41
	v_cvt_pk_bf16_f32 v36, v42, v43
	v_cvt_pk_bf16_f32 v37, v44, v45
	global_store_dwordx4 v[58:59], v[34:37], off offset:2304
	global_load_dwordx4 v[38:41], v[148:149], off offset:16
	global_load_dwordx4 v[42:45], v[148:149], off
	v_lshlrev_b64 v[34:35], 11, v[54:55]
	v_lshl_add_u64 v[34:35], s[56:57], 0, v[34:35]
	v_lshl_add_u64 v[36:37], v[34:35], 0, v[150:151]
	v_mad_i64_i32 v[34:35], s[24:25], v54, s48, v[154:155]
	v_lshl_add_u64 v[34:35], v[34:35], 0, s[94:95]
	v_lshl_add_u64 v[50:51], v[34:35], 0, v[150:151]
	global_load_dwordx4 v[46:49], v[36:37], off
	v_lshl_add_u64 v[34:35], v[34:35], 0, v[156:157]
	global_load_dwordx4 v[50:53], v[50:51], off
	s_waitcnt vmcnt(0)
	v_add_f32_e32 v26, v26, v38
	v_add_f32_e32 v30, v30, v42
	v_add_f32_e32 v31, v31, v43
	v_mul_f32_e32 v30, 0xbfb8aa3b, v30
	v_mul_f32_e32 v31, 0xbfb8aa3b, v31
	v_exp_f32_e32 v30, v30
	v_exp_f32_e32 v31, v31
	v_add_f32_e32 v27, v27, v39
	v_mul_f32_e32 v26, 0xbfb8aa3b, v26
	v_mul_f32_e32 v27, 0xbfb8aa3b, v27
	v_exp_f32_e32 v26, v26
	v_lshlrev_b32_e32 v56, 16, v50
	v_mul_f32_e32 v38, 0xbfb8aa3b, v56
	v_exp_f32_e32 v38, v38
	v_and_b32_e32 v57, 0xffff0000, v50
	v_exp_f32_e32 v27, v27
	v_add_f32_e32 v30, 1.0, v30
	v_add_f32_e32 v38, 1.0, v38
	v_rcp_f32_e32 v58, v38
	v_mul_f32_e32 v38, 0xbfb8aa3b, v57
	v_exp_f32_e32 v38, v38
	v_add_f32_e32 v31, 1.0, v31
	v_rcp_f32_e32 v30, v30
	v_rcp_f32_e32 v31, v31
	v_add_f32_e32 v38, 1.0, v38
	v_rcp_f32_e32 v59, v38
	v_add_f32_e32 v26, 1.0, v26
	v_add_f32_e32 v27, 1.0, v27
	v_rcp_f32_e32 v26, v26
	v_rcp_f32_e32 v27, v27
	v_lshlrev_b32_e32 v42, 16, v46
	v_and_b32_e32 v43, 0xffff0000, v46
	v_pk_mul_f32 v[30:31], v[30:31], v[42:43]
	v_pk_mul_f32 v[42:43], v[58:59], v[56:57]
	v_lshlrev_b32_e32 v38, 16, v48
	v_pk_mul_f32 v[30:31], v[30:31], v[42:43]
	v_and_b32_e32 v39, 0xffff0000, v48
	v_lshlrev_b32_e32 v42, 16, v52
	v_and_b32_e32 v43, 0xffff0000, v52
	v_mul_f32_e32 v46, 0xbfb8aa3b, v42
	v_pk_mul_f32 v[26:27], v[26:27], v[38:39]
	v_mul_f32_e32 v38, 0xbfb8aa3b, v43
	v_exp_f32_e32 v46, v46
	v_exp_f32_e32 v38, v38
	v_add_f32_e32 v46, 1.0, v46
	v_add_f32_e32 v38, 1.0, v38
	v_rcp_f32_e32 v56, v46
	v_rcp_f32_e32 v57, v38
	s_nop 0
	v_pk_mul_f32 v[38:39], v[56:57], v[42:43]
	s_nop 0
	v_pk_mul_f32 v[38:39], v[26:27], v[38:39]
	v_add_f32_e32 v27, v28, v40
	v_mul_f32_e32 v27, 0xbfb8aa3b, v27
	v_exp_f32_e32 v27, v27
	v_add_f32_e32 v26, v32, v44
	v_mul_f32_e32 v26, 0xbfb8aa3b, v26
	v_exp_f32_e32 v26, v26
	v_add_f32_e32 v27, 1.0, v27
	v_rcp_f32_e32 v28, v27
	v_add_f32_e32 v27, v33, v45
	v_mul_f32_e32 v27, 0xbfb8aa3b, v27
	v_exp_f32_e32 v27, v27
	v_add_f32_e32 v26, 1.0, v26
	v_rcp_f32_e32 v26, v26
	v_lshlrev_b32_e32 v32, 16, v47
	v_add_f32_e32 v27, 1.0, v27
	v_rcp_f32_e32 v27, v27
	v_and_b32_e32 v33, 0xffff0000, v47
	v_lshlrev_b32_e32 v42, 16, v51
	v_and_b32_e32 v43, 0xffff0000, v51
	v_mul_f32_e32 v40, 0xbfb8aa3b, v42
	v_pk_mul_f32 v[26:27], v[26:27], v[32:33]
	v_mul_f32_e32 v32, 0xbfb8aa3b, v43
	v_exp_f32_e32 v40, v40
	v_exp_f32_e32 v32, v32
	v_add_f32_e32 v40, 1.0, v40
	v_add_f32_e32 v32, 1.0, v32
	v_rcp_f32_e32 v44, v40
	v_rcp_f32_e32 v45, v32
	v_lshlrev_b32_e32 v40, 16, v53
	v_pk_mul_f32 v[32:33], v[44:45], v[42:43]
	s_nop 0
	v_pk_mul_f32 v[32:33], v[26:27], v[32:33]
	v_add_f32_e32 v26, v29, v41
	v_mul_f32_e32 v26, 0xbfb8aa3b, v26
	v_exp_f32_e32 v26, v26
	v_and_b32_e32 v27, 0xffff0000, v49
	v_and_b32_e32 v41, 0xffff0000, v53
	v_mul_f32_e32 v42, 0xbfb8aa3b, v40
	v_add_f32_e32 v26, 1.0, v26
	v_rcp_f32_e32 v29, v26
	v_lshlrev_b32_e32 v26, 16, v49
	v_exp_f32_e32 v42, v42
	v_pk_mul_f32 v[26:27], v[28:29], v[26:27]
	v_mul_f32_e32 v28, 0xbfb8aa3b, v41
	v_exp_f32_e32 v28, v28
	v_add_f32_e32 v42, 1.0, v42
	v_rcp_f32_e32 v42, v42
	v_add_f32_e32 v28, 1.0, v28
	v_rcp_f32_e32 v43, v28
	s_nop 0
	v_pk_mul_f32 v[28:29], v[42:43], v[40:41]
	s_nop 0
	v_pk_mul_f32 v[40:41], v[26:27], v[28:29]
	v_cvt_pk_bf16_f32 v26, v30, v31
	v_lshlrev_b64 v[30:31], 12, v[54:55]
	v_lshl_add_u64 v[30:31], s[36:37], 0, v[30:31]
	v_cvt_pk_bf16_f32 v27, v32, v33
	v_cvt_pk_bf16_f32 v28, v38, v39
	v_cvt_pk_bf16_f32 v29, v40, v41
	v_lshl_add_u64 v[42:43], v[30:31], 0, v[150:151]
	global_store_dwordx4 v[42:43], v[26:29], off offset:2048
	global_load_dwordx4 v[26:29], v[148:149], off offset:528
	s_nop 0
	global_load_dwordx4 v[30:33], v[148:149], off offset:512
	global_load_dwordx4 v[38:41], v[36:37], off offset:256
	s_waitcnt vmcnt(0)
	v_add_f32_e32 v18, v18, v26
	global_load_dwordx4 v[34:37], v[34:35], off
	v_add_f32_e32 v22, v22, v30
	v_add_f32_e32 v23, v23, v31
	v_mul_f32_e32 v22, 0xbfb8aa3b, v22
	v_mul_f32_e32 v23, 0xbfb8aa3b, v23
	v_exp_f32_e32 v22, v22
	v_exp_f32_e32 v23, v23
	v_add_f32_e32 v19, v19, v27
	v_mul_f32_e32 v18, 0xbfb8aa3b, v18
	v_mul_f32_e32 v19, 0xbfb8aa3b, v19
	v_exp_f32_e32 v18, v18
	v_exp_f32_e32 v19, v19
	v_add_f32_e32 v22, 1.0, v22
	v_add_f32_e32 v23, 1.0, v23
	v_rcp_f32_e32 v22, v22
	v_rcp_f32_e32 v23, v23
	v_add_f32_e32 v18, 1.0, v18
	v_add_f32_e32 v19, 1.0, v19
	v_rcp_f32_e32 v18, v18
	v_rcp_f32_e32 v19, v19
	v_lshlrev_b32_e32 v30, 16, v38
	v_and_b32_e32 v31, 0xffff0000, v38
	v_pk_mul_f32 v[22:23], v[22:23], v[30:31]
	v_and_b32_e32 v27, 0xffff0000, v40
	v_add_u32_e32 v38, 0xb0, v152
	s_waitcnt vmcnt(0)
	v_lshlrev_b32_e32 v44, 16, v34
	v_mul_f32_e32 v26, 0xbfb8aa3b, v44
	v_exp_f32_e32 v26, v26
	v_and_b32_e32 v45, 0xffff0000, v34
	v_add_f32_e32 v26, 1.0, v26
	v_rcp_f32_e32 v46, v26
	v_mul_f32_e32 v26, 0xbfb8aa3b, v45
	v_exp_f32_e32 v26, v26
	s_nop 0
	v_add_f32_e32 v26, 1.0, v26
	v_rcp_f32_e32 v47, v26
	v_lshlrev_b32_e32 v26, 16, v40
	v_pk_mul_f32 v[18:19], v[18:19], v[26:27]
	v_pk_mul_f32 v[30:31], v[46:47], v[44:45]
	s_nop 0
	v_pk_mul_f32 v[22:23], v[22:23], v[30:31]
	v_lshlrev_b32_e32 v30, 16, v36
	v_and_b32_e32 v31, 0xffff0000, v36
	v_mul_f32_e32 v34, 0xbfb8aa3b, v30
	v_mul_f32_e32 v26, 0xbfb8aa3b, v31
	v_exp_f32_e32 v34, v34
	v_exp_f32_e32 v26, v26
	v_add_f32_e32 v34, 1.0, v34
	v_add_f32_e32 v26, 1.0, v26
	v_rcp_f32_e32 v44, v34
	v_rcp_f32_e32 v45, v26
	s_nop 0
	v_pk_mul_f32 v[26:27], v[44:45], v[30:31]
	s_nop 0
	v_pk_mul_f32 v[26:27], v[18:19], v[26:27]
	v_add_f32_e32 v19, v20, v28
	v_mul_f32_e32 v19, 0xbfb8aa3b, v19
	v_exp_f32_e32 v19, v19
	v_add_f32_e32 v18, v24, v32
	v_mul_f32_e32 v18, 0xbfb8aa3b, v18
	v_exp_f32_e32 v18, v18
	v_add_f32_e32 v19, 1.0, v19
	v_rcp_f32_e32 v20, v19
	v_add_f32_e32 v19, v25, v33
	v_mul_f32_e32 v19, 0xbfb8aa3b, v19
	v_exp_f32_e32 v19, v19
	v_add_f32_e32 v18, 1.0, v18
	v_rcp_f32_e32 v18, v18
	v_lshlrev_b32_e32 v24, 16, v39
	v_add_f32_e32 v19, 1.0, v19
	v_rcp_f32_e32 v19, v19
	v_and_b32_e32 v25, 0xffff0000, v39
	v_lshlrev_b32_e32 v30, 16, v35
	v_and_b32_e32 v31, 0xffff0000, v35
	v_mul_f32_e32 v28, 0xbfb8aa3b, v30
	v_pk_mul_f32 v[18:19], v[18:19], v[24:25]
	v_mul_f32_e32 v24, 0xbfb8aa3b, v31
	v_exp_f32_e32 v28, v28
	v_exp_f32_e32 v24, v24
	v_ashrrev_i32_e32 v39, 31, v38
	v_add_f32_e32 v28, 1.0, v28
	v_add_f32_e32 v24, 1.0, v24
	v_rcp_f32_e32 v32, v28
	v_rcp_f32_e32 v33, v24
	v_lshlrev_b32_e32 v28, 16, v37
	v_pk_mul_f32 v[24:25], v[32:33], v[30:31]
	s_nop 0
	v_pk_mul_f32 v[24:25], v[18:19], v[24:25]
	v_add_f32_e32 v18, v21, v29
	v_mul_f32_e32 v18, 0xbfb8aa3b, v18
	v_exp_f32_e32 v18, v18
	v_and_b32_e32 v19, 0xffff0000, v41
	v_and_b32_e32 v29, 0xffff0000, v37
	v_mul_f32_e32 v30, 0xbfb8aa3b, v28
	v_add_f32_e32 v18, 1.0, v18
	v_rcp_f32_e32 v21, v18
	v_lshlrev_b32_e32 v18, 16, v41
	v_exp_f32_e32 v30, v30
	v_pk_mul_f32 v[18:19], v[20:21], v[18:19]
	v_mul_f32_e32 v20, 0xbfb8aa3b, v29
	v_exp_f32_e32 v20, v20
	v_add_f32_e32 v30, 1.0, v30
	v_rcp_f32_e32 v30, v30
	v_add_f32_e32 v20, 1.0, v20
	v_rcp_f32_e32 v31, v20
	s_nop 0
	v_pk_mul_f32 v[20:21], v[30:31], v[28:29]
	s_nop 0
	v_pk_mul_f32 v[28:29], v[18:19], v[20:21]
	v_cvt_pk_bf16_f32 v18, v22, v23
	v_cvt_pk_bf16_f32 v19, v24, v25
	v_cvt_pk_bf16_f32 v20, v26, v27
	v_cvt_pk_bf16_f32 v21, v28, v29
	global_store_dwordx4 v[42:43], v[18:21], off offset:2304
	global_load_dwordx4 v[22:25], v[148:149], off offset:16
	global_load_dwordx4 v[26:29], v[148:149], off
	v_lshlrev_b64 v[18:19], 11, v[38:39]
	v_lshl_add_u64 v[18:19], s[56:57], 0, v[18:19]
	v_lshl_add_u64 v[20:21], v[18:19], 0, v[150:151]
	v_mad_i64_i32 v[18:19], s[24:25], v38, s48, v[154:155]
	v_lshl_add_u64 v[18:19], v[18:19], 0, s[94:95]
	v_lshl_add_u64 v[34:35], v[18:19], 0, v[150:151]
	global_load_dwordx4 v[30:33], v[20:21], off
	v_lshl_add_u64 v[18:19], v[18:19], 0, v[156:157]
	global_load_dwordx4 v[34:37], v[34:35], off
	s_waitcnt vmcnt(0)
	v_add_f32_e32 v10, v10, v22
	v_add_f32_e32 v14, v14, v26
	v_add_f32_e32 v15, v15, v27
	v_mul_f32_e32 v14, 0xbfb8aa3b, v14
	v_mul_f32_e32 v15, 0xbfb8aa3b, v15
	v_exp_f32_e32 v14, v14
	v_exp_f32_e32 v15, v15
	v_add_f32_e32 v11, v11, v23
	v_mul_f32_e32 v10, 0xbfb8aa3b, v10
	v_mul_f32_e32 v11, 0xbfb8aa3b, v11
	v_exp_f32_e32 v10, v10
	v_lshlrev_b32_e32 v40, 16, v34
	v_mul_f32_e32 v22, 0xbfb8aa3b, v40
	v_exp_f32_e32 v22, v22
	v_and_b32_e32 v41, 0xffff0000, v34
	v_exp_f32_e32 v11, v11
	v_add_f32_e32 v14, 1.0, v14
	v_add_f32_e32 v22, 1.0, v22
	v_rcp_f32_e32 v42, v22
	v_mul_f32_e32 v22, 0xbfb8aa3b, v41
	v_exp_f32_e32 v22, v22
	v_add_f32_e32 v15, 1.0, v15
	v_rcp_f32_e32 v14, v14
	v_rcp_f32_e32 v15, v15
	v_add_f32_e32 v22, 1.0, v22
	v_rcp_f32_e32 v43, v22
	v_add_f32_e32 v10, 1.0, v10
	v_add_f32_e32 v11, 1.0, v11
	v_rcp_f32_e32 v10, v10
	v_rcp_f32_e32 v11, v11
	v_lshlrev_b32_e32 v26, 16, v30
	v_and_b32_e32 v27, 0xffff0000, v30
	v_pk_mul_f32 v[14:15], v[14:15], v[26:27]
	v_pk_mul_f32 v[26:27], v[42:43], v[40:41]
	v_lshlrev_b32_e32 v22, 16, v32
	v_pk_mul_f32 v[14:15], v[14:15], v[26:27]
	v_and_b32_e32 v23, 0xffff0000, v32
	v_lshlrev_b32_e32 v26, 16, v36
	v_and_b32_e32 v27, 0xffff0000, v36
	v_mul_f32_e32 v30, 0xbfb8aa3b, v26
	v_pk_mul_f32 v[10:11], v[10:11], v[22:23]
	v_mul_f32_e32 v22, 0xbfb8aa3b, v27
	v_exp_f32_e32 v30, v30
	v_exp_f32_e32 v22, v22
	v_add_f32_e32 v30, 1.0, v30
	v_add_f32_e32 v22, 1.0, v22
	v_rcp_f32_e32 v40, v30
	v_rcp_f32_e32 v41, v22
	s_nop 0
	v_pk_mul_f32 v[22:23], v[40:41], v[26:27]
	s_nop 0
	v_pk_mul_f32 v[22:23], v[10:11], v[22:23]
	v_add_f32_e32 v11, v12, v24
	v_mul_f32_e32 v11, 0xbfb8aa3b, v11
	v_exp_f32_e32 v11, v11
	v_add_f32_e32 v10, v16, v28
	v_mul_f32_e32 v10, 0xbfb8aa3b, v10
	v_exp_f32_e32 v10, v10
	v_add_f32_e32 v11, 1.0, v11
	v_rcp_f32_e32 v12, v11
	v_add_f32_e32 v11, v17, v29
	v_mul_f32_e32 v11, 0xbfb8aa3b, v11
	v_exp_f32_e32 v11, v11
	v_add_f32_e32 v10, 1.0, v10
	v_rcp_f32_e32 v10, v10
	v_lshlrev_b32_e32 v16, 16, v31
	v_add_f32_e32 v11, 1.0, v11
	v_rcp_f32_e32 v11, v11
	v_and_b32_e32 v17, 0xffff0000, v31
	v_lshlrev_b32_e32 v26, 16, v35
	v_and_b32_e32 v27, 0xffff0000, v35
	v_mul_f32_e32 v24, 0xbfb8aa3b, v26
	v_pk_mul_f32 v[10:11], v[10:11], v[16:17]
	v_mul_f32_e32 v16, 0xbfb8aa3b, v27
	v_exp_f32_e32 v24, v24
	v_exp_f32_e32 v16, v16
	v_add_f32_e32 v24, 1.0, v24
	v_add_f32_e32 v16, 1.0, v16
	v_rcp_f32_e32 v28, v24
	v_rcp_f32_e32 v29, v16
	v_lshlrev_b32_e32 v24, 16, v37
	v_pk_mul_f32 v[16:17], v[28:29], v[26:27]
	s_nop 0
	v_pk_mul_f32 v[16:17], v[10:11], v[16:17]
	v_add_f32_e32 v10, v13, v25
	v_mul_f32_e32 v10, 0xbfb8aa3b, v10
	v_exp_f32_e32 v10, v10
	v_and_b32_e32 v11, 0xffff0000, v33
	v_and_b32_e32 v25, 0xffff0000, v37
	v_mul_f32_e32 v26, 0xbfb8aa3b, v24
	v_add_f32_e32 v10, 1.0, v10
	v_rcp_f32_e32 v13, v10
	v_lshlrev_b32_e32 v10, 16, v33
	v_exp_f32_e32 v26, v26
	v_pk_mul_f32 v[10:11], v[12:13], v[10:11]
	v_mul_f32_e32 v12, 0xbfb8aa3b, v25
	v_exp_f32_e32 v12, v12
	v_add_f32_e32 v26, 1.0, v26
	v_rcp_f32_e32 v26, v26
	v_add_f32_e32 v12, 1.0, v12
	v_rcp_f32_e32 v27, v12
	s_nop 0
	v_pk_mul_f32 v[12:13], v[26:27], v[24:25]
	s_nop 0
	v_pk_mul_f32 v[24:25], v[10:11], v[12:13]
	v_cvt_pk_bf16_f32 v10, v14, v15
	v_lshlrev_b64 v[14:15], 12, v[38:39]
	v_lshl_add_u64 v[14:15], s[36:37], 0, v[14:15]
	v_cvt_pk_bf16_f32 v11, v16, v17
	v_cvt_pk_bf16_f32 v12, v22, v23
	v_cvt_pk_bf16_f32 v13, v24, v25
	v_lshl_add_u64 v[26:27], v[14:15], 0, v[150:151]
	global_store_dwordx4 v[26:27], v[10:13], off offset:2048
	global_load_dwordx4 v[10:13], v[148:149], off offset:528
	s_nop 0
	global_load_dwordx4 v[14:17], v[148:149], off offset:512
	global_load_dwordx4 v[22:25], v[20:21], off offset:256
	s_waitcnt vmcnt(0)
	v_add_f32_e32 v2, v2, v10
	global_load_dwordx4 v[18:21], v[18:19], off
	v_add_f32_e32 v6, v6, v14
	v_add_f32_e32 v7, v7, v15
	v_mul_f32_e32 v6, 0xbfb8aa3b, v6
	v_mul_f32_e32 v7, 0xbfb8aa3b, v7
	v_exp_f32_e32 v6, v6
	v_exp_f32_e32 v7, v7
	v_add_f32_e32 v3, v3, v11
	v_mul_f32_e32 v2, 0xbfb8aa3b, v2
	v_mul_f32_e32 v3, 0xbfb8aa3b, v3
	v_exp_f32_e32 v2, v2
	v_exp_f32_e32 v3, v3
	v_add_f32_e32 v6, 1.0, v6
	v_add_f32_e32 v7, 1.0, v7
	v_rcp_f32_e32 v6, v6
	v_rcp_f32_e32 v7, v7
	v_add_f32_e32 v2, 1.0, v2
	v_add_f32_e32 v3, 1.0, v3
	v_rcp_f32_e32 v2, v2
	v_rcp_f32_e32 v3, v3
	v_lshlrev_b32_e32 v14, 16, v22
	v_and_b32_e32 v15, 0xffff0000, v22
	v_pk_mul_f32 v[6:7], v[6:7], v[14:15]
	v_and_b32_e32 v11, 0xffff0000, v24
	s_waitcnt vmcnt(0)
	v_lshlrev_b32_e32 v28, 16, v18
	v_mul_f32_e32 v10, 0xbfb8aa3b, v28
	v_exp_f32_e32 v10, v10
	v_and_b32_e32 v29, 0xffff0000, v18
	v_add_f32_e32 v10, 1.0, v10
	v_rcp_f32_e32 v30, v10
	v_mul_f32_e32 v10, 0xbfb8aa3b, v29
	v_exp_f32_e32 v10, v10
	s_nop 0
	v_add_f32_e32 v10, 1.0, v10
	v_rcp_f32_e32 v31, v10
	v_lshlrev_b32_e32 v10, 16, v24
	v_pk_mul_f32 v[2:3], v[2:3], v[10:11]
	v_pk_mul_f32 v[14:15], v[30:31], v[28:29]
	s_nop 0
	v_pk_mul_f32 v[6:7], v[6:7], v[14:15]
	v_lshlrev_b32_e32 v14, 16, v20
	v_and_b32_e32 v15, 0xffff0000, v20
	v_mul_f32_e32 v18, 0xbfb8aa3b, v14
	v_mul_f32_e32 v10, 0xbfb8aa3b, v15
	v_exp_f32_e32 v18, v18
	v_exp_f32_e32 v10, v10
	v_add_f32_e32 v18, 1.0, v18
	v_add_f32_e32 v10, 1.0, v10
	v_rcp_f32_e32 v28, v18
	v_rcp_f32_e32 v29, v10
	s_nop 0
	v_pk_mul_f32 v[10:11], v[28:29], v[14:15]
	s_nop 0
	v_pk_mul_f32 v[10:11], v[2:3], v[10:11]
	v_add_f32_e32 v3, v4, v12
	v_mul_f32_e32 v3, 0xbfb8aa3b, v3
	v_exp_f32_e32 v3, v3
	v_add_f32_e32 v2, v8, v16
	v_mul_f32_e32 v2, 0xbfb8aa3b, v2
	v_exp_f32_e32 v2, v2
	v_add_f32_e32 v3, 1.0, v3
	v_rcp_f32_e32 v4, v3
	v_add_f32_e32 v3, v9, v17
	v_mul_f32_e32 v3, 0xbfb8aa3b, v3
	v_exp_f32_e32 v3, v3
	v_add_f32_e32 v2, 1.0, v2
	v_rcp_f32_e32 v2, v2
	v_lshlrev_b32_e32 v8, 16, v23
	v_add_f32_e32 v3, 1.0, v3
	v_rcp_f32_e32 v3, v3
	v_and_b32_e32 v9, 0xffff0000, v23
	v_lshlrev_b32_e32 v14, 16, v19
	v_and_b32_e32 v15, 0xffff0000, v19
	v_mul_f32_e32 v12, 0xbfb8aa3b, v14
	v_pk_mul_f32 v[2:3], v[2:3], v[8:9]
	v_mul_f32_e32 v8, 0xbfb8aa3b, v15
	v_exp_f32_e32 v12, v12
	v_exp_f32_e32 v8, v8
	v_add_f32_e32 v12, 1.0, v12
	v_add_f32_e32 v8, 1.0, v8
	v_rcp_f32_e32 v16, v12
	v_rcp_f32_e32 v17, v8
	v_lshlrev_b32_e32 v12, 16, v21
	v_pk_mul_f32 v[8:9], v[16:17], v[14:15]
	s_nop 0
	v_pk_mul_f32 v[8:9], v[2:3], v[8:9]
	v_add_f32_e32 v2, v5, v13
	v_mul_f32_e32 v2, 0xbfb8aa3b, v2
	v_exp_f32_e32 v2, v2
	v_and_b32_e32 v3, 0xffff0000, v25
	v_and_b32_e32 v13, 0xffff0000, v21
	v_mul_f32_e32 v14, 0xbfb8aa3b, v12
	v_add_f32_e32 v2, 1.0, v2
	v_rcp_f32_e32 v5, v2
	v_lshlrev_b32_e32 v2, 16, v25
	v_exp_f32_e32 v14, v14
	v_pk_mul_f32 v[2:3], v[4:5], v[2:3]
	v_mul_f32_e32 v4, 0xbfb8aa3b, v13
	v_exp_f32_e32 v4, v4
	v_add_f32_e32 v14, 1.0, v14
	v_rcp_f32_e32 v14, v14
	v_add_f32_e32 v4, 1.0, v4
	v_rcp_f32_e32 v15, v4
	s_nop 0
	v_pk_mul_f32 v[4:5], v[14:15], v[12:13]
	s_nop 0
	v_pk_mul_f32 v[12:13], v[2:3], v[4:5]
	v_cvt_pk_bf16_f32 v2, v6, v7
	v_cvt_pk_bf16_f32 v3, v8, v9
	v_cvt_pk_bf16_f32 v4, v10, v11
	v_cvt_pk_bf16_f32 v5, v12, v13
	global_store_dwordx4 v[26:27], v[2:5], off offset:2304
	s_cbranch_vccz .LBB0_970
	v_readlane_b32 s4, v254, 12
	s_waitcnt vmcnt(0)
	v_readlane_b32 s5, v254, 13
	s_andn2_b64 vcc, exec, s[4:5]
	s_cbranch_vccnz .LBB0_981
	s_barrier

.LBB0_1044:
	s_add_u32 s2, s68, 0xfff80080
	s_addc_u32 s17, s69, -1
	s_add_i32 s26, 0, 0x10000
	v_add_u32_e32 v156, s26, v141
	ds_read_b128 v[144:147], v156
	ds_read_b128 v[148:151], v156 offset:1024
	ds_read_b128 v[152:155], v156 offset:2048
	ds_read_b128 v[156:159], v156 offset:3072
	s_cmp_eq_u32 s44, 28
	s_cselect_b32 s73, s55, s17
	s_cselect_b32 s72, s24, s2
	s_cselect_b32 s71, s25, s92
	s_cselect_b32 s70, s43, s83
	v_lshl_add_u64 v[164:165], s[68:69], 0, v[136:137]
	s_add_i32 m0, s58, 0xc000
	ds_read_b128 v[160:163], v143
	ds_read_b128 v[188:191], v143 offset:1024
	ds_read_b128 v[192:195], v143 offset:2048
	ds_read_b128 v[196:199], v143 offset:3072
	ds_read_b128 v[200:203], v143 offset:4096
	ds_read_b128 v[216:219], v143 offset:5120
	ds_read_b128 v[220:223], v143 offset:6144
	ds_read_b128 v[224:227], v143 offset:7168
	global_load_lds_dwordx4 v[164:165], off
	v_lshl_add_u64 v[164:165], s[68:69], 0, v[138:139]
	s_add_i32 m0, s58, 0xe000
	s_nop 0
	global_load_lds_dwordx4 v[164:165], off
	s_waitcnt lgkmcnt(8)
	s_barrier
	s_waitcnt lgkmcnt(7)
	v_mfma_f32_16x16x32_bf16 v[126:129], v[144:147], v[160:163], v[126:129]
	v_mfma_f32_16x16x32_bf16 v[122:125], v[152:155], v[160:163], v[122:125]
	s_waitcnt lgkmcnt(3)
	v_mfma_f32_16x16x32_bf16 v[118:121], v[144:147], v[192:195], v[118:121]
	v_mfma_f32_16x16x32_bf16 v[114:117], v[152:155], v[192:195], v[114:117]
	v_mfma_f32_16x16x32_bf16 v[102:105], v[144:147], v[200:203], v[102:105]
	v_mfma_f32_16x16x32_bf16 v[98:101], v[152:155], v[200:203], v[98:101]
	s_waitcnt lgkmcnt(0)
	v_mfma_f32_16x16x32_bf16 v[86:89], v[144:147], v[220:223], v[86:89]
	v_mfma_f32_16x16x32_bf16 v[82:85], v[152:155], v[220:223], v[82:85]
	v_mfma_f32_16x16x32_bf16 v[126:129], v[148:151], v[188:191], v[126:129]
	v_mfma_f32_16x16x32_bf16 v[122:125], v[156:159], v[188:191], v[122:125]
	v_mfma_f32_16x16x32_bf16 v[118:121], v[148:151], v[196:199], v[118:121]
	v_mfma_f32_16x16x32_bf16 v[114:117], v[156:159], v[196:199], v[114:117]
	v_mfma_f32_16x16x32_bf16 v[102:105], v[148:151], v[216:219], v[102:105]
	v_mfma_f32_16x16x32_bf16 v[98:101], v[156:159], v[216:219], v[98:101]
	v_mfma_f32_16x16x32_bf16 v[86:89], v[148:151], v[224:227], v[86:89]
	v_mfma_f32_16x16x32_bf16 v[82:85], v[156:159], v[224:227], v[82:85]
	s_barrier
	s_add_i32 s2, 0, 0x14000
	v_add_u32_e32 v164, s2, v141
	s_add_i32 s17, s26, s3
	ds_read_b128 v[228:231], v164
	ds_read_b128 v[232:235], v164 offset:1024
	ds_read_b128 v[236:239], v164 offset:2048
	ds_read_b128 v[240:243], v164 offset:3072
	v_lshl_add_u64 v[164:165], s[70:71], 0, v[0:1]
	s_mov_b32 m0, s17
	v_lshl_add_u64 v[204:205], s[70:71], 0, v[130:131]
	global_load_lds_dwordx4 v[164:165], off
	s_add_i32 m0, s17, 0x2000
	s_nop 0
	global_load_lds_dwordx4 v[204:205], off
	s_barrier
	s_waitcnt lgkmcnt(1)
	v_mfma_f32_16x16x32_bf16 v[110:113], v[228:231], v[160:163], v[110:113]
	v_mfma_f32_16x16x32_bf16 v[106:109], v[236:239], v[160:163], v[106:109]
	v_mfma_f32_16x16x32_bf16 v[94:97], v[228:231], v[192:195], v[94:97]
	v_mfma_f32_16x16x32_bf16 v[90:93], v[236:239], v[192:195], v[90:93]
	v_mfma_f32_16x16x32_bf16 v[78:81], v[228:231], v[200:203], v[78:81]
	v_mfma_f32_16x16x32_bf16 v[74:77], v[236:239], v[200:203], v[74:77]
	s_waitcnt lgkmcnt(0)
	v_mfma_f32_16x16x32_bf16 v[70:73], v[228:231], v[220:223], v[70:73]
	v_mfma_f32_16x16x32_bf16 v[66:69], v[236:239], v[220:223], v[66:69]
	v_mfma_f32_16x16x32_bf16 v[110:113], v[232:235], v[188:191], v[110:113]
	v_mfma_f32_16x16x32_bf16 v[106:109], v[240:243], v[188:191], v[106:109]
	v_mfma_f32_16x16x32_bf16 v[94:97], v[232:235], v[196:199], v[94:97]
	v_mfma_f32_16x16x32_bf16 v[90:93], v[240:243], v[196:199], v[90:93]
	v_mfma_f32_16x16x32_bf16 v[78:81], v[232:235], v[216:219], v[78:81]
	v_mfma_f32_16x16x32_bf16 v[74:77], v[240:243], v[216:219], v[74:77]
	v_mfma_f32_16x16x32_bf16 v[70:73], v[232:235], v[224:227], v[70:73]
	v_mfma_f32_16x16x32_bf16 v[66:69], v[240:243], v[224:227], v[66:69]
	s_mov_b32 m0, s58
	v_lshl_add_u64 v[244:245], s[72:73], 0, v[134:135]
	s_barrier
	ds_read_b128 v[160:163], v143 offset:16384
	ds_read_b128 v[188:191], v143 offset:17408
	ds_read_b128 v[192:195], v143 offset:18432
	ds_read_b128 v[196:199], v143 offset:19456
	ds_read_b128 v[200:203], v143 offset:20480
	ds_read_b128 v[216:219], v143 offset:21504
	ds_read_b128 v[220:223], v143 offset:22528
	ds_read_b128 v[224:227], v143 offset:23552
	global_load_lds_dwordx4 v[244:245], off
	v_lshl_add_u64 v[246:247], s[72:73], 0, v[132:133]
	s_mov_b32 m0, s74
	s_nop 0
	global_load_lds_dwordx4 v[246:247], off
	s_barrier
	s_waitcnt lgkmcnt(7)
	v_mfma_f32_16x16x32_bf16 v[62:65], v[144:147], v[160:163], v[62:65]
	v_mfma_f32_16x16x32_bf16 v[58:61], v[152:155], v[160:163], v[58:61]
	s_waitcnt lgkmcnt(3)
	v_mfma_f32_16x16x32_bf16 v[54:57], v[144:147], v[192:195], v[54:57]
	v_mfma_f32_16x16x32_bf16 v[50:53], v[152:155], v[192:195], v[50:53]
	v_mfma_f32_16x16x32_bf16 v[38:41], v[144:147], v[200:203], v[38:41]
	v_mfma_f32_16x16x32_bf16 v[34:37], v[152:155], v[200:203], v[34:37]
	s_waitcnt lgkmcnt(0)
	v_mfma_f32_16x16x32_bf16 v[22:25], v[144:147], v[220:223], v[22:25]
	v_mfma_f32_16x16x32_bf16 v[18:21], v[152:155], v[220:223], v[18:21]
	v_mfma_f32_16x16x32_bf16 v[62:65], v[148:151], v[188:191], v[62:65]
	v_mfma_f32_16x16x32_bf16 v[58:61], v[156:159], v[188:191], v[58:61]
	v_mfma_f32_16x16x32_bf16 v[54:57], v[148:151], v[196:199], v[54:57]
	v_mfma_f32_16x16x32_bf16 v[50:53], v[156:159], v[196:199], v[50:53]
	v_mfma_f32_16x16x32_bf16 v[38:41], v[148:151], v[216:219], v[38:41]
	v_mfma_f32_16x16x32_bf16 v[34:37], v[156:159], v[216:219], v[34:37]
	v_mfma_f32_16x16x32_bf16 v[22:25], v[148:151], v[224:227], v[22:25]
	v_mfma_f32_16x16x32_bf16 v[18:21], v[156:159], v[224:227], v[18:21]
	s_barrier
	s_add_u32 s26, s70, 0x80000
	s_addc_u32 s27, s71, 0
	s_add_i32 s2, s2, s3
	v_lshl_add_u64 v[144:145], s[26:27], 0, v[0:1]
	s_mov_b32 m0, s2
	s_nop 0
	global_load_lds_dwordx4 v[144:145], off
	v_lshl_add_u64 v[144:145], s[26:27], 0, v[130:131]
	s_add_i32 m0, s2, 0x2000
	s_nop 0
	global_load_lds_dwordx4 v[144:145], off
	s_waitcnt vmcnt(6)
	s_barrier
	v_mfma_f32_16x16x32_bf16 v[46:49], v[228:231], v[160:163], v[46:49]
	v_mfma_f32_16x16x32_bf16 v[42:45], v[236:239], v[160:163], v[42:45]
	v_mfma_f32_16x16x32_bf16 v[30:33], v[228:231], v[192:195], v[30:33]
	v_mfma_f32_16x16x32_bf16 v[26:29], v[236:239], v[192:195], v[26:29]
	v_mfma_f32_16x16x32_bf16 v[14:17], v[228:231], v[200:203], v[14:17]
	v_mfma_f32_16x16x32_bf16 v[10:13], v[236:239], v[200:203], v[10:13]
	v_mfma_f32_16x16x32_bf16 v[6:9], v[228:231], v[220:223], v[6:9]
	v_mfma_f32_16x16x32_bf16 v[2:5], v[236:239], v[220:223], v[2:5]
	v_mfma_f32_16x16x32_bf16 v[46:49], v[232:235], v[188:191], v[46:49]
	v_mfma_f32_16x16x32_bf16 v[42:45], v[240:243], v[188:191], v[42:45]
	v_mfma_f32_16x16x32_bf16 v[30:33], v[232:235], v[196:199], v[30:33]
	v_mfma_f32_16x16x32_bf16 v[26:29], v[240:243], v[196:199], v[26:29]
	v_mfma_f32_16x16x32_bf16 v[14:17], v[232:235], v[216:219], v[14:17]
	v_mfma_f32_16x16x32_bf16 v[10:13], v[240:243], v[216:219], v[10:13]
	v_mfma_f32_16x16x32_bf16 v[6:9], v[232:235], v[224:227], v[6:9]
	v_mfma_f32_16x16x32_bf16 v[2:5], v[240:243], v[224:227], v[2:5]
	s_add_i32 s2, 0, 0x18000
	v_add_u32_e32 v156, s2, v141
	s_barrier
	ds_read_b128 v[144:147], v156
	ds_read_b128 v[148:151], v156 offset:1024
	ds_read_b128 v[152:155], v156 offset:2048
	ds_read_b128 v[156:159], v156 offset:3072
	s_add_u32 s26, s72, 0x80000
	s_addc_u32 s27, s73, 0
	s_mov_b32 m0, s75
	v_lshl_add_u64 v[228:229], s[26:27], 0, v[134:135]
	ds_read_b128 v[160:163], v143 offset:32768
	ds_read_b128 v[188:191], v143 offset:33792
	ds_read_b128 v[192:195], v143 offset:34816
	ds_read_b128 v[196:199], v143 offset:35840
	ds_read_b128 v[200:203], v143 offset:36864
	ds_read_b128 v[216:219], v143 offset:37888
	ds_read_b128 v[220:223], v143 offset:38912
	ds_read_b128 v[224:227], v143 offset:39936
	global_load_lds_dwordx4 v[228:229], off
	v_lshl_add_u64 v[228:229], s[26:27], 0, v[132:133]
	s_mov_b32 m0, s79
	s_nop 0
	global_load_lds_dwordx4 v[228:229], off
	s_waitcnt lgkmcnt(8)
	s_barrier
	s_waitcnt lgkmcnt(7)
	v_mfma_f32_16x16x32_bf16 v[126:129], v[144:147], v[160:163], v[126:129]
	v_mfma_f32_16x16x32_bf16 v[122:125], v[152:155], v[160:163], v[122:125]
	s_waitcnt lgkmcnt(3)
	v_mfma_f32_16x16x32_bf16 v[118:121], v[144:147], v[192:195], v[118:121]
	v_mfma_f32_16x16x32_bf16 v[114:117], v[152:155], v[192:195], v[114:117]
	v_mfma_f32_16x16x32_bf16 v[102:105], v[144:147], v[200:203], v[102:105]
	v_mfma_f32_16x16x32_bf16 v[98:101], v[152:155], v[200:203], v[98:101]
	s_waitcnt lgkmcnt(0)
	v_mfma_f32_16x16x32_bf16 v[86:89], v[144:147], v[220:223], v[86:89]
	v_mfma_f32_16x16x32_bf16 v[82:85], v[152:155], v[220:223], v[82:85]
	v_mfma_f32_16x16x32_bf16 v[126:129], v[148:151], v[188:191], v[126:129]
	v_mfma_f32_16x16x32_bf16 v[122:125], v[156:159], v[188:191], v[122:125]
	v_mfma_f32_16x16x32_bf16 v[118:121], v[148:151], v[196:199], v[118:121]
	v_mfma_f32_16x16x32_bf16 v[114:117], v[156:159], v[196:199], v[114:117]
	v_mfma_f32_16x16x32_bf16 v[102:105], v[148:151], v[216:219], v[102:105]
	v_mfma_f32_16x16x32_bf16 v[98:101], v[156:159], v[216:219], v[98:101]
	v_mfma_f32_16x16x32_bf16 v[86:89], v[148:151], v[224:227], v[86:89]
	v_mfma_f32_16x16x32_bf16 v[82:85], v[156:159], v[224:227], v[82:85]
	s_barrier
	s_add_i32 s17, 0, 0x1c000
	s_add_i32 s2, s2, s3
	v_add_u32_e32 v206, s17, v141
	v_lshl_add_u64 v[164:165], v[164:165], 0, s[28:29]
	s_mov_b32 m0, s2
	ds_read_b128 v[228:231], v206
	ds_read_b128 v[232:235], v206 offset:1024
	ds_read_b128 v[236:239], v206 offset:2048
	ds_read_b128 v[240:243], v206 offset:3072
	global_load_lds_dwordx4 v[164:165], off
	v_lshl_add_u64 v[164:165], v[204:205], 0, s[28:29]
	s_add_i32 m0, s2, 0x2000
	s_nop 0
	global_load_lds_dwordx4 v[164:165], off
	s_barrier
	s_waitcnt lgkmcnt(1)
	v_mfma_f32_16x16x32_bf16 v[110:113], v[228:231], v[160:163], v[110:113]
	v_mfma_f32_16x16x32_bf16 v[106:109], v[236:239], v[160:163], v[106:109]
	v_mfma_f32_16x16x32_bf16 v[94:97], v[228:231], v[192:195], v[94:97]
	v_mfma_f32_16x16x32_bf16 v[90:93], v[236:239], v[192:195], v[90:93]
	v_mfma_f32_16x16x32_bf16 v[78:81], v[228:231], v[200:203], v[78:81]
	v_mfma_f32_16x16x32_bf16 v[74:77], v[236:239], v[200:203], v[74:77]
	s_waitcnt lgkmcnt(0)
	v_mfma_f32_16x16x32_bf16 v[70:73], v[228:231], v[220:223], v[70:73]
	v_mfma_f32_16x16x32_bf16 v[66:69], v[236:239], v[220:223], v[66:69]
	v_mfma_f32_16x16x32_bf16 v[110:113], v[232:235], v[188:191], v[110:113]
	v_mfma_f32_16x16x32_bf16 v[106:109], v[240:243], v[188:191], v[106:109]
	v_mfma_f32_16x16x32_bf16 v[94:97], v[232:235], v[196:199], v[94:97]
	v_mfma_f32_16x16x32_bf16 v[90:93], v[240:243], v[196:199], v[90:93]
	v_mfma_f32_16x16x32_bf16 v[78:81], v[232:235], v[216:219], v[78:81]
	v_mfma_f32_16x16x32_bf16 v[74:77], v[240:243], v[216:219], v[74:77]
	v_mfma_f32_16x16x32_bf16 v[70:73], v[232:235], v[224:227], v[70:73]
	v_mfma_f32_16x16x32_bf16 v[66:69], v[240:243], v[224:227], v[66:69]
	s_mov_b32 m0, s80
	v_lshl_add_u64 v[164:165], v[244:245], 0, s[28:29]
	s_barrier
	ds_read_b128 v[160:163], v143 offset:49152
	ds_read_b128 v[188:191], v143 offset:50176
	ds_read_b128 v[192:195], v143 offset:51200
	ds_read_b128 v[196:199], v143 offset:52224
	ds_read_b128 v[200:203], v143 offset:53248
	ds_read_b128 v[216:219], v143 offset:54272
	ds_read_b128 v[220:223], v143 offset:55296
	ds_read_b128 v[224:227], v143 offset:56320
	global_load_lds_dwordx4 v[164:165], off
	v_lshl_add_u64 v[164:165], v[246:247], 0, s[28:29]
	s_mov_b32 m0, s81
	s_nop 0
	global_load_lds_dwordx4 v[164:165], off
	s_barrier
	s_waitcnt lgkmcnt(7)
	v_mfma_f32_16x16x32_bf16 v[62:65], v[144:147], v[160:163], v[62:65]
	v_mfma_f32_16x16x32_bf16 v[58:61], v[152:155], v[160:163], v[58:61]
	s_waitcnt lgkmcnt(3)
	v_mfma_f32_16x16x32_bf16 v[54:57], v[144:147], v[192:195], v[54:57]
	v_mfma_f32_16x16x32_bf16 v[50:53], v[152:155], v[192:195], v[50:53]
	v_mfma_f32_16x16x32_bf16 v[38:41], v[144:147], v[200:203], v[38:41]
	v_mfma_f32_16x16x32_bf16 v[34:37], v[152:155], v[200:203], v[34:37]
	s_waitcnt lgkmcnt(0)
	v_mfma_f32_16x16x32_bf16 v[22:25], v[144:147], v[220:223], v[22:25]
	v_mfma_f32_16x16x32_bf16 v[18:21], v[152:155], v[220:223], v[18:21]
	v_mfma_f32_16x16x32_bf16 v[62:65], v[148:151], v[188:191], v[62:65]
	v_mfma_f32_16x16x32_bf16 v[58:61], v[156:159], v[188:191], v[58:61]
	v_mfma_f32_16x16x32_bf16 v[54:57], v[148:151], v[196:199], v[54:57]
	v_mfma_f32_16x16x32_bf16 v[50:53], v[156:159], v[196:199], v[50:53]
	v_mfma_f32_16x16x32_bf16 v[38:41], v[148:151], v[216:219], v[38:41]
	v_mfma_f32_16x16x32_bf16 v[34:37], v[156:159], v[216:219], v[34:37]
	v_mfma_f32_16x16x32_bf16 v[22:25], v[148:151], v[224:227], v[22:25]
	v_mfma_f32_16x16x32_bf16 v[18:21], v[156:159], v[224:227], v[18:21]
	s_barrier
	s_add_u32 s26, s70, 0x80080
	s_addc_u32 s27, s71, 0
	s_add_i32 s2, s17, s3
	v_lshl_add_u64 v[144:145], s[26:27], 0, v[0:1]
	s_mov_b32 m0, s2
	s_nop 0
	global_load_lds_dwordx4 v[144:145], off
	v_lshl_add_u64 v[144:145], s[26:27], 0, v[130:131]
	s_add_i32 m0, s2, 0x2000
	s_nop 0
	global_load_lds_dwordx4 v[144:145], off
	s_waitcnt vmcnt(6)
	s_barrier
	v_mfma_f32_16x16x32_bf16 v[46:49], v[228:231], v[160:163], v[46:49]
	v_mfma_f32_16x16x32_bf16 v[42:45], v[236:239], v[160:163], v[42:45]
	v_mfma_f32_16x16x32_bf16 v[30:33], v[228:231], v[192:195], v[30:33]
	v_mfma_f32_16x16x32_bf16 v[26:29], v[236:239], v[192:195], v[26:29]
	v_mfma_f32_16x16x32_bf16 v[14:17], v[228:231], v[200:203], v[14:17]
	v_mfma_f32_16x16x32_bf16 v[10:13], v[236:239], v[200:203], v[10:13]
	v_mfma_f32_16x16x32_bf16 v[6:9], v[228:231], v[220:223], v[6:9]
	v_mfma_f32_16x16x32_bf16 v[2:5], v[236:239], v[220:223], v[2:5]
	v_mfma_f32_16x16x32_bf16 v[46:49], v[232:235], v[188:191], v[46:49]
	v_mfma_f32_16x16x32_bf16 v[42:45], v[240:243], v[188:191], v[42:45]
	v_mfma_f32_16x16x32_bf16 v[30:33], v[232:235], v[196:199], v[30:33]
	v_mfma_f32_16x16x32_bf16 v[26:29], v[240:243], v[196:199], v[26:29]
	v_mfma_f32_16x16x32_bf16 v[14:17], v[232:235], v[216:219], v[14:17]
	v_mfma_f32_16x16x32_bf16 v[10:13], v[240:243], v[216:219], v[10:13]
	v_mfma_f32_16x16x32_bf16 v[6:9], v[232:235], v[224:227], v[6:9]
	v_mfma_f32_16x16x32_bf16 v[2:5], v[240:243], v[224:227], v[2:5]
	s_add_i32 s44, s44, 2
	s_add_u32 s68, s68, 0x100
	s_addc_u32 s69, s69, 0
	s_add_u32 s83, s83, 0x100
	s_addc_u32 s92, s92, 0
	s_cmp_gt_u32 s44, 29
	s_barrier
	s_cbranch_scc0 .LBB0_1044
	v_lshl_add_u32 v144, s47, 8, v140
	v_lshl_or_b32 v146, s46, 8, v142
	v_ashrrev_i32_e32 v145, 31, v144
	v_cvt_pk_bf16_f32 v126, v126, v127
	v_cvt_pk_bf16_f32 v127, v128, v129
	v_cvt_pk_bf16_f32 v128, v122, v123
	v_lshlrev_b64 v[122:123], 12, v[144:145]
	v_ashrrev_i32_e32 v147, 31, v146
	v_cvt_pk_bf16_f32 v129, v124, v125
	v_lshl_add_u64 v[122:123], s[22:23], 0, v[122:123]
	v_lshlrev_b64 v[124:125], 1, v[146:147]
	v_lshl_add_u64 v[122:123], v[122:123], 0, v[124:125]
	v_cvt_pk_bf16_f32 v110, v110, v111
	v_cvt_pk_bf16_f32 v111, v112, v113
	v_cvt_pk_bf16_f32 v112, v106, v107
	v_cvt_pk_bf16_f32 v113, v108, v109
	global_store_dwordx4 v[122:123], v[110:113], off offset:256
	v_cvt_pk_bf16_f32 v94, v94, v95
	v_cvt_pk_bf16_f32 v95, v96, v97
	v_or_b32_e32 v110, 16, v144
	v_ashrrev_i32_e32 v111, 31, v110
	v_lshlrev_b64 v[110:111], 12, v[110:111]
	v_lshl_add_u64 v[110:111], s[22:23], 0, v[110:111]
	v_lshl_add_u64 v[110:111], v[110:111], 0, v[124:125]
	v_cvt_pk_bf16_f32 v96, v90, v91
	v_cvt_pk_bf16_f32 v97, v92, v93
	global_store_dwordx4 v[110:111], v[94:97], off offset:256
	s_mov_b32 s2, 0x80000
	v_cvt_pk_bf16_f32 v62, v62, v63
	v_or_b32_e32 v94, 32, v144
	v_ashrrev_i32_e32 v95, 31, v94
	v_cvt_pk_bf16_f32 v63, v64, v65
	v_cvt_pk_bf16_f32 v65, v60, v61
	s_mov_b64 s[4:5], 0x80000
	v_add_co_u32_e32 v60, vcc, s2, v122
	v_lshlrev_b64 v[94:95], 12, v[94:95]
	v_cvt_pk_bf16_f32 v64, v58, v59
	v_lshl_add_u64 v[58:59], v[122:123], 0, s[4:5]
	v_addc_co_u32_e32 v61, vcc, 0, v123, vcc
	v_cvt_pk_bf16_f32 v46, v46, v47
	v_cvt_pk_bf16_f32 v47, v48, v49
	v_cvt_pk_bf16_f32 v48, v42, v43
	v_cvt_pk_bf16_f32 v49, v44, v45
	s_mov_b32 s2, 0x90000
	v_lshl_add_u64 v[94:95], s[22:23], 0, v[94:95]
	global_store_dwordx4 v[58:59], v[46:49], off offset:256
	s_mov_b64 s[4:5], 0x90000
	v_lshl_add_u64 v[94:95], v[94:95], 0, v[124:125]
	v_add_co_u32_e32 v48, vcc, s2, v122
	v_cvt_pk_bf16_f32 v78, v78, v79
	v_cvt_pk_bf16_f32 v79, v80, v81
	v_cvt_pk_bf16_f32 v80, v74, v75
	v_cvt_pk_bf16_f32 v81, v76, v77
	v_lshl_add_u64 v[46:47], v[122:123], 0, s[4:5]
	v_addc_co_u32_e32 v49, vcc, 0, v123, vcc
	v_cvt_pk_bf16_f32 v30, v30, v31
	v_cvt_pk_bf16_f32 v31, v32, v33
	v_cvt_pk_bf16_f32 v32, v26, v27
	v_cvt_pk_bf16_f32 v33, v28, v29
	s_mov_b32 s2, 0xa0000
	global_store_dwordx4 v[94:95], v[78:81], off offset:256
	global_store_dwordx4 v[46:47], v[30:33], off offset:256
	s_mov_b64 s[4:5], 0xa0000
	v_or_b32_e32 v78, 48, v144
	v_add_co_u32_e32 v32, vcc, s2, v122
	v_ashrrev_i32_e32 v79, 31, v78
	v_lshl_add_u64 v[30:31], v[122:123], 0, s[4:5]
	v_addc_co_u32_e32 v33, vcc, 0, v123, vcc
	v_cvt_pk_bf16_f32 v14, v14, v15
	v_cvt_pk_bf16_f32 v15, v16, v17
	v_cvt_pk_bf16_f32 v16, v10, v11
	v_cvt_pk_bf16_f32 v17, v12, v13
	s_mov_b32 s2, 0xb0000
	v_lshlrev_b64 v[78:79], 12, v[78:79]
	global_store_dwordx4 v[30:31], v[14:17], off offset:256
	v_lshl_add_u64 v[78:79], s[22:23], 0, v[78:79]
	s_mov_b64 s[4:5], 0xb0000
	v_add_co_u32_e32 v16, vcc, s2, v122
	v_cvt_pk_bf16_f32 v106, v118, v119
	s_nop 0
	v_addc_co_u32_e32 v17, vcc, 0, v123, vcc
	v_cvt_pk_bf16_f32 v107, v120, v121
	v_cvt_pk_bf16_f32 v108, v114, v115
	v_cvt_pk_bf16_f32 v109, v116, v117
	v_cvt_pk_bf16_f32 v90, v102, v103
	v_cvt_pk_bf16_f32 v91, v104, v105
	v_cvt_pk_bf16_f32 v92, v98, v99
	v_cvt_pk_bf16_f32 v93, v100, v101
	v_cvt_pk_bf16_f32 v74, v86, v87
	v_cvt_pk_bf16_f32 v75, v88, v89
	v_cvt_pk_bf16_f32 v76, v82, v83
	v_cvt_pk_bf16_f32 v77, v84, v85
	v_lshl_add_u64 v[78:79], v[78:79], 0, v[124:125]
	v_cvt_pk_bf16_f32 v70, v70, v71
	v_cvt_pk_bf16_f32 v71, v72, v73
	v_cvt_pk_bf16_f32 v72, v66, v67
	v_cvt_pk_bf16_f32 v73, v68, v69
	v_cvt_pk_bf16_f32 v42, v54, v55
	v_cvt_pk_bf16_f32 v43, v56, v57
	v_cvt_pk_bf16_f32 v44, v50, v51
	v_cvt_pk_bf16_f32 v45, v52, v53
	v_cvt_pk_bf16_f32 v26, v38, v39
	v_cvt_pk_bf16_f32 v27, v40, v41
	v_cvt_pk_bf16_f32 v28, v34, v35
	v_cvt_pk_bf16_f32 v29, v36, v37
	v_cvt_pk_bf16_f32 v10, v22, v23
	v_cvt_pk_bf16_f32 v11, v24, v25
	v_cvt_pk_bf16_f32 v12, v18, v19
	v_cvt_pk_bf16_f32 v13, v20, v21
	v_lshl_add_u64 v[14:15], v[122:123], 0, s[4:5]
	v_cvt_pk_bf16_f32 v6, v6, v7
	v_cvt_pk_bf16_f32 v7, v8, v9
	v_cvt_pk_bf16_f32 v8, v2, v3
	v_cvt_pk_bf16_f32 v9, v4, v5
	s_and_b64 vcc, exec, s[0:1]
	s_mov_b32 s46, s42
	s_mov_b32 s47, s54
	s_mov_b64 s[70:71], s[64:65]
	s_mov_b64 s[68:69], s[62:63]
	global_store_dwordx4 v[122:123], v[126:129], off
	global_store_dwordx4 v[110:111], v[106:109], off
	global_store_dwordx4 v[94:95], v[90:93], off
	global_store_dwordx4 v[78:79], v[74:77], off
	global_store_dwordx4 v[78:79], v[70:73], off offset:256
	global_store_dwordx4 v[60:61], v[62:65], off
	global_store_dwordx4 v[48:49], v[42:45], off
	global_store_dwordx4 v[32:33], v[26:29], off
	global_store_dwordx4 v[16:17], v[10:13], off
	global_store_dwordx4 v[14:15], v[6:9], off offset:256
	s_cbranch_vccz .LBB0_1041
	v_readlane_b32 s0, v254, 12
	s_waitcnt vmcnt(0)
	v_readlane_b32 s1, v254, 13
	v_readlane_b32 s84, v251, 38
	s_andn2_b64 vcc, exec, s[0:1]
	v_readlane_b32 s85, v251, 39
	v_readlane_b32 s86, v251, 40
	v_readlane_b32 s87, v251, 41
	s_cbranch_vccnz .LBB0_1048
	s_barrier
